# comb4 + saddr-form LDS-DMA addressing in all GEMM K-loops
# baseline (speedup 1.0000x reference)
; #define PG8_STAGE(bufoff, gbase, voff) do { _Pragma("unroll") for (int _i = 0; _i < 2; ++_i) \
;         __builtin_amdgcn_global_load_lds((const unsigned*)((const char*)(gbase) + (voff)[_i]), (LAS unsigned*)(lds + (bufoff) + ldsw + _i * 8192), 16, 0, 0); } while (0)
; #define PG8_LDA(dst, b, h) do { _Pragma("unroll") for (int m = 0; m < 4; ++m) _Pragma("unroll") for (int k = 0; k < 2; ++k) dst[m][k] = *(const LAS bf16x8*)(lds + PG8_SA(b, h) + aoff + m * 2048 + k * 1024); } while (0)
; #define PG8_LDB(dst, b, h) do { _Pragma("unroll") for (int n = 0; n < 2; ++n) _Pragma("unroll") for (int k = 0; k < 2; ++k) dst[n][k] = *(const LAS bf16x8*)(lds + PG8_SB(b, h) + boff + n * 2048 + k * 1024); } while (0)
; #define PG8_MMA(ai, bj, At, Bt) do { __builtin_amdgcn_s_setprio(1); _Pragma("unroll") for (int m = 0; m < 4; ++m) _Pragma("unroll") for (int n = 0; n < 2; ++n) _Pragma("unroll") for (int k = 0; k < 2; ++k) \
;         acc[ai][bj][m][n] = __builtin_amdgcn_mfma_f32_16x16x32_bf16(Bt[n][k], At[m][k], acc[ai][bj][m][n], 0, 0, 0); __builtin_amdgcn_s_setprio(0); } while (0)
; #define PG8_WAIT_V(n) asm volatile("s_waitcnt vmcnt(" #n ")" ::: "memory")
; #define PG8_WAIT_L(n) asm volatile("s_waitcnt lgkmcnt(" #n ")" ::: "memory")
; #define PG8_BAR __builtin_amdgcn_s_barrier()
; template <class Epi, class Sched, bool ALIGN_EPI, class Hook = NoHook>
; __device__ __forceinline__ void gemm_phase(LAS unsigned char* lds, const Gemm g, const Sched& S, const Epi& E, const Hook& H = Hook()) {
;     ...
;             const bool last = (t == nt - 2);
;             const char* a1 = cA + (size_t)(t + 1) * kstep;
;             const char* a2 = last ? nA : cA + (size_t)(t + 2) * kstep; const char* b2 = last ? nB : cB + (size_t)(t + 2) * kstep;
;             const char* a3 = a2 + kstep; const char* b3 = b2 + kstep;
;             if (last && has_next) S.a_ready(nxt);
;             PG8_LDB(B0, 0, 0); PG8_LDB(B1, 0, 1); PG8_SCHED; PG8_LDA(At, 0, 0); PG8_STAGE(PG8_SA(1, 1), a1 + hA, voffA);
;             PG8_WAIT_V(8); PG8_WAIT_L(0); PG8_BAR; PG8_MMA(0, 0, At, B0); PG8_MMA(0, 1, At, B1); PG8_BAR; PG8_SCHED;
;             PG8_LDA(At, 0, 1); PG8_STAGE(PG8_SB(0, 0), b2, voffB); PG8_STAGE(PG8_SB(0, 1), b2 + hB, voffB); PG8_STAGE(PG8_SA(0, 0), a2, voffA);
;             PG8_WAIT_V(8); PG8_WAIT_L(0); PG8_BAR; PG8_MMA(1, 0, At, B0); PG8_MMA(1, 1, At, B1); PG8_BAR; PG8_SCHED;
.LBB0_262:
	ds_read_b128 v[148:151], v145
	ds_read_b128 v[152:155], v145 offset:1024
	ds_read_b128 v[156:159], v145 offset:2048
	ds_read_b128 v[160:163], v145 offset:3072
	ds_read_b128 v[164:167], v146
	ds_read_b128 v[168:171], v146 offset:1024
	ds_read_b128 v[172:175], v146 offset:2048
	ds_read_b128 v[176:179], v146 offset:3072
	s_add_u32 s22, s20, 0xfff00080
	s_addc_u32 s23, s21, -1
	s_cmp_eq_u32 s50, 4
	s_cselect_b32 s25, s11, s23
	s_cselect_b32 s24, s13, s22
	s_cselect_b32 s23, s40, s43
	s_cselect_b32 s22, s41, s42
	s_add_i32 m0, s5, 0xc000
	ds_read_b128 v[180:183], v147
	ds_read_b128 v[184:187], v147 offset:1024
	ds_read_b128 v[188:191], v147 offset:2048
	ds_read_b128 v[192:195], v147 offset:3072
	ds_read_b128 v[196:199], v147 offset:4096
	ds_read_b128 v[200:203], v147 offset:5120
	ds_read_b128 v[204:207], v147 offset:6144
	ds_read_b128 v[208:211], v147 offset:7168
	global_load_lds_dwordx4 v136, s[20:21]
	s_add_i32 m0, s5, 0xe000
	s_nop 0
	global_load_lds_dwordx4 v138, s[20:21]
	s_waitcnt vmcnt(8)
	s_waitcnt lgkmcnt(0)
	s_barrier
	s_setprio 1
	s_waitcnt lgkmcnt(0)
	v_mfma_f32_16x16x32_bf16 v[126:129], v[148:151], v[180:183], v[126:129]
	v_mfma_f32_16x16x32_bf16 v[122:125], v[156:159], v[180:183], v[122:125]
	v_mfma_f32_16x16x32_bf16 v[118:121], v[148:151], v[188:191], v[118:121]
	v_mfma_f32_16x16x32_bf16 v[114:117], v[156:159], v[188:191], v[114:117]
	v_mfma_f32_16x16x32_bf16 v[106:109], v[148:151], v[196:199], v[106:109]
	v_mfma_f32_16x16x32_bf16 v[98:101], v[156:159], v[196:199], v[98:101]
	v_mfma_f32_16x16x32_bf16 v[90:93], v[148:151], v[204:207], v[90:93]
	v_mfma_f32_16x16x32_bf16 v[82:85], v[156:159], v[204:207], v[82:85]
	v_mfma_f32_16x16x32_bf16 v[126:129], v[152:155], v[184:187], v[126:129]
	v_mfma_f32_16x16x32_bf16 v[122:125], v[160:163], v[184:187], v[122:125]
	v_mfma_f32_16x16x32_bf16 v[118:121], v[152:155], v[192:195], v[118:121]
	v_mfma_f32_16x16x32_bf16 v[114:117], v[160:163], v[192:195], v[114:117]
	v_mfma_f32_16x16x32_bf16 v[106:109], v[152:155], v[200:203], v[106:109]
	v_mfma_f32_16x16x32_bf16 v[98:101], v[160:163], v[200:203], v[98:101]
	v_mfma_f32_16x16x32_bf16 v[90:93], v[152:155], v[208:211], v[90:93]
	v_mfma_f32_16x16x32_bf16 v[82:85], v[160:163], v[208:211], v[82:85]
	s_setprio 0
	s_setprio 1
	v_mfma_f32_16x16x32_bf16 v[110:113], v[164:167], v[180:183], v[110:113]
	v_mfma_f32_16x16x32_bf16 v[102:105], v[172:175], v[180:183], v[102:105]
	v_mfma_f32_16x16x32_bf16 v[94:97], v[164:167], v[188:191], v[94:97]
	v_mfma_f32_16x16x32_bf16 v[86:89], v[172:175], v[188:191], v[86:89]
	v_mfma_f32_16x16x32_bf16 v[78:81], v[164:167], v[196:199], v[78:81]
	v_mfma_f32_16x16x32_bf16 v[74:77], v[172:175], v[196:199], v[74:77]
	v_mfma_f32_16x16x32_bf16 v[70:73], v[164:167], v[204:207], v[70:73]
	v_mfma_f32_16x16x32_bf16 v[66:69], v[172:175], v[204:207], v[66:69]
	v_mfma_f32_16x16x32_bf16 v[110:113], v[168:171], v[184:187], v[110:113]
	v_mfma_f32_16x16x32_bf16 v[102:105], v[176:179], v[184:187], v[102:105]
	v_mfma_f32_16x16x32_bf16 v[94:97], v[168:171], v[192:195], v[94:97]
	v_mfma_f32_16x16x32_bf16 v[86:89], v[176:179], v[192:195], v[86:89]
	v_mfma_f32_16x16x32_bf16 v[78:81], v[168:171], v[200:203], v[78:81]
	v_mfma_f32_16x16x32_bf16 v[74:77], v[176:179], v[200:203], v[74:77]
	v_mfma_f32_16x16x32_bf16 v[70:73], v[168:171], v[208:211], v[70:73]
	v_mfma_f32_16x16x32_bf16 v[66:69], v[176:179], v[208:211], v[66:69]
	s_setprio 0
	s_barrier
	s_add_i32 s51, s38, s29
	s_mov_b32 m0, s51
	ds_read_b128 v[180:183], v147 offset:16384
	ds_read_b128 v[184:187], v147 offset:17408
	ds_read_b128 v[188:191], v147 offset:18432
	ds_read_b128 v[192:195], v147 offset:19456
	ds_read_b128 v[196:199], v147 offset:20480
	ds_read_b128 v[200:203], v147 offset:21504
	ds_read_b128 v[204:207], v147 offset:22528
	ds_read_b128 v[208:211], v147 offset:23552
	global_load_lds_dwordx4 v132, s[22:23]
	s_add_i32 m0, s51, 0x2000
	s_add_u32 s52, s22, 0x100000
	s_addc_u32 s53, s23, 0
	s_add_i32 s51, s39, s29
	global_load_lds_dwordx4 v130, s[22:23]
	s_mov_b32 m0, s51
	s_nop 0
	global_load_lds_dwordx4 v132, s[52:53]
	s_add_i32 m0, s51, 0x2000
	s_nop 0
	global_load_lds_dwordx4 v130, s[52:53]
	s_add_u32 s56, s24, s8
	s_addc_u32 s57, s25, s9
	s_mov_b32 m0, s5
	s_nop 0
	global_load_lds_dwordx4 v132, s[24:25]
	s_mov_b32 m0, s7
	s_nop 0
	global_load_lds_dwordx4 v130, s[24:25]
	s_waitcnt vmcnt(8)
	s_waitcnt lgkmcnt(0)
	s_barrier
	s_setprio 1
	s_waitcnt lgkmcnt(0)
	v_mfma_f32_16x16x32_bf16 v[62:65], v[148:151], v[180:183], v[62:65]
	v_mfma_f32_16x16x32_bf16 v[58:61], v[156:159], v[180:183], v[58:61]
	v_mfma_f32_16x16x32_bf16 v[54:57], v[148:151], v[188:191], v[54:57]
	v_mfma_f32_16x16x32_bf16 v[50:53], v[156:159], v[188:191], v[50:53]
	v_mfma_f32_16x16x32_bf16 v[38:41], v[148:151], v[196:199], v[38:41]
	v_mfma_f32_16x16x32_bf16 v[34:37], v[156:159], v[196:199], v[34:37]
	v_mfma_f32_16x16x32_bf16 v[22:25], v[148:151], v[204:207], v[22:25]
	v_mfma_f32_16x16x32_bf16 v[18:21], v[156:159], v[204:207], v[18:21]
	v_mfma_f32_16x16x32_bf16 v[62:65], v[152:155], v[184:187], v[62:65]
	v_mfma_f32_16x16x32_bf16 v[58:61], v[160:163], v[184:187], v[58:61]
	v_mfma_f32_16x16x32_bf16 v[54:57], v[152:155], v[192:195], v[54:57]
	v_mfma_f32_16x16x32_bf16 v[50:53], v[160:163], v[192:195], v[50:53]
	v_mfma_f32_16x16x32_bf16 v[38:41], v[152:155], v[200:203], v[38:41]
	v_mfma_f32_16x16x32_bf16 v[34:37], v[160:163], v[200:203], v[34:37]
	v_mfma_f32_16x16x32_bf16 v[22:25], v[152:155], v[208:211], v[22:25]
	v_mfma_f32_16x16x32_bf16 v[18:21], v[160:163], v[208:211], v[18:21]
	s_setprio 0
	s_setprio 1
	v_mfma_f32_16x16x32_bf16 v[46:49], v[164:167], v[180:183], v[46:49]
	v_mfma_f32_16x16x32_bf16 v[42:45], v[172:175], v[180:183], v[42:45]
	v_mfma_f32_16x16x32_bf16 v[30:33], v[164:167], v[188:191], v[30:33]
	v_mfma_f32_16x16x32_bf16 v[26:29], v[172:175], v[188:191], v[26:29]
	v_mfma_f32_16x16x32_bf16 v[14:17], v[164:167], v[196:199], v[14:17]
	v_mfma_f32_16x16x32_bf16 v[10:13], v[172:175], v[196:199], v[10:13]
	v_mfma_f32_16x16x32_bf16 v[6:9], v[164:167], v[204:207], v[6:9]
	v_mfma_f32_16x16x32_bf16 v[2:5], v[172:175], v[204:207], v[2:5]
	v_mfma_f32_16x16x32_bf16 v[46:49], v[168:171], v[184:187], v[46:49]
	v_mfma_f32_16x16x32_bf16 v[42:45], v[176:179], v[184:187], v[42:45]
	v_mfma_f32_16x16x32_bf16 v[30:33], v[168:171], v[192:195], v[30:33]
	v_mfma_f32_16x16x32_bf16 v[26:29], v[176:179], v[192:195], v[26:29]
	v_mfma_f32_16x16x32_bf16 v[14:17], v[168:171], v[200:203], v[14:17]
	v_mfma_f32_16x16x32_bf16 v[10:13], v[176:179], v[200:203], v[10:13]
	v_mfma_f32_16x16x32_bf16 v[6:9], v[168:171], v[208:211], v[6:9]
	v_mfma_f32_16x16x32_bf16 v[2:5], v[176:179], v[208:211], v[2:5]
	s_setprio 0
	s_barrier
; #define PG8_STAGE(bufoff, gbase, voff) do { _Pragma("unroll") for (int _i = 0; _i < 2; ++_i) \
;         __builtin_amdgcn_global_load_lds((const unsigned*)((const char*)(gbase) + (voff)[_i]), (LAS unsigned*)(lds + (bufoff) + ldsw + _i * 8192), 16, 0, 0); } while (0)
; #define PG8_LDA(dst, b, h) do { _Pragma("unroll") for (int m = 0; m < 4; ++m) _Pragma("unroll") for (int k = 0; k < 2; ++k) dst[m][k] = *(const LAS bf16x8*)(lds + PG8_SA(b, h) + aoff + m * 2048 + k * 1024); } while (0)
; #define PG8_LDB(dst, b, h) do { _Pragma("unroll") for (int n = 0; n < 2; ++n) _Pragma("unroll") for (int k = 0; k < 2; ++k) dst[n][k] = *(const LAS bf16x8*)(lds + PG8_SB(b, h) + boff + n * 2048 + k * 1024); } while (0)
; #define PG8_MMA(ai, bj, At, Bt) do { __builtin_amdgcn_s_setprio(1); _Pragma("unroll") for (int m = 0; m < 4; ++m) _Pragma("unroll") for (int n = 0; n < 2; ++n) _Pragma("unroll") for (int k = 0; k < 2; ++k) \
;         acc[ai][bj][m][n] = __builtin_amdgcn_mfma_f32_16x16x32_bf16(Bt[n][k], At[m][k], acc[ai][bj][m][n], 0, 0, 0); __builtin_amdgcn_s_setprio(0); } while (0)
; #define PG8_WAIT_V(n) asm volatile("s_waitcnt vmcnt(" #n ")" ::: "memory")
; #define PG8_WAIT_L(n) asm volatile("s_waitcnt lgkmcnt(" #n ")" ::: "memory")
; #define PG8_BAR __builtin_amdgcn_s_barrier()
; #define PG8_SCHED __builtin_amdgcn_sched_barrier(0)
; template <class Epi, class Sched, bool ALIGN_EPI, class Hook = NoHook>
; __device__ __forceinline__ void gemm_phase(LAS unsigned char* lds, const Gemm g, const Sched& S, const Epi& E, const Hook& H = Hook()) {
;     ...
;             PG8_LDB(B0, 1, 0); PG8_LDB(B1, 1, 1); PG8_SCHED; PG8_LDA(At, 1, 0); PG8_STAGE(PG8_SA(0, 1), a2 + hA, voffA);
;             PG8_WAIT_V(8); PG8_WAIT_L(0); PG8_BAR; PG8_MMA(0, 0, At, B0); PG8_MMA(0, 1, At, B1); PG8_BAR; PG8_SCHED;
;             PG8_LDA(At, 1, 1); PG8_STAGE(PG8_SB(1, 0), b3, voffB); PG8_STAGE(PG8_SB(1, 1), b3 + hB, voffB); PG8_STAGE(PG8_SA(1, 0), a3, voffA);
;             PG8_WAIT_V(8); PG8_WAIT_L(0); PG8_BAR; PG8_MMA(1, 0, At, B0); PG8_MMA(1, 1, At, B1); PG8_BAR; PG8_SCHED;
	s_add_i32 s51, 0, 0x18000
	s_add_i32 s52, 0, 0x1c000
	v_add_u32_e32 v160, s51, v144
	v_add_u32_e32 v176, s52, v144
	ds_read_b128 v[148:151], v160
	ds_read_b128 v[152:155], v160 offset:1024
	ds_read_b128 v[156:159], v160 offset:2048
	ds_read_b128 v[160:163], v160 offset:3072
	ds_read_b128 v[164:167], v176
	ds_read_b128 v[168:171], v176 offset:1024
	ds_read_b128 v[172:175], v176 offset:2048
	ds_read_b128 v[176:179], v176 offset:3072
	s_add_u32 s24, s24, 0x100000
	s_addc_u32 s25, s25, 0
	s_mov_b32 m0, s30
	ds_read_b128 v[180:183], v147 offset:32768
	ds_read_b128 v[184:187], v147 offset:33792
	ds_read_b128 v[188:191], v147 offset:34816
	ds_read_b128 v[192:195], v147 offset:35840
	ds_read_b128 v[196:199], v147 offset:36864
	ds_read_b128 v[200:203], v147 offset:37888
	ds_read_b128 v[204:207], v147 offset:38912
	ds_read_b128 v[208:211], v147 offset:39936
	global_load_lds_dwordx4 v132, s[24:25]
	s_mov_b32 m0, s31
	s_nop 0
	global_load_lds_dwordx4 v130, s[24:25]
	s_waitcnt vmcnt(8)
	s_waitcnt lgkmcnt(0)
	s_barrier
	s_setprio 1
	s_waitcnt lgkmcnt(0)
	v_mfma_f32_16x16x32_bf16 v[126:129], v[148:151], v[180:183], v[126:129]
	v_mfma_f32_16x16x32_bf16 v[122:125], v[156:159], v[180:183], v[122:125]
	v_mfma_f32_16x16x32_bf16 v[118:121], v[148:151], v[188:191], v[118:121]
	v_mfma_f32_16x16x32_bf16 v[114:117], v[156:159], v[188:191], v[114:117]
	v_mfma_f32_16x16x32_bf16 v[106:109], v[148:151], v[196:199], v[106:109]
	v_mfma_f32_16x16x32_bf16 v[98:101], v[156:159], v[196:199], v[98:101]
	v_mfma_f32_16x16x32_bf16 v[90:93], v[148:151], v[204:207], v[90:93]
	v_mfma_f32_16x16x32_bf16 v[82:85], v[156:159], v[204:207], v[82:85]
	v_mfma_f32_16x16x32_bf16 v[126:129], v[152:155], v[184:187], v[126:129]
	v_mfma_f32_16x16x32_bf16 v[122:125], v[160:163], v[184:187], v[122:125]
	v_mfma_f32_16x16x32_bf16 v[118:121], v[152:155], v[192:195], v[118:121]
	v_mfma_f32_16x16x32_bf16 v[114:117], v[160:163], v[192:195], v[114:117]
	v_mfma_f32_16x16x32_bf16 v[106:109], v[152:155], v[200:203], v[106:109]
	v_mfma_f32_16x16x32_bf16 v[98:101], v[160:163], v[200:203], v[98:101]
	v_mfma_f32_16x16x32_bf16 v[90:93], v[152:155], v[208:211], v[90:93]
	v_mfma_f32_16x16x32_bf16 v[82:85], v[160:163], v[208:211], v[82:85]
	s_setprio 0
	s_setprio 1
	v_mfma_f32_16x16x32_bf16 v[110:113], v[164:167], v[180:183], v[110:113]
	v_mfma_f32_16x16x32_bf16 v[102:105], v[172:175], v[180:183], v[102:105]
	v_mfma_f32_16x16x32_bf16 v[94:97], v[164:167], v[188:191], v[94:97]
	v_mfma_f32_16x16x32_bf16 v[86:89], v[172:175], v[188:191], v[86:89]
	v_mfma_f32_16x16x32_bf16 v[78:81], v[164:167], v[196:199], v[78:81]
	v_mfma_f32_16x16x32_bf16 v[74:77], v[172:175], v[196:199], v[74:77]
	v_mfma_f32_16x16x32_bf16 v[70:73], v[164:167], v[204:207], v[70:73]
	v_mfma_f32_16x16x32_bf16 v[66:69], v[172:175], v[204:207], v[66:69]
	v_mfma_f32_16x16x32_bf16 v[110:113], v[168:171], v[184:187], v[110:113]
	v_mfma_f32_16x16x32_bf16 v[102:105], v[176:179], v[184:187], v[102:105]
	v_mfma_f32_16x16x32_bf16 v[94:97], v[168:171], v[192:195], v[94:97]
	v_mfma_f32_16x16x32_bf16 v[86:89], v[176:179], v[192:195], v[86:89]
	v_mfma_f32_16x16x32_bf16 v[78:81], v[168:171], v[200:203], v[78:81]
	v_mfma_f32_16x16x32_bf16 v[74:77], v[176:179], v[200:203], v[74:77]
	v_mfma_f32_16x16x32_bf16 v[70:73], v[168:171], v[208:211], v[70:73]
	v_mfma_f32_16x16x32_bf16 v[66:69], v[176:179], v[208:211], v[66:69]
	s_setprio 0
	s_barrier
	s_add_i32 s24, s51, s29
	s_add_u32 s54, s22, s8
	s_addc_u32 s55, s23, s9
	s_mov_b32 m0, s24
	ds_read_b128 v[180:183], v147 offset:49152
	ds_read_b128 v[184:187], v147 offset:50176
	ds_read_b128 v[188:191], v147 offset:51200
	ds_read_b128 v[192:195], v147 offset:52224
	ds_read_b128 v[196:199], v147 offset:53248
	ds_read_b128 v[200:203], v147 offset:54272
	ds_read_b128 v[204:207], v147 offset:55296
	ds_read_b128 v[208:211], v147 offset:56320
	global_load_lds_dwordx4 v132, s[54:55]
	s_add_i32 m0, s24, 0x2000
	s_add_u32 s22, s22, 0x100080
	s_addc_u32 s23, s23, 0
	s_add_i32 s24, s52, s29
	global_load_lds_dwordx4 v130, s[54:55]
	s_mov_b32 m0, s24
	s_nop 0
	global_load_lds_dwordx4 v132, s[22:23]
	s_add_i32 m0, s24, 0x2000
	s_nop 0
	global_load_lds_dwordx4 v130, s[22:23]
	s_mov_b32 m0, s35
	s_nop 0
	global_load_lds_dwordx4 v132, s[56:57]
	s_mov_b32 m0, s36
	s_nop 0
	global_load_lds_dwordx4 v130, s[56:57]
	s_waitcnt vmcnt(8)
	s_waitcnt lgkmcnt(0)
	s_barrier
; #define PG8_MMA(ai, bj, At, Bt) do { __builtin_amdgcn_s_setprio(1); _Pragma("unroll") for (int m = 0; m < 4; ++m) _Pragma("unroll") for (int n = 0; n < 2; ++n) _Pragma("unroll") for (int k = 0; k < 2; ++k) \
;         acc[ai][bj][m][n] = __builtin_amdgcn_mfma_f32_16x16x32_bf16(Bt[n][k], At[m][k], acc[ai][bj][m][n], 0, 0, 0); __builtin_amdgcn_s_setprio(0); } while (0)
; #define PG8_WAIT_V(n) asm volatile("s_waitcnt vmcnt(" #n ")" ::: "memory")
; #define PG8_WAIT_L(n) asm volatile("s_waitcnt lgkmcnt(" #n ")" ::: "memory")
; #define PG8_BAR __builtin_amdgcn_s_barrier()
;     __device__ __forceinline__ void operator()(const f32x4 (&acc)[2][2][4][2], const Unit& u, int wr, int wc, int fr, int fq) const {
;         float* base = C + (size_t)(u.ka / kslab) * slab_stride;
;         const int row0 = u.pm * BM + wr * 64 + fr, col0 = wc * 32 + 4 * fq;
; #pragma unroll
;         for (int ai = 0; ai < 2; ++ai)
; #pragma unroll
;             for (int m = 0; m < 4; ++m) { float* rowp = base + (size_t)(row0 + ai * HALF + m * 16) * 256 + col0;
; #pragma unroll
;                 for (int bj = 0; bj < 2; ++bj)
; #pragma unroll
;                     for (int n = 0; n < 2; ++n) *(f32x4*)(rowp + bj * HALF + n * 16) = acc[ai][bj][m][n]; }
;     }
; template <class Epi, class Sched, bool ALIGN_EPI, class Hook = NoHook>
; __device__ __forceinline__ void gemm_phase(LAS unsigned char* lds, const Gemm g, const Sched& S, const Epi& E, const Hook& H = Hook()) {
;     ...
;             PG8_WAIT_V(8); PG8_WAIT_L(0); PG8_BAR; PG8_MMA(1, 0, At, B0); PG8_MMA(1, 1, At, B1); PG8_BAR; PG8_SCHED;
;         }
;         if constexpr (Hook::ON) H.after(te, acc, cur, wr, wc, fr, fq);
;         }
;         if constexpr (ALIGN_EPI) { if (wr == 0) PG8_BAR; }
;         if constexpr (!Epi::AFTER_DRAIN) { E(acc, cur, wr, wc, fr, fq); S.done(cur); }
;         if (!has_next) break;
;         if constexpr (Hook::ON) H.unit_start(nxt);
; #pragma unroll
;         for (int a = 0; a < 2; ++a)
; #pragma unroll
;             for (int b = 0; b < 2; ++b)
; #pragma unroll
;                 for (int m = 0; m < 4; ++m)
; #pragma unroll
;                     for (int n = 0; n < 2; ++n) acc[a][b][m][n] = (f32x4){0.f, 0.f, 0.f, 0.f};
;         cur = nxt; cA = nA; cB = nB; ++ui;
;         if constexpr (ALIGN_EPI) { if (wr == 1) PG8_BAR; }
;     }
;     PG8_WAIT_V(0);
;     if constexpr (!ALIGN_EPI) { if (wr == 0) PG8_BAR; }
	s_setprio 1
	s_waitcnt lgkmcnt(0)
	v_mfma_f32_16x16x32_bf16 v[62:65], v[148:151], v[180:183], v[62:65]
	v_mfma_f32_16x16x32_bf16 v[58:61], v[156:159], v[180:183], v[58:61]
	v_mfma_f32_16x16x32_bf16 v[54:57], v[148:151], v[188:191], v[54:57]
	v_mfma_f32_16x16x32_bf16 v[50:53], v[156:159], v[188:191], v[50:53]
	v_mfma_f32_16x16x32_bf16 v[38:41], v[148:151], v[196:199], v[38:41]
	v_mfma_f32_16x16x32_bf16 v[34:37], v[156:159], v[196:199], v[34:37]
	v_mfma_f32_16x16x32_bf16 v[22:25], v[148:151], v[204:207], v[22:25]
	v_mfma_f32_16x16x32_bf16 v[18:21], v[156:159], v[204:207], v[18:21]
	v_mfma_f32_16x16x32_bf16 v[62:65], v[152:155], v[184:187], v[62:65]
	v_mfma_f32_16x16x32_bf16 v[58:61], v[160:163], v[184:187], v[58:61]
	v_mfma_f32_16x16x32_bf16 v[54:57], v[152:155], v[192:195], v[54:57]
	v_mfma_f32_16x16x32_bf16 v[50:53], v[160:163], v[192:195], v[50:53]
	v_mfma_f32_16x16x32_bf16 v[38:41], v[152:155], v[200:203], v[38:41]
	v_mfma_f32_16x16x32_bf16 v[34:37], v[160:163], v[200:203], v[34:37]
	v_mfma_f32_16x16x32_bf16 v[22:25], v[152:155], v[208:211], v[22:25]
	v_mfma_f32_16x16x32_bf16 v[18:21], v[160:163], v[208:211], v[18:21]
	s_setprio 0
	s_setprio 1
	v_mfma_f32_16x16x32_bf16 v[46:49], v[164:167], v[180:183], v[46:49]
	v_mfma_f32_16x16x32_bf16 v[42:45], v[172:175], v[180:183], v[42:45]
	v_mfma_f32_16x16x32_bf16 v[30:33], v[164:167], v[188:191], v[30:33]
	v_mfma_f32_16x16x32_bf16 v[26:29], v[172:175], v[188:191], v[26:29]
	v_mfma_f32_16x16x32_bf16 v[14:17], v[164:167], v[196:199], v[14:17]
	v_mfma_f32_16x16x32_bf16 v[10:13], v[172:175], v[196:199], v[10:13]
	v_mfma_f32_16x16x32_bf16 v[6:9], v[164:167], v[204:207], v[6:9]
	v_mfma_f32_16x16x32_bf16 v[2:5], v[172:175], v[204:207], v[2:5]
	v_mfma_f32_16x16x32_bf16 v[46:49], v[168:171], v[184:187], v[46:49]
	v_mfma_f32_16x16x32_bf16 v[42:45], v[176:179], v[184:187], v[42:45]
	v_mfma_f32_16x16x32_bf16 v[30:33], v[168:171], v[192:195], v[30:33]
	v_mfma_f32_16x16x32_bf16 v[26:29], v[176:179], v[192:195], v[26:29]
	v_mfma_f32_16x16x32_bf16 v[14:17], v[168:171], v[200:203], v[14:17]
	v_mfma_f32_16x16x32_bf16 v[10:13], v[176:179], v[200:203], v[10:13]
	v_mfma_f32_16x16x32_bf16 v[6:9], v[168:171], v[208:211], v[6:9]
	v_mfma_f32_16x16x32_bf16 v[2:5], v[176:179], v[208:211], v[2:5]
	s_setprio 0
	s_barrier
	s_add_i32 s50, s50, 2
	s_add_u32 s20, s20, 0x100
	s_addc_u32 s21, s21, 0
	s_add_u32 s42, s42, 0x100
	s_addc_u32 s43, s43, 0
	s_cmp_gt_u32 s50, 5
	s_cbranch_scc0 .LBB0_262
	s_ashr_i32 s11, s6, 31
	s_lshr_b32 s11, s11, 23
	s_add_i32 s6, s6, s11
	s_ashr_i32 s20, s6, 9
	s_ashr_i32 s21, s20, 31
	v_lshl_add_u32 v148, s4, 8, v1
	s_lshl_b64 s[20:21], s[20:21], 23
	v_ashrrev_i32_e32 v149, 31, v148
	v_lshl_add_u64 v[150:151], v[134:135], 0, s[20:21]
	v_lshlrev_b64 v[152:153], 10, v[148:149]
	v_lshl_add_u64 v[152:153], v[150:151], 0, v[152:153]
	global_store_dwordx4 v[152:153], v[126:129], off
	global_store_dwordx4 v[152:153], v[122:125], off offset:64
	global_store_dwordx4 v[152:153], v[110:113], off offset:512
	global_store_dwordx4 v[152:153], v[102:105], off offset:576
	s_mov_b32 s4, 0x20000
	s_mov_b64 s[20:21], 0x20000
	v_or_b32_e32 v102, 16, v148
	v_ashrrev_i32_e32 v103, 31, v102
	v_lshlrev_b64 v[102:103], 10, v[102:103]
	v_lshl_add_u64 v[102:103], v[150:151], 0, v[102:103]
	global_store_dwordx4 v[102:103], v[118:121], off
	global_store_dwordx4 v[102:103], v[114:117], off offset:64
	global_store_dwordx4 v[102:103], v[94:97], off offset:512
	global_store_dwordx4 v[102:103], v[86:89], off offset:576
	s_mov_b32 s6, s12
	s_mov_b64 s[22:23], s[18:19]
	v_or_b32_e32 v86, 32, v148
	v_ashrrev_i32_e32 v87, 31, v86
	v_lshlrev_b64 v[86:87], 10, v[86:87]
	v_lshl_add_u64 v[86:87], v[150:151], 0, v[86:87]
	global_store_dwordx4 v[86:87], v[106:109], off
	global_store_dwordx4 v[86:87], v[98:101], off offset:64
	global_store_dwordx4 v[86:87], v[78:81], off offset:512
	global_store_dwordx4 v[86:87], v[74:77], off offset:576
	s_nop 1
	v_or_b32_e32 v74, 48, v148
	v_ashrrev_i32_e32 v75, 31, v74
	v_lshlrev_b64 v[74:75], 10, v[74:75]
	v_lshl_add_u64 v[74:75], v[150:151], 0, v[74:75]
	global_store_dwordx4 v[74:75], v[90:93], off
	global_store_dwordx4 v[74:75], v[82:85], off offset:64
	global_store_dwordx4 v[74:75], v[70:73], off offset:512
	global_store_dwordx4 v[74:75], v[66:69], off offset:576
	s_nop 1
	v_add_co_u32_e32 v68, vcc, s4, v152
	s_mov_b32 s4, 0x24000
	s_nop 0
	v_addc_co_u32_e32 v69, vcc, 0, v153, vcc
	v_lshl_add_u64 v[66:67], v[152:153], 0, s[20:21]
	global_store_dwordx4 v[68:69], v[62:65], off
	global_store_dwordx4 v[66:67], v[58:61], off offset:64
	global_store_dwordx4 v[66:67], v[46:49], off offset:512
	global_store_dwordx4 v[66:67], v[42:45], off offset:576
	s_mov_b64 s[20:21], 0x24000
	s_nop 0
	v_add_co_u32_e32 v44, vcc, s4, v152
	s_mov_b32 s4, 0x28000
	s_nop 0
	v_addc_co_u32_e32 v45, vcc, 0, v153, vcc
	v_lshl_add_u64 v[42:43], v[152:153], 0, s[20:21]
	global_store_dwordx4 v[44:45], v[54:57], off
	global_store_dwordx4 v[42:43], v[50:53], off offset:64
	global_store_dwordx4 v[42:43], v[30:33], off offset:512
	global_store_dwordx4 v[42:43], v[26:29], off offset:576
	s_mov_b64 s[20:21], 0x28000
	s_nop 0
	v_add_co_u32_e32 v28, vcc, s4, v152
	v_lshl_add_u64 v[26:27], v[152:153], 0, s[20:21]
	s_nop 0
	v_addc_co_u32_e32 v29, vcc, 0, v153, vcc
	global_store_dwordx4 v[28:29], v[38:41], off
	global_store_dwordx4 v[26:27], v[34:37], off offset:64
	global_store_dwordx4 v[26:27], v[14:17], off offset:512
	global_store_dwordx4 v[26:27], v[10:13], off offset:576
	s_mov_b64 s[20:21], 0x2c000
	s_mov_b32 s4, s10
	v_add_co_u32_e32 v12, vcc, 0x2c000, v152
	v_lshl_add_u64 v[10:11], v[152:153], 0, s[20:21]
	s_nop 0
	v_addc_co_u32_e32 v13, vcc, 0, v153, vcc
	s_and_b64 vcc, exec, s[2:3]
	s_mov_b64 s[20:21], s[14:15]
	global_store_dwordx4 v[12:13], v[22:25], off
	global_store_dwordx4 v[10:11], v[18:21], off offset:64
	global_store_dwordx4 v[10:11], v[6:9], off offset:512
	global_store_dwordx4 v[10:11], v[2:5], off offset:576
	s_cbranch_vccz .LBB0_259
	s_waitcnt vmcnt(0)
	s_cmpk_gt_u32 s26, 0xff
	s_cbranch_scc1 .LBB0_266
	s_barrier

; #define PG8_STAGE(bufoff, gbase, voff) do { _Pragma("unroll") for (int _i = 0; _i < 2; ++_i) \
;         __builtin_amdgcn_global_load_lds((const unsigned*)((const char*)(gbase) + (voff)[_i]), (LAS unsigned*)(lds + (bufoff) + ldsw + _i * 8192), 16, 0, 0); } while (0)
; #define PG8_LDA(dst, b, h) do { _Pragma("unroll") for (int m = 0; m < 4; ++m) _Pragma("unroll") for (int k = 0; k < 2; ++k) dst[m][k] = *(const LAS bf16x8*)(lds + PG8_SA(b, h) + aoff + m * 2048 + k * 1024); } while (0)
; #define PG8_LDB(dst, b, h) do { _Pragma("unroll") for (int n = 0; n < 2; ++n) _Pragma("unroll") for (int k = 0; k < 2; ++k) dst[n][k] = *(const LAS bf16x8*)(lds + PG8_SB(b, h) + boff + n * 2048 + k * 1024); } while (0)
; #define PG8_MMA(ai, bj, At, Bt) do { __builtin_amdgcn_s_setprio(1); _Pragma("unroll") for (int m = 0; m < 4; ++m) _Pragma("unroll") for (int n = 0; n < 2; ++n) _Pragma("unroll") for (int k = 0; k < 2; ++k) \
;         acc[ai][bj][m][n] = __builtin_amdgcn_mfma_f32_16x16x32_bf16(Bt[n][k], At[m][k], acc[ai][bj][m][n], 0, 0, 0); __builtin_amdgcn_s_setprio(0); } while (0)
; #define PG8_WAIT_V(n) asm volatile("s_waitcnt vmcnt(" #n ")" ::: "memory")
; #define PG8_WAIT_L(n) asm volatile("s_waitcnt lgkmcnt(" #n ")" ::: "memory")
; #define PG8_BAR __builtin_amdgcn_s_barrier()
; template <class Epi, class Sched, bool ALIGN_EPI, class Hook = NoHook>
; __device__ __forceinline__ void gemm_phase(LAS unsigned char* lds, const Gemm g, const Sched& S, const Epi& E, const Hook& H = Hook()) {
;     ...
;             const bool last = (t == nt - 2);
;             const char* a1 = cA + (size_t)(t + 1) * kstep;
;             const char* a2 = last ? nA : cA + (size_t)(t + 2) * kstep; const char* b2 = last ? nB : cB + (size_t)(t + 2) * kstep;
;             const char* a3 = a2 + kstep; const char* b3 = b2 + kstep;
;             if (last && has_next) S.a_ready(nxt);
;             PG8_LDB(B0, 0, 0); PG8_LDB(B1, 0, 1); PG8_SCHED; PG8_LDA(At, 0, 0); PG8_STAGE(PG8_SA(1, 1), a1 + hA, voffA);
;             PG8_WAIT_V(8); PG8_WAIT_L(0); PG8_BAR; PG8_MMA(0, 0, At, B0); PG8_MMA(0, 1, At, B1); PG8_BAR; PG8_SCHED;
;             PG8_LDA(At, 0, 1); PG8_STAGE(PG8_SB(0, 0), b2, voffB); PG8_STAGE(PG8_SB(0, 1), b2 + hB, voffB); PG8_STAGE(PG8_SA(0, 0), a2, voffA);
;             PG8_WAIT_V(8); PG8_WAIT_L(0); PG8_BAR; PG8_MMA(1, 0, At, B0); PG8_MMA(1, 1, At, B1); PG8_BAR; PG8_SCHED;
.LBB0_783:
	v_add_u32_e32 v3, s56, v222
	s_add_i32 s67, s67, 2
	ds_read_b128 v[126:129], v3
	ds_read_b128 v[130:133], v3 offset:1024
	ds_read_b128 v[142:145], v3 offset:2048
	ds_read_b128 v[146:149], v3 offset:3072
	v_add_u32_e32 v3, s57, v222
	s_add_u32 s28, s22, s26
	ds_read_b128 v[150:153], v3
	ds_read_b128 v[154:157], v3 offset:1024
	ds_read_b128 v[158:161], v3 offset:2048
	ds_read_b128 v[162:165], v3 offset:3072
	s_addc_u32 s29, s23, s27
	s_add_u32 s28, s28, 0x100
	s_addc_u32 s29, s29, 0
	s_add_u32 s68, s63, s26
	s_addc_u32 s69, s64, s27
	s_cmpk_eq_i32 s26, 0x5f00
	s_cselect_b32 s31, s5, s29
	s_cselect_b32 s30, s4, s28
	s_cselect_b32 s29, s21, s69
	s_cselect_b32 s28, s20, s68
	v_lshl_add_u64 v[4:5], v[182:183], 0, s[26:27]
	s_add_i32 m0, s37, 0xc000
	ds_read_b128 v[186:189], v224
	ds_read_b128 v[190:193], v224 offset:1024
	ds_read_b128 v[194:197], v224 offset:2048
	ds_read_b128 v[198:201], v224 offset:3072
	ds_read_b128 v[202:205], v224 offset:4096
	ds_read_b128 v[206:209], v224 offset:5120
	ds_read_b128 v[210:213], v224 offset:6144
	ds_read_b128 v[214:217], v224 offset:7168
	global_load_lds_dwordx4 v[4:5], off
	v_lshl_add_u64 v[4:5], v[184:185], 0, s[26:27]
	s_add_i32 m0, s37, 0xe000
	s_nop 0
	global_load_lds_dwordx4 v[4:5], off
	s_waitcnt vmcnt(8)
	s_waitcnt lgkmcnt(0)
	s_barrier
	s_setprio 1
	s_waitcnt lgkmcnt(0)
	v_mfma_f32_16x16x32_bf16 v[138:141], v[126:129], v[186:189], v[138:141]
	v_mfma_f32_16x16x32_bf16 v[134:137], v[142:145], v[186:189], v[134:137]
	v_mfma_f32_16x16x32_bf16 v[122:125], v[126:129], v[194:197], v[122:125]
	v_mfma_f32_16x16x32_bf16 v[118:121], v[142:145], v[194:197], v[118:121]
	v_mfma_f32_16x16x32_bf16 v[114:117], v[126:129], v[202:205], v[114:117]
	v_mfma_f32_16x16x32_bf16 v[110:113], v[142:145], v[202:205], v[110:113]
	v_mfma_f32_16x16x32_bf16 v[106:109], v[126:129], v[210:213], v[106:109]
	v_mfma_f32_16x16x32_bf16 v[102:105], v[142:145], v[210:213], v[102:105]
	v_mfma_f32_16x16x32_bf16 v[138:141], v[130:133], v[190:193], v[138:141]
	v_mfma_f32_16x16x32_bf16 v[134:137], v[146:149], v[190:193], v[134:137]
	v_mfma_f32_16x16x32_bf16 v[122:125], v[130:133], v[198:201], v[122:125]
	v_mfma_f32_16x16x32_bf16 v[118:121], v[146:149], v[198:201], v[118:121]
	v_mfma_f32_16x16x32_bf16 v[114:117], v[130:133], v[206:209], v[114:117]
	v_mfma_f32_16x16x32_bf16 v[110:113], v[146:149], v[206:209], v[110:113]
	v_mfma_f32_16x16x32_bf16 v[106:109], v[130:133], v[214:217], v[106:109]
	v_mfma_f32_16x16x32_bf16 v[102:105], v[146:149], v[214:217], v[102:105]
	s_setprio 0
	s_setprio 1
	v_mfma_f32_16x16x32_bf16 v[66:69], v[150:153], v[186:189], v[66:69]
	v_mfma_f32_16x16x32_bf16 v[62:65], v[158:161], v[186:189], v[62:65]
	v_mfma_f32_16x16x32_bf16 v[58:61], v[150:153], v[194:197], v[58:61]
	v_mfma_f32_16x16x32_bf16 v[54:57], v[158:161], v[194:197], v[54:57]
	v_mfma_f32_16x16x32_bf16 v[50:53], v[150:153], v[202:205], v[50:53]
	v_mfma_f32_16x16x32_bf16 v[46:49], v[158:161], v[202:205], v[46:49]
	v_mfma_f32_16x16x32_bf16 v[42:45], v[150:153], v[210:213], v[42:45]
	v_mfma_f32_16x16x32_bf16 v[38:41], v[158:161], v[210:213], v[38:41]
	v_mfma_f32_16x16x32_bf16 v[66:69], v[154:157], v[190:193], v[66:69]
	v_mfma_f32_16x16x32_bf16 v[62:65], v[162:165], v[190:193], v[62:65]
	v_mfma_f32_16x16x32_bf16 v[58:61], v[154:157], v[198:201], v[58:61]
	v_mfma_f32_16x16x32_bf16 v[54:57], v[162:165], v[198:201], v[54:57]
	v_mfma_f32_16x16x32_bf16 v[50:53], v[154:157], v[206:209], v[50:53]
	v_mfma_f32_16x16x32_bf16 v[46:49], v[162:165], v[206:209], v[46:49]
	v_mfma_f32_16x16x32_bf16 v[42:45], v[154:157], v[214:217], v[42:45]
	v_mfma_f32_16x16x32_bf16 v[38:41], v[162:165], v[214:217], v[38:41]
	s_setprio 0
	s_barrier
	s_add_i32 s68, s56, s35
	s_mov_b32 m0, s68
	ds_read_b128 v[186:189], v224 offset:16384
	ds_read_b128 v[190:193], v224 offset:17408
	ds_read_b128 v[194:197], v224 offset:18432
	ds_read_b128 v[198:201], v224 offset:19456
	ds_read_b128 v[202:205], v224 offset:20480
	ds_read_b128 v[206:209], v224 offset:21504
	ds_read_b128 v[210:213], v224 offset:22528
	ds_read_b128 v[214:217], v224 offset:23552
	global_load_lds_dwordx4 v168, s[28:29]
	s_add_i32 m0, s68, 0x2000
	s_add_u32 s68, s28, 0x300000
	s_addc_u32 s69, s29, 0
	s_add_i32 s70, s57, s35
	global_load_lds_dwordx4 v172, s[28:29]
	s_mov_b32 m0, s70
	s_add_u32 s74, s30, s14
	s_addc_u32 s75, s31, s15
	global_load_lds_dwordx4 v168, s[68:69]
	s_add_i32 m0, s70, 0x2000
	s_nop 0
	global_load_lds_dwordx4 v172, s[68:69]
	s_mov_b32 m0, s37
	s_nop 0
	global_load_lds_dwordx4 v166, s[30:31]
	s_mov_b32 m0, s38
	s_nop 0
	global_load_lds_dwordx4 v170, s[30:31]
	s_waitcnt vmcnt(8)
	s_waitcnt lgkmcnt(0)
	s_barrier
; #define PG8_STAGE(bufoff, gbase, voff) do { _Pragma("unroll") for (int _i = 0; _i < 2; ++_i) \
;         __builtin_amdgcn_global_load_lds((const unsigned*)((const char*)(gbase) + (voff)[_i]), (LAS unsigned*)(lds + (bufoff) + ldsw + _i * 8192), 16, 0, 0); } while (0)
; #define PG8_LDA(dst, b, h) do { _Pragma("unroll") for (int m = 0; m < 4; ++m) _Pragma("unroll") for (int k = 0; k < 2; ++k) dst[m][k] = *(const LAS bf16x8*)(lds + PG8_SA(b, h) + aoff + m * 2048 + k * 1024); } while (0)
; #define PG8_LDB(dst, b, h) do { _Pragma("unroll") for (int n = 0; n < 2; ++n) _Pragma("unroll") for (int k = 0; k < 2; ++k) dst[n][k] = *(const LAS bf16x8*)(lds + PG8_SB(b, h) + boff + n * 2048 + k * 1024); } while (0)
; #define PG8_MMA(ai, bj, At, Bt) do { __builtin_amdgcn_s_setprio(1); _Pragma("unroll") for (int m = 0; m < 4; ++m) _Pragma("unroll") for (int n = 0; n < 2; ++n) _Pragma("unroll") for (int k = 0; k < 2; ++k) \
;         acc[ai][bj][m][n] = __builtin_amdgcn_mfma_f32_16x16x32_bf16(Bt[n][k], At[m][k], acc[ai][bj][m][n], 0, 0, 0); __builtin_amdgcn_s_setprio(0); } while (0)
; #define PG8_WAIT_V(n) asm volatile("s_waitcnt vmcnt(" #n ")" ::: "memory")
; #define PG8_WAIT_L(n) asm volatile("s_waitcnt lgkmcnt(" #n ")" ::: "memory")
; #define PG8_BAR __builtin_amdgcn_s_barrier()
; #define PG8_SCHED __builtin_amdgcn_sched_barrier(0)
; template <class Epi, class Sched, bool ALIGN_EPI, class Hook = NoHook>
; __device__ __forceinline__ void gemm_phase(LAS unsigned char* lds, const Gemm g, const Sched& S, const Epi& E, const Hook& H = Hook()) {
;     ...
;             PG8_WAIT_V(8); PG8_WAIT_L(0); PG8_BAR; PG8_MMA(1, 0, At, B0); PG8_MMA(1, 1, At, B1); PG8_BAR; PG8_SCHED;
;             PG8_LDB(B0, 1, 0); PG8_LDB(B1, 1, 1); PG8_SCHED; PG8_LDA(At, 1, 0); PG8_STAGE(PG8_SA(0, 1), a2 + hA, voffA);
;             PG8_WAIT_V(8); PG8_WAIT_L(0); PG8_BAR; PG8_MMA(0, 0, At, B0); PG8_MMA(0, 1, At, B1); PG8_BAR; PG8_SCHED;
	s_setprio 1
	s_waitcnt lgkmcnt(0)
	v_mfma_f32_16x16x32_bf16 v[98:101], v[126:129], v[186:189], v[98:101]
	v_mfma_f32_16x16x32_bf16 v[94:97], v[142:145], v[186:189], v[94:97]
	v_mfma_f32_16x16x32_bf16 v[90:93], v[126:129], v[194:197], v[90:93]
	v_mfma_f32_16x16x32_bf16 v[86:89], v[142:145], v[194:197], v[86:89]
	v_mfma_f32_16x16x32_bf16 v[82:85], v[126:129], v[202:205], v[82:85]
	v_mfma_f32_16x16x32_bf16 v[78:81], v[142:145], v[202:205], v[78:81]
	v_mfma_f32_16x16x32_bf16 v[74:77], v[126:129], v[210:213], v[74:77]
	v_mfma_f32_16x16x32_bf16 v[70:73], v[142:145], v[210:213], v[70:73]
	v_mfma_f32_16x16x32_bf16 v[98:101], v[130:133], v[190:193], v[98:101]
	v_mfma_f32_16x16x32_bf16 v[94:97], v[146:149], v[190:193], v[94:97]
	v_mfma_f32_16x16x32_bf16 v[90:93], v[130:133], v[198:201], v[90:93]
	v_mfma_f32_16x16x32_bf16 v[86:89], v[146:149], v[198:201], v[86:89]
	v_mfma_f32_16x16x32_bf16 v[82:85], v[130:133], v[206:209], v[82:85]
	v_mfma_f32_16x16x32_bf16 v[78:81], v[146:149], v[206:209], v[78:81]
	v_mfma_f32_16x16x32_bf16 v[74:77], v[130:133], v[214:217], v[74:77]
	v_mfma_f32_16x16x32_bf16 v[70:73], v[146:149], v[214:217], v[70:73]
	s_setprio 0
	s_setprio 1
	v_mfma_f32_16x16x32_bf16 v[34:37], v[150:153], v[186:189], v[34:37]
	v_mfma_f32_16x16x32_bf16 v[30:33], v[158:161], v[186:189], v[30:33]
	v_mfma_f32_16x16x32_bf16 v[26:29], v[150:153], v[194:197], v[26:29]
	v_mfma_f32_16x16x32_bf16 v[22:25], v[158:161], v[194:197], v[22:25]
	v_mfma_f32_16x16x32_bf16 v[18:21], v[150:153], v[202:205], v[18:21]
	v_mfma_f32_16x16x32_bf16 v[14:17], v[158:161], v[202:205], v[14:17]
	v_mfma_f32_16x16x32_bf16 v[10:13], v[150:153], v[210:213], v[10:13]
	v_mfma_f32_16x16x32_bf16 v[4:7], v[158:161], v[210:213], v[6:9]
	v_mfma_f32_16x16x32_bf16 v[34:37], v[154:157], v[190:193], v[34:37]
	v_mfma_f32_16x16x32_bf16 v[30:33], v[162:165], v[190:193], v[30:33]
	v_mfma_f32_16x16x32_bf16 v[26:29], v[154:157], v[198:201], v[26:29]
	v_mfma_f32_16x16x32_bf16 v[22:25], v[162:165], v[198:201], v[22:25]
	v_mfma_f32_16x16x32_bf16 v[18:21], v[154:157], v[206:209], v[18:21]
	v_mfma_f32_16x16x32_bf16 v[14:17], v[162:165], v[206:209], v[14:17]
	v_mfma_f32_16x16x32_bf16 v[10:13], v[154:157], v[214:217], v[10:13]
	v_mfma_f32_16x16x32_bf16 v[4:7], v[162:165], v[214:217], v[4:7]
	s_setprio 0
	s_barrier
	s_add_i32 s68, 0, 0x18000
	v_add_u32_e32 v3, s68, v222
	s_add_i32 s69, 0, 0x1c000
	ds_read_b128 v[126:129], v3
	ds_read_b128 v[130:133], v3 offset:1024
	ds_read_b128 v[142:145], v3 offset:2048
	ds_read_b128 v[146:149], v3 offset:3072
	v_add_u32_e32 v3, s69, v222
	ds_read_b128 v[150:153], v3
	ds_read_b128 v[154:157], v3 offset:1024
	ds_read_b128 v[158:161], v3 offset:2048
	ds_read_b128 v[162:165], v3 offset:3072
	s_add_u32 s30, s30, 0x300000
	s_addc_u32 s31, s31, 0
	s_mov_b32 m0, s39
	ds_read_b128 v[186:189], v224 offset:32768
	ds_read_b128 v[190:193], v224 offset:33792
	ds_read_b128 v[194:197], v224 offset:34816
	ds_read_b128 v[198:201], v224 offset:35840
	ds_read_b128 v[202:205], v224 offset:36864
	ds_read_b128 v[206:209], v224 offset:37888
	ds_read_b128 v[210:213], v224 offset:38912
	ds_read_b128 v[214:217], v224 offset:39936
	global_load_lds_dwordx4 v166, s[30:31]
	s_mov_b32 m0, s40
	s_nop 0
	global_load_lds_dwordx4 v170, s[30:31]
	s_waitcnt vmcnt(8)
	s_waitcnt lgkmcnt(0)
	s_barrier
	s_setprio 1
	s_waitcnt lgkmcnt(0)
	v_mfma_f32_16x16x32_bf16 v[138:141], v[126:129], v[186:189], v[138:141]
	v_mfma_f32_16x16x32_bf16 v[134:137], v[142:145], v[186:189], v[134:137]
	v_mfma_f32_16x16x32_bf16 v[122:125], v[126:129], v[194:197], v[122:125]
	v_mfma_f32_16x16x32_bf16 v[118:121], v[142:145], v[194:197], v[118:121]
	v_mfma_f32_16x16x32_bf16 v[114:117], v[126:129], v[202:205], v[114:117]
	v_mfma_f32_16x16x32_bf16 v[110:113], v[142:145], v[202:205], v[110:113]
	v_mfma_f32_16x16x32_bf16 v[106:109], v[126:129], v[210:213], v[106:109]
	v_mfma_f32_16x16x32_bf16 v[102:105], v[142:145], v[210:213], v[102:105]
	v_mfma_f32_16x16x32_bf16 v[138:141], v[130:133], v[190:193], v[138:141]
	v_mfma_f32_16x16x32_bf16 v[134:137], v[146:149], v[190:193], v[134:137]
	v_mfma_f32_16x16x32_bf16 v[122:125], v[130:133], v[198:201], v[122:125]
	v_mfma_f32_16x16x32_bf16 v[118:121], v[146:149], v[198:201], v[118:121]
	v_mfma_f32_16x16x32_bf16 v[114:117], v[130:133], v[206:209], v[114:117]
	v_mfma_f32_16x16x32_bf16 v[110:113], v[146:149], v[206:209], v[110:113]
	v_mfma_f32_16x16x32_bf16 v[106:109], v[130:133], v[214:217], v[106:109]
	v_mfma_f32_16x16x32_bf16 v[102:105], v[146:149], v[214:217], v[102:105]
	s_setprio 0
	s_setprio 1
	v_mfma_f32_16x16x32_bf16 v[66:69], v[150:153], v[186:189], v[66:69]
	v_mfma_f32_16x16x32_bf16 v[62:65], v[158:161], v[186:189], v[62:65]
	v_mfma_f32_16x16x32_bf16 v[58:61], v[150:153], v[194:197], v[58:61]
	v_mfma_f32_16x16x32_bf16 v[54:57], v[158:161], v[194:197], v[54:57]
	v_mfma_f32_16x16x32_bf16 v[50:53], v[150:153], v[202:205], v[50:53]
	v_mfma_f32_16x16x32_bf16 v[46:49], v[158:161], v[202:205], v[46:49]
	v_mfma_f32_16x16x32_bf16 v[42:45], v[150:153], v[210:213], v[42:45]
	v_mfma_f32_16x16x32_bf16 v[38:41], v[158:161], v[210:213], v[38:41]
	v_mfma_f32_16x16x32_bf16 v[66:69], v[154:157], v[190:193], v[66:69]
	v_mfma_f32_16x16x32_bf16 v[62:65], v[162:165], v[190:193], v[62:65]
	v_mfma_f32_16x16x32_bf16 v[58:61], v[154:157], v[198:201], v[58:61]
	v_mfma_f32_16x16x32_bf16 v[54:57], v[162:165], v[198:201], v[54:57]
	v_mfma_f32_16x16x32_bf16 v[50:53], v[154:157], v[206:209], v[50:53]
	v_mfma_f32_16x16x32_bf16 v[46:49], v[162:165], v[206:209], v[46:49]
	v_mfma_f32_16x16x32_bf16 v[42:45], v[154:157], v[214:217], v[42:45]
	v_mfma_f32_16x16x32_bf16 v[38:41], v[162:165], v[214:217], v[38:41]
	s_setprio 0
	s_barrier
; #define PG8_STAGE(bufoff, gbase, voff) do { _Pragma("unroll") for (int _i = 0; _i < 2; ++_i) \
;         __builtin_amdgcn_global_load_lds((const unsigned*)((const char*)(gbase) + (voff)[_i]), (LAS unsigned*)(lds + (bufoff) + ldsw + _i * 8192), 16, 0, 0); } while (0)
; #define PG8_LDA(dst, b, h) do { _Pragma("unroll") for (int m = 0; m < 4; ++m) _Pragma("unroll") for (int k = 0; k < 2; ++k) dst[m][k] = *(const LAS bf16x8*)(lds + PG8_SA(b, h) + aoff + m * 2048 + k * 1024); } while (0)
; #define PG8_MMA(ai, bj, At, Bt) do { __builtin_amdgcn_s_setprio(1); _Pragma("unroll") for (int m = 0; m < 4; ++m) _Pragma("unroll") for (int n = 0; n < 2; ++n) _Pragma("unroll") for (int k = 0; k < 2; ++k) \
;         acc[ai][bj][m][n] = __builtin_amdgcn_mfma_f32_16x16x32_bf16(Bt[n][k], At[m][k], acc[ai][bj][m][n], 0, 0, 0); __builtin_amdgcn_s_setprio(0); } while (0)
; #define PG8_WAIT_V(n) asm volatile("s_waitcnt vmcnt(" #n ")" ::: "memory")
; #define PG8_WAIT_L(n) asm volatile("s_waitcnt lgkmcnt(" #n ")" ::: "memory")
; #define PG8_BAR __builtin_amdgcn_s_barrier()
; #define PG8_SCHED __builtin_amdgcn_sched_barrier(0)
;     __device__ __forceinline__ void after(int te, f32x4 (&acc)[2][2][4][2], const Unit& u, int wr, int wc, int fr, int fq) const {
;         if (te > D_INNER / BK) return;
;         const int g = (te >> 4) - 1;
;         asm volatile("" : "+v"(fr), "+v"(fq));
; #pragma unroll
;         for (int ai = 0; ai < 2; ++ai)
; #pragma unroll
;             for (int m = 0; m < 4; ++m) { const float f = tab[(ai * HALF + wr * 64 + m * 16 + fr) * 8 + g];
; #pragma unroll
;                 for (int bj = 0; bj < 2; ++bj)
; #pragma unroll
;                     for (int n = 0; n < 2; ++n) acc[ai][bj][m][n] *= f; }
; template <class Epi, class Sched, bool ALIGN_EPI, class Hook = NoHook>
; __device__ __forceinline__ void gemm_phase(LAS unsigned char* lds, const Gemm g, const Sched& S, const Epi& E, const Hook& H = Hook()) {
;     ...
;             PG8_LDA(At, 1, 1); PG8_STAGE(PG8_SB(1, 0), b3, voffB); PG8_STAGE(PG8_SB(1, 1), b3 + hB, voffB); PG8_STAGE(PG8_SA(1, 0), a3, voffA);
;             PG8_WAIT_V(8); PG8_WAIT_L(0); PG8_BAR; PG8_MMA(1, 0, At, B0); PG8_MMA(1, 1, At, B1); PG8_BAR; PG8_SCHED;
;         }
;         if constexpr (Hook::ON) H.after(te, acc, cur, wr, wc, fr, fq);
	s_add_i32 s30, s68, s35
	s_add_u32 s72, s28, s14
	s_addc_u32 s73, s29, s15
	s_mov_b32 m0, s30
	ds_read_b128 v[186:189], v224 offset:49152
	ds_read_b128 v[190:193], v224 offset:50176
	ds_read_b128 v[194:197], v224 offset:51200
	ds_read_b128 v[198:201], v224 offset:52224
	ds_read_b128 v[202:205], v224 offset:53248
	ds_read_b128 v[206:209], v224 offset:54272
	ds_read_b128 v[210:213], v224 offset:55296
	ds_read_b128 v[214:217], v224 offset:56320
	global_load_lds_dwordx4 v168, s[72:73]
	s_add_i32 m0, s30, 0x2000
	s_add_u32 s28, s28, 0x300080
	s_addc_u32 s29, s29, 0
	s_add_i32 s30, s69, s35
	global_load_lds_dwordx4 v172, s[72:73]
	s_mov_b32 m0, s30
	s_nop 0
	global_load_lds_dwordx4 v168, s[28:29]
	s_add_i32 m0, s30, 0x2000
	s_nop 0
	global_load_lds_dwordx4 v172, s[28:29]
	s_mov_b32 m0, s45
	s_nop 0
	global_load_lds_dwordx4 v166, s[74:75]
	s_mov_b32 m0, s46
	s_nop 0
	global_load_lds_dwordx4 v170, s[74:75]
	s_waitcnt vmcnt(8)
	s_waitcnt lgkmcnt(0)
	s_barrier
	s_setprio 1
	s_waitcnt lgkmcnt(0)
	v_mfma_f32_16x16x32_bf16 v[98:101], v[126:129], v[186:189], v[98:101]
	v_mfma_f32_16x16x32_bf16 v[94:97], v[142:145], v[186:189], v[94:97]
	v_mfma_f32_16x16x32_bf16 v[90:93], v[126:129], v[194:197], v[90:93]
	v_mfma_f32_16x16x32_bf16 v[86:89], v[142:145], v[194:197], v[86:89]
	v_mfma_f32_16x16x32_bf16 v[82:85], v[126:129], v[202:205], v[82:85]
	v_mfma_f32_16x16x32_bf16 v[78:81], v[142:145], v[202:205], v[78:81]
	v_mfma_f32_16x16x32_bf16 v[74:77], v[126:129], v[210:213], v[74:77]
	v_mfma_f32_16x16x32_bf16 v[70:73], v[142:145], v[210:213], v[70:73]
	v_mfma_f32_16x16x32_bf16 v[98:101], v[130:133], v[190:193], v[98:101]
	v_mfma_f32_16x16x32_bf16 v[94:97], v[146:149], v[190:193], v[94:97]
	v_mfma_f32_16x16x32_bf16 v[90:93], v[130:133], v[198:201], v[90:93]
	v_mfma_f32_16x16x32_bf16 v[86:89], v[146:149], v[198:201], v[86:89]
	v_mfma_f32_16x16x32_bf16 v[82:85], v[130:133], v[206:209], v[82:85]
	v_mfma_f32_16x16x32_bf16 v[78:81], v[146:149], v[206:209], v[78:81]
	v_mfma_f32_16x16x32_bf16 v[74:77], v[130:133], v[214:217], v[74:77]
	v_mfma_f32_16x16x32_bf16 v[70:73], v[146:149], v[214:217], v[70:73]
	s_setprio 0
	s_setprio 1
	v_mfma_f32_16x16x32_bf16 v[34:37], v[150:153], v[186:189], v[34:37]
	v_mfma_f32_16x16x32_bf16 v[30:33], v[158:161], v[186:189], v[30:33]
	v_mfma_f32_16x16x32_bf16 v[26:29], v[150:153], v[194:197], v[26:29]
	v_mfma_f32_16x16x32_bf16 v[22:25], v[158:161], v[194:197], v[22:25]
	v_mfma_f32_16x16x32_bf16 v[18:21], v[150:153], v[202:205], v[18:21]
	v_mfma_f32_16x16x32_bf16 v[14:17], v[158:161], v[202:205], v[14:17]
	v_mfma_f32_16x16x32_bf16 v[8:11], v[150:153], v[210:213], v[10:13]
	v_mfma_f32_16x16x32_bf16 v[4:7], v[158:161], v[210:213], v[4:7]
	v_mfma_f32_16x16x32_bf16 v[34:37], v[154:157], v[190:193], v[34:37]
	v_mfma_f32_16x16x32_bf16 v[30:33], v[162:165], v[190:193], v[30:33]
	v_mfma_f32_16x16x32_bf16 v[26:29], v[154:157], v[198:201], v[26:29]
	v_mfma_f32_16x16x32_bf16 v[22:25], v[162:165], v[198:201], v[22:25]
	v_mfma_f32_16x16x32_bf16 v[18:21], v[154:157], v[206:209], v[18:21]
	v_mfma_f32_16x16x32_bf16 v[14:17], v[162:165], v[206:209], v[14:17]
	v_mfma_f32_16x16x32_bf16 v[10:13], v[154:157], v[214:217], v[8:11]
	v_mfma_f32_16x16x32_bf16 v[6:9], v[162:165], v[214:217], v[4:7]
	s_setprio 0
	s_barrier
	s_add_u32 s26, s26, 0x100
	s_addc_u32 s27, s27, 0
	s_cmp_ge_u32 s67, s66
	s_cbranch_scc0 .LBB0_783
	s_cmpk_gt_u32 s65, 0x7f
	s_cbranch_scc1 .LBB0_787
	s_lshr_b32 s26, s66, 4
	s_add_i32 s26, s26, -1
	v_mov_b32_e32 v3, v1
	v_mov_b32_e32 v4, v220
	s_lshl_b32 s27, s26, 2
	s_add_i32 s28, s27, s48
	v_lshlrev_b32_e32 v5, 5, v3
	v_add_u32_e32 v126, s28, v5
	ds_read_b32 v126, v126
	s_add_i32 s28, s27, s49
	s_waitcnt lgkmcnt(0)
	v_pk_mul_f32 v[140:141], v[140:141], v[126:127] op_sel_hi:[1,0]
	v_pk_mul_f32 v[138:139], v[138:139], v[126:127] op_sel_hi:[1,0]
	v_pk_mul_f32 v[136:137], v[136:137], v[126:127] op_sel_hi:[1,0]
	v_pk_mul_f32 v[134:135], v[134:135], v[126:127] op_sel_hi:[1,0]
	v_pk_mul_f32 v[68:69], v[68:69], v[126:127] op_sel_hi:[1,0]
	v_pk_mul_f32 v[66:67], v[66:67], v[126:127] op_sel_hi:[1,0]
	v_pk_mul_f32 v[64:65], v[64:65], v[126:127] op_sel_hi:[1,0]
	v_pk_mul_f32 v[62:63], v[62:63], v[126:127] op_sel_hi:[1,0]
	v_add_u32_e32 v126, s28, v5
	ds_read_b32 v126, v126
	s_add_i32 s28, s27, s50
	s_waitcnt lgkmcnt(0)
	v_pk_mul_f32 v[124:125], v[124:125], v[126:127] op_sel_hi:[1,0]
	v_pk_mul_f32 v[122:123], v[122:123], v[126:127] op_sel_hi:[1,0]
	v_pk_mul_f32 v[120:121], v[120:121], v[126:127] op_sel_hi:[1,0]
	v_pk_mul_f32 v[118:119], v[118:119], v[126:127] op_sel_hi:[1,0]
	v_pk_mul_f32 v[60:61], v[60:61], v[126:127] op_sel_hi:[1,0]
	v_pk_mul_f32 v[58:59], v[58:59], v[126:127] op_sel_hi:[1,0]
	v_pk_mul_f32 v[56:57], v[56:57], v[126:127] op_sel_hi:[1,0]
	v_pk_mul_f32 v[54:55], v[54:55], v[126:127] op_sel_hi:[1,0]
	v_add_u32_e32 v126, s28, v5
	ds_read_b32 v126, v126
	s_add_i32 s28, s27, s51
	s_waitcnt lgkmcnt(0)
	v_pk_mul_f32 v[116:117], v[116:117], v[126:127] op_sel_hi:[1,0]
	v_pk_mul_f32 v[114:115], v[114:115], v[126:127] op_sel_hi:[1,0]
	v_pk_mul_f32 v[112:113], v[112:113], v[126:127] op_sel_hi:[1,0]
	v_pk_mul_f32 v[110:111], v[110:111], v[126:127] op_sel_hi:[1,0]
	v_pk_mul_f32 v[52:53], v[52:53], v[126:127] op_sel_hi:[1,0]
	v_pk_mul_f32 v[50:51], v[50:51], v[126:127] op_sel_hi:[1,0]
	v_pk_mul_f32 v[48:49], v[48:49], v[126:127] op_sel_hi:[1,0]
	v_pk_mul_f32 v[46:47], v[46:47], v[126:127] op_sel_hi:[1,0]
	v_add_u32_e32 v126, s28, v5
	ds_read_b32 v126, v126
	s_add_i32 s28, s27, s52
	s_waitcnt lgkmcnt(0)
;     __device__ __forceinline__ void after(int te, f32x4 (&acc)[2][2][4][2], const Unit& u, int wr, int wc, int fr, int fq) const {
;     ...
;             for (int m = 0; m < 4; ++m) { const float f = tab[(ai * HALF + wr * 64 + m * 16 + fr) * 8 + g];
; #pragma unroll
;                 for (int bj = 0; bj < 2; ++bj)
; #pragma unroll
;                     for (int n = 0; n < 2; ++n) acc[ai][bj][m][n] *= f; }
;         if (g == 7) {
;             const int row0 = u.pm * BM + wr * 64 + fr, col0 = u.pn * BM + wc * 32 + 8 * fq;
; #pragma unroll
;             for (int bj = 0; bj < 2; ++bj) { const int c = col0 + bj * HALF;
;                 const f32x4 s0 = *(const f32x4*)(gb + c), s1 = *(const f32x4*)(gb + c + 4), a0 = *(const f32x4*)(gb + D_MODEL + c), a1 = *(const f32x4*)(gb + D_MODEL + c + 4);
; #pragma unroll
;                 for (int ai = 0; ai < 2; ++ai) {
;                     u32x4 gs[4], ga[4];
; #pragma unroll
;                     for (int m = 0; m < 4; ++m) { const size_t r = (size_t)(row0 + ai * HALF + m * 16); gs[m] = *(const u32x4*)(proj + r * LDP + PGS + c); ga[m] = *(const u32x4*)(proj + r * LDP + PGA + c); }
	v_pk_mul_f32 v[108:109], v[108:109], v[126:127] op_sel_hi:[1,0]
	v_pk_mul_f32 v[106:107], v[106:107], v[126:127] op_sel_hi:[1,0]
	v_pk_mul_f32 v[104:105], v[104:105], v[126:127] op_sel_hi:[1,0]
	v_pk_mul_f32 v[102:103], v[102:103], v[126:127] op_sel_hi:[1,0]
	v_pk_mul_f32 v[44:45], v[44:45], v[126:127] op_sel_hi:[1,0]
	v_pk_mul_f32 v[42:43], v[42:43], v[126:127] op_sel_hi:[1,0]
	v_pk_mul_f32 v[40:41], v[40:41], v[126:127] op_sel_hi:[1,0]
	v_pk_mul_f32 v[38:39], v[38:39], v[126:127] op_sel_hi:[1,0]
	v_add_u32_e32 v126, s28, v5
	ds_read_b32 v126, v126
	s_add_i32 s28, s27, s53
	s_waitcnt lgkmcnt(0)
	v_pk_mul_f32 v[100:101], v[100:101], v[126:127] op_sel_hi:[1,0]
	v_pk_mul_f32 v[98:99], v[98:99], v[126:127] op_sel_hi:[1,0]
	v_pk_mul_f32 v[96:97], v[96:97], v[126:127] op_sel_hi:[1,0]
	v_pk_mul_f32 v[94:95], v[94:95], v[126:127] op_sel_hi:[1,0]
	v_pk_mul_f32 v[36:37], v[36:37], v[126:127] op_sel_hi:[1,0]
	v_pk_mul_f32 v[34:35], v[34:35], v[126:127] op_sel_hi:[1,0]
	v_pk_mul_f32 v[32:33], v[32:33], v[126:127] op_sel_hi:[1,0]
	v_pk_mul_f32 v[30:31], v[30:31], v[126:127] op_sel_hi:[1,0]
	v_add_u32_e32 v126, s28, v5
	ds_read_b32 v126, v126
	s_add_i32 s28, s27, s54
	s_add_i32 s27, s27, s55
	s_cmp_lg_u32 s26, 7
	s_waitcnt lgkmcnt(0)
	v_pk_mul_f32 v[92:93], v[92:93], v[126:127] op_sel_hi:[1,0]
	v_pk_mul_f32 v[90:91], v[90:91], v[126:127] op_sel_hi:[1,0]
	v_pk_mul_f32 v[88:89], v[88:89], v[126:127] op_sel_hi:[1,0]
	v_pk_mul_f32 v[86:87], v[86:87], v[126:127] op_sel_hi:[1,0]
	v_pk_mul_f32 v[28:29], v[28:29], v[126:127] op_sel_hi:[1,0]
	v_pk_mul_f32 v[26:27], v[26:27], v[126:127] op_sel_hi:[1,0]
	v_pk_mul_f32 v[24:25], v[24:25], v[126:127] op_sel_hi:[1,0]
	v_pk_mul_f32 v[22:23], v[22:23], v[126:127] op_sel_hi:[1,0]
	v_add_u32_e32 v126, s28, v5
	ds_read_b32 v126, v126
	v_add_u32_e32 v5, s27, v5
	s_waitcnt lgkmcnt(0)
	v_pk_mul_f32 v[84:85], v[84:85], v[126:127] op_sel_hi:[1,0]
	v_pk_mul_f32 v[82:83], v[82:83], v[126:127] op_sel_hi:[1,0]
	v_pk_mul_f32 v[80:81], v[80:81], v[126:127] op_sel_hi:[1,0]
	v_pk_mul_f32 v[78:79], v[78:79], v[126:127] op_sel_hi:[1,0]
	v_pk_mul_f32 v[20:21], v[20:21], v[126:127] op_sel_hi:[1,0]
	v_pk_mul_f32 v[18:19], v[18:19], v[126:127] op_sel_hi:[1,0]
	v_pk_mul_f32 v[16:17], v[16:17], v[126:127] op_sel_hi:[1,0]
	v_pk_mul_f32 v[14:15], v[14:15], v[126:127] op_sel_hi:[1,0]
	ds_read_b32 v126, v5
	s_waitcnt lgkmcnt(0)
	v_pk_mul_f32 v[76:77], v[76:77], v[126:127] op_sel_hi:[1,0]
	v_pk_mul_f32 v[74:75], v[74:75], v[126:127] op_sel_hi:[1,0]
	v_pk_mul_f32 v[72:73], v[72:73], v[126:127] op_sel_hi:[1,0]
	v_pk_mul_f32 v[70:71], v[70:71], v[126:127] op_sel_hi:[1,0]
	v_pk_mul_f32 v[12:13], v[12:13], v[126:127] op_sel_hi:[1,0]
	v_pk_mul_f32 v[10:11], v[10:11], v[126:127] op_sel_hi:[1,0]
	v_pk_mul_f32 v[8:9], v[8:9], v[126:127] op_sel_hi:[1,0]
	v_pk_mul_f32 v[6:7], v[6:7], v[126:127] op_sel_hi:[1,0]
	s_cbranch_scc1 .LBB0_787
	v_add_u32_e32 v126, s62, v3
	v_ashrrev_i32_e32 v127, 31, v126
	v_lshl_add_u32 v4, v4, 3, s61
	v_lshlrev_b64 v[126:127], 14, v[126:127]
	v_ashrrev_i32_e32 v5, 31, v4
	v_lshl_add_u64 v[126:127], s[76:77], 0, v[126:127]
	v_lshl_add_u64 v[192:193], v[4:5], 1, v[126:127]
	v_readlane_b32 s68, v254, 20
	global_load_dwordx4 v[204:207], v[192:193], off
	v_add_co_u32_e32 v126, vcc, s41, v192
	v_lshlrev_b64 v[4:5], 2, v[4:5]
	v_readlane_b32 s70, v254, 22
	v_readlane_b32 s71, v254, 23
	v_addc_co_u32_e32 v127, vcc, 0, v193, vcc
	s_nop 0
	v_lshl_add_u64 v[196:197], s[70:71], 0, v[4:5]
	global_load_dwordx4 v[208:211], v[126:127], off
	global_load_dwordx4 v[142:145], v[196:197], off
	s_nop 0
	global_load_dwordx4 v[126:129], v[196:197], off offset:16
	v_lshl_add_u64 v[198:199], s[12:13], 0, v[4:5]
	global_load_dwordx4 v[146:149], v[198:199], off
	global_load_dwordx4 v[130:133], v[198:199], off offset:16
	s_mov_b64 s[26:27], 0x40000
	v_lshl_add_u64 v[4:5], v[192:193], 0, s[26:27]
	s_mov_b32 s26, 0x40000
	v_add_co_u32_e32 v150, vcc, s26, v192
	s_mov_b64 s[26:27], 0x42000
	s_nop 0
	v_addc_co_u32_e32 v151, vcc, 0, v193, vcc
	v_lshl_add_u64 v[186:187], v[192:193], 0, s[26:27]
	s_mov_b32 s26, 0x42000
	v_add_co_u32_e32 v152, vcc, s26, v192
	s_mov_b64 s[26:27], 0x80000
	s_nop 0
	v_addc_co_u32_e32 v153, vcc, 0, v193, vcc
	v_lshl_add_u64 v[188:189], v[192:193], 0, s[26:27]
	s_mov_b32 s26, 0x80000
	v_add_co_u32_e32 v154, vcc, s26, v192
	s_mov_b64 s[26:27], 0x82000
	s_nop 0
	v_addc_co_u32_e32 v155, vcc, 0, v193, vcc
	v_lshl_add_u64 v[190:191], v[192:193], 0, s[26:27]
	s_mov_b32 s26, 0x82000
	v_add_co_u32_e32 v156, vcc, s26, v192
	s_mov_b64 s[26:27], 0xc0000
	s_nop 0
	v_addc_co_u32_e32 v157, vcc, 0, v193, vcc
	v_lshl_add_u64 v[194:195], v[192:193], 0, s[26:27]
	s_mov_b32 s26, 0xc0000
	v_add_co_u32_e32 v228, vcc, s26, v192
	s_mov_b64 s[26:27], 0xc2000
	s_nop 0
	v_addc_co_u32_e32 v229, vcc, 0, v193, vcc
	v_lshl_add_u64 v[200:201], v[192:193], 0, s[26:27]
	s_mov_b32 s26, 0xc2000
	v_add_co_u32_e32 v230, vcc, s26, v192
	s_mov_b32 s26, 0x200000
	s_nop 0
	v_addc_co_u32_e32 v231, vcc, 0, v193, vcc
	global_load_dwordx4 v[212:215], v[150:151], off
	global_load_dwordx4 v[216:219], v[152:153], off
	global_load_dwordx4 v[162:165], v[154:155], off
	global_load_dwordx4 v[158:161], v[156:157], off
	s_nop 0
	global_load_dwordx4 v[154:157], v[228:229], off
	global_load_dwordx4 v[150:153], v[230:231], off
	v_lshl_add_u64 v[202:203], v[192:193], 0, s[18:19]
	v_readlane_b32 s76, v254, 28
	v_readlane_b32 s77, v254, 29
	v_readlane_b32 s76, v255, 8
	v_readlane_b32 s77, v255, 9
	v_readlane_b32 s69, v254, 21
	v_readlane_b32 s72, v254, 24
	v_readlane_b32 s73, v254, 25
	v_readlane_b32 s74, v254, 26
	v_readlane_b32 s75, v254, 27
	v_readlane_b32 s78, v254, 30
	v_readlane_b32 s79, v254, 31
	v_readlane_b32 s80, v254, 32
	v_readlane_b32 s81, v254, 33
	v_readlane_b32 s82, v254, 34
	v_readlane_b32 s83, v254, 35
	s_waitcnt vmcnt(0)
; __device__ __forceinline__ void unpack8(const u32x4 w, float (&v)[8]) { v[0] = bf_lo(w.x); v[1] = bf_hi(w.x); v[2] = bf_lo(w.y); v[3] = bf_hi(w.y); v[4] = bf_lo(w.z); v[5] = bf_hi(w.z); v[6] = bf_lo(w.w); v[7] = bf_hi(w.w); }
;     __device__ __forceinline__ void after(int te, f32x4 (&acc)[2][2][4][2], const Unit& u, int wr, int wc, int fr, int fq) const {
;     ...
;                     for (int m = 0; m < 4; ++m) { float vs[8], va[8]; unpack8(gs[m], vs); unpack8(ga[m], va);
; #pragma unroll
;                         for (int e = 0; e < 4; ++e) {
;                             acc[ai][bj][m][0][e] *= (1.f + __expf(-(va[e] + a0[e]))) * __builtin_amdgcn_rcpf(1.f + __expf(-(vs[e] + s0[e])));
;                             acc[ai][bj][m][1][e] *= (1.f + __expf(-(va[4 + e] + a1[e]))) * __builtin_amdgcn_rcpf(1.f + __expf(-(vs[4 + e] + s1[e]))); } }
	v_lshlrev_b32_e32 v3, 16, v204
	v_and_b32_e32 v204, 0xffff0000, v204
	v_lshlrev_b32_e32 v225, 16, v205
	v_and_b32_e32 v227, 0xffff0000, v205
	v_lshlrev_b32_e32 v205, 16, v206
	v_and_b32_e32 v228, 0xffff0000, v206
	v_lshlrev_b32_e32 v229, 16, v207
	v_and_b32_e32 v233, 0xffff0000, v207
	v_add_f32_e32 v3, v142, v3
	v_add_f32_e32 v204, v143, v204
	v_mul_f32_e32 v3, 0xbfb8aa3b, v3
	v_mul_f32_e32 v204, 0xbfb8aa3b, v204
	v_exp_f32_e32 v3, v3
	v_lshlrev_b32_e32 v230, 16, v209
	v_and_b32_e32 v231, 0xffff0000, v209
	v_exp_f32_e32 v209, v204
	v_lshlrev_b32_e32 v206, 16, v208
	v_and_b32_e32 v207, 0xffff0000, v208
	v_lshlrev_b32_e32 v208, 16, v210
	v_add_f32_e32 v206, v146, v206
	v_add_f32_e32 v208, v130, v208
	v_mul_f32_e32 v206, 0xbfb8aa3b, v206
	v_mul_f32_e32 v208, 0xbfb8aa3b, v208
	v_add_f32_e32 v3, 1.0, v3
	v_exp_f32_e32 v204, v206
	v_exp_f32_e32 v206, v208
	v_rcp_f32_e32 v208, v3
	v_add_f32_e32 v3, 1.0, v209
	v_rcp_f32_e32 v209, v3
	v_add_f32_e32 v3, v127, v228
	v_mul_f32_e32 v3, 0xbfb8aa3b, v3
	v_exp_f32_e32 v3, v3
	v_lshlrev_b32_e32 v234, 16, v211
	v_and_b32_e32 v235, 0xffff0000, v211
	v_add_f32_e32 v205, v126, v205
	v_add_f32_e32 v3, 1.0, v3
	v_rcp_f32_e32 v211, v3
	v_add_f32_e32 v3, v144, v225
	v_mul_f32_e32 v3, 0xbfb8aa3b, v3
	v_exp_f32_e32 v3, v3
	v_mul_f32_e32 v205, 0xbfb8aa3b, v205
	v_exp_f32_e32 v205, v205
	v_add_f32_e32 v225, v148, v230
	v_add_f32_e32 v3, 1.0, v3
	v_rcp_f32_e32 v230, v3
	v_add_f32_e32 v3, v128, v229
	v_mul_f32_e32 v3, 0xbfb8aa3b, v3
	v_add_f32_e32 v227, v145, v227
	v_mul_f32_e32 v225, 0xbfb8aa3b, v225
	v_exp_f32_e32 v3, v3
	v_mul_f32_e32 v227, 0xbfb8aa3b, v227
	v_add_f32_e32 v207, v147, v207
	v_exp_f32_e32 v228, v225
	v_add_f32_e32 v225, v132, v234
	v_exp_f32_e32 v227, v227
	v_and_b32_e32 v232, 0xffff0000, v210
	v_mul_f32_e32 v207, 0xbfb8aa3b, v207
	v_add_f32_e32 v205, 1.0, v205
	v_mul_f32_e32 v225, 0xbfb8aa3b, v225
	v_rcp_f32_e32 v210, v205
	v_exp_f32_e32 v205, v207
	v_add_f32_e32 v207, v131, v232
	v_exp_f32_e32 v232, v225
	v_add_f32_e32 v225, v149, v231
	v_add_f32_e32 v3, 1.0, v3
	v_mul_f32_e32 v225, 0xbfb8aa3b, v225
	v_exp_f32_e32 v229, v225
	v_rcp_f32_e32 v234, v3
	v_add_f32_e32 v3, 1.0, v227
	v_rcp_f32_e32 v231, v3
	v_pk_add_f32 v[228:229], v[228:229], 1.0 op_sel_hi:[1,0]
	v_pk_add_f32 v[204:205], v[204:205], 1.0 op_sel_hi:[1,0]
	v_add_f32_e32 v3, v133, v235
	v_pk_mul_f32 v[204:205], v[204:205], v[208:209]
	v_pk_mul_f32 v[208:209], v[228:229], v[230:231]
	v_mul_f32_e32 v3, 0xbfb8aa3b, v3
	v_pk_mul_f32 v[140:141], v[140:141], v[208:209]
	v_add_f32_e32 v208, v129, v233
	v_mul_f32_e32 v208, 0xbfb8aa3b, v208
	v_exp_f32_e32 v208, v208
	v_exp_f32_e32 v233, v3
	v_mul_f32_e32 v207, 0xbfb8aa3b, v207
	v_exp_f32_e32 v207, v207
	v_add_f32_e32 v3, 1.0, v208
	v_rcp_f32_e32 v235, v3
	v_lshlrev_b32_e32 v3, 16, v212
	v_add_f32_e32 v3, v142, v3
	v_mul_f32_e32 v3, 0xbfb8aa3b, v3
	v_exp_f32_e32 v3, v3
	v_pk_add_f32 v[206:207], v[206:207], 1.0 op_sel_hi:[1,0]
	v_pk_mul_f32 v[138:139], v[138:139], v[204:205]
	v_pk_mul_f32 v[206:207], v[206:207], v[210:211]
	v_add_f32_e32 v3, 1.0, v3
	v_pk_mul_f32 v[134:135], v[134:135], v[206:207]
	v_lshlrev_b32_e32 v207, 16, v214
	v_rcp_f32_e32 v206, v3
	v_add_f32_e32 v3, v126, v207
	v_mul_f32_e32 v3, 0xbfb8aa3b, v3
	v_exp_f32_e32 v3, v3
	v_pk_add_f32 v[204:205], v[232:233], 1.0 op_sel_hi:[1,0]
	v_lshlrev_b32_e32 v208, 16, v218
	v_pk_mul_f32 v[204:205], v[204:205], v[234:235]
	v_add_f32_e32 v3, 1.0, v3
	v_pk_mul_f32 v[136:137], v[136:137], v[204:205]
	v_and_b32_e32 v205, 0xffff0000, v212
	v_rcp_f32_e32 v210, v3
	v_add_f32_e32 v3, v143, v205
	v_mul_f32_e32 v3, 0xbfb8aa3b, v3
	v_exp_f32_e32 v3, v3
	v_add_f32_e32 v207, v130, v208
	v_and_b32_e32 v209, 0xffff0000, v214
	v_mul_f32_e32 v207, 0xbfb8aa3b, v207
	v_add_f32_e32 v3, 1.0, v3
	v_exp_f32_e32 v208, v207
	v_rcp_f32_e32 v207, v3
	v_add_f32_e32 v3, v127, v209
	v_mul_f32_e32 v3, 0xbfb8aa3b, v3
	v_exp_f32_e32 v3, v3
	v_lshlrev_b32_e32 v212, 16, v213
	v_and_b32_e32 v211, 0xffff0000, v216
	v_add_f32_e32 v205, v147, v211
	v_add_f32_e32 v3, 1.0, v3
	v_rcp_f32_e32 v211, v3
	v_add_f32_e32 v3, v144, v212
	v_mul_f32_e32 v3, 0xbfb8aa3b, v3
	v_exp_f32_e32 v3, v3
	v_lshlrev_b32_e32 v225, 16, v215
	v_lshlrev_b32_e32 v214, 16, v217
	v_and_b32_e32 v213, 0xffff0000, v213
	v_add_f32_e32 v3, 1.0, v3
	v_add_f32_e32 v212, v148, v214
	v_rcp_f32_e32 v214, v3
	v_add_f32_e32 v3, v128, v225
	v_mul_f32_e32 v3, 0xbfb8aa3b, v3
	v_add_f32_e32 v213, v145, v213
	v_and_b32_e32 v227, 0xffff0000, v215
	v_lshlrev_b32_e32 v204, 16, v216
	v_and_b32_e32 v215, 0xffff0000, v217
	v_and_b32_e32 v216, 0xffff0000, v218
	v_lshlrev_b32_e32 v217, 16, v219
	v_exp_f32_e32 v3, v3
	v_mul_f32_e32 v213, 0xbfb8aa3b, v213
	v_add_f32_e32 v209, v131, v216
	v_add_f32_e32 v216, v132, v217
	v_exp_f32_e32 v217, v213
	v_add_f32_e32 v204, v146, v204
	v_add_f32_e32 v215, v149, v215
	v_mul_f32_e32 v204, 0xbfb8aa3b, v204
	v_mul_f32_e32 v205, 0xbfb8aa3b, v205
	v_mul_f32_e32 v212, 0xbfb8aa3b, v212
	v_add_f32_e32 v3, 1.0, v3
	v_mul_f32_e32 v213, 0xbfb8aa3b, v215
	v_exp_f32_e32 v204, v204
	v_exp_f32_e32 v205, v205
	v_exp_f32_e32 v212, v212
	v_exp_f32_e32 v213, v213
	v_rcp_f32_e32 v218, v3
	v_add_f32_e32 v3, 1.0, v217
	v_rcp_f32_e32 v215, v3
	v_pk_add_f32 v[212:213], v[212:213], 1.0 op_sel_hi:[1,0]
	v_pk_add_f32 v[204:205], v[204:205], 1.0 op_sel_hi:[1,0]
	v_and_b32_e32 v219, 0xffff0000, v219
	v_pk_mul_f32 v[204:205], v[204:205], v[206:207]
	v_pk_mul_f32 v[206:207], v[212:213], v[214:215]
	v_add_f32_e32 v3, v133, v219
	v_pk_mul_f32 v[124:125], v[124:125], v[206:207]
	v_add_f32_e32 v206, v129, v227
	v_mul_f32_e32 v206, 0xbfb8aa3b, v206
	v_exp_f32_e32 v206, v206
	v_mul_f32_e32 v3, 0xbfb8aa3b, v3
	v_exp_f32_e32 v217, v3
; __device__ __forceinline__ void unpack8(const u32x4 w, float (&v)[8]) { v[0] = bf_lo(w.x); v[1] = bf_hi(w.x); v[2] = bf_lo(w.y); v[3] = bf_hi(w.y); v[4] = bf_lo(w.z); v[5] = bf_hi(w.z); v[6] = bf_lo(w.w); v[7] = bf_hi(w.w); }
;     __device__ __forceinline__ void after(int te, f32x4 (&acc)[2][2][4][2], const Unit& u, int wr, int wc, int fr, int fq) const {
;     ...
;                     for (int m = 0; m < 4; ++m) { float vs[8], va[8]; unpack8(gs[m], vs); unpack8(ga[m], va);
; #pragma unroll
;                         for (int e = 0; e < 4; ++e) {
;                             acc[ai][bj][m][0][e] *= (1.f + __expf(-(va[e] + a0[e]))) * __builtin_amdgcn_rcpf(1.f + __expf(-(vs[e] + s0[e])));
;                             acc[ai][bj][m][1][e] *= (1.f + __expf(-(va[4 + e] + a1[e]))) * __builtin_amdgcn_rcpf(1.f + __expf(-(vs[4 + e] + s1[e]))); } }
	v_mul_f32_e32 v216, 0xbfb8aa3b, v216
	v_add_f32_e32 v3, 1.0, v206
	v_rcp_f32_e32 v219, v3
	v_lshlrev_b32_e32 v3, 16, v162
	v_mul_f32_e32 v209, 0xbfb8aa3b, v209
	v_exp_f32_e32 v216, v216
	v_add_f32_e32 v3, v142, v3
	v_exp_f32_e32 v209, v209
	v_mul_f32_e32 v3, 0xbfb8aa3b, v3
	v_exp_f32_e32 v3, v3
	v_pk_mul_f32 v[122:123], v[122:123], v[204:205]
	v_pk_add_f32 v[204:205], v[216:217], 1.0 op_sel_hi:[1,0]
	v_pk_add_f32 v[206:207], v[208:209], 1.0 op_sel_hi:[1,0]
	v_pk_mul_f32 v[204:205], v[204:205], v[218:219]
	v_pk_mul_f32 v[206:207], v[206:207], v[210:211]
	v_pk_mul_f32 v[120:121], v[120:121], v[204:205]
	v_and_b32_e32 v204, 0xffff0000, v162
	v_lshlrev_b32_e32 v162, 16, v164
	v_add_f32_e32 v3, 1.0, v3
	v_pk_mul_f32 v[118:119], v[118:119], v[206:207]
	v_lshlrev_b32_e32 v206, 16, v159
	v_and_b32_e32 v210, 0xffff0000, v159
	v_lshlrev_b32_e32 v159, 16, v160
	v_and_b32_e32 v211, 0xffff0000, v160
	v_rcp_f32_e32 v160, v3
	v_add_f32_e32 v3, v126, v162
	v_mul_f32_e32 v3, 0xbfb8aa3b, v3
	v_exp_f32_e32 v3, v3
	v_lshlrev_b32_e32 v205, 16, v163
	v_and_b32_e32 v207, 0xffff0000, v163
	v_and_b32_e32 v163, 0xffff0000, v164
	v_lshlrev_b32_e32 v164, 16, v158
	v_add_f32_e32 v3, 1.0, v3
	v_lshlrev_b32_e32 v208, 16, v165
	v_and_b32_e32 v209, 0xffff0000, v165
	v_and_b32_e32 v165, 0xffff0000, v158
	v_add_f32_e32 v158, v146, v164
	v_rcp_f32_e32 v164, v3
	v_add_f32_e32 v3, v143, v204
	v_mul_f32_e32 v3, 0xbfb8aa3b, v3
	v_exp_f32_e32 v3, v3
	v_lshlrev_b32_e32 v212, 16, v161
	v_and_b32_e32 v213, 0xffff0000, v161
	v_add_f32_e32 v159, v130, v159
	v_add_f32_e32 v3, 1.0, v3
	v_rcp_f32_e32 v161, v3
	v_add_f32_e32 v3, v127, v163
	v_mul_f32_e32 v3, 0xbfb8aa3b, v3
	v_exp_f32_e32 v3, v3
	v_mul_f32_e32 v159, 0xbfb8aa3b, v159
	v_exp_f32_e32 v162, v159
	v_add_f32_e32 v159, v147, v165
	v_add_f32_e32 v3, 1.0, v3
	v_rcp_f32_e32 v165, v3
	v_add_f32_e32 v3, v144, v205
	v_mul_f32_e32 v3, 0xbfb8aa3b, v3
	v_exp_f32_e32 v3, v3
	v_add_f32_e32 v204, v148, v206
	v_add_f32_e32 v207, v145, v207
	v_mul_f32_e32 v207, 0xbfb8aa3b, v207
	v_add_f32_e32 v3, 1.0, v3
	v_rcp_f32_e32 v206, v3
	v_add_f32_e32 v3, v128, v208
	v_mul_f32_e32 v3, 0xbfb8aa3b, v3
	v_exp_f32_e32 v3, v3
	v_add_f32_e32 v205, v132, v212
	v_exp_f32_e32 v207, v207
	v_mul_f32_e32 v205, 0xbfb8aa3b, v205
	v_exp_f32_e32 v208, v205
	v_add_f32_e32 v205, v149, v210
	v_mul_f32_e32 v158, 0xbfb8aa3b, v158
	v_mul_f32_e32 v159, 0xbfb8aa3b, v159
	v_mul_f32_e32 v204, 0xbfb8aa3b, v204
	v_add_f32_e32 v3, 1.0, v3
	v_mul_f32_e32 v205, 0xbfb8aa3b, v205
	v_exp_f32_e32 v158, v158
	v_exp_f32_e32 v159, v159
	v_exp_f32_e32 v204, v204
	v_exp_f32_e32 v205, v205
	v_rcp_f32_e32 v210, v3
	v_add_f32_e32 v3, 1.0, v207
	v_rcp_f32_e32 v207, v3
	v_pk_add_f32 v[204:205], v[204:205], 1.0 op_sel_hi:[1,0]
	v_pk_add_f32 v[158:159], v[158:159], 1.0 op_sel_hi:[1,0]
	v_add_f32_e32 v3, v133, v213
	v_pk_mul_f32 v[158:159], v[158:159], v[160:161]
	v_pk_mul_f32 v[160:161], v[204:205], v[206:207]
	v_mul_f32_e32 v3, 0xbfb8aa3b, v3
	v_pk_mul_f32 v[116:117], v[116:117], v[160:161]
	v_add_f32_e32 v160, v129, v209
	v_mul_f32_e32 v160, 0xbfb8aa3b, v160
	v_exp_f32_e32 v160, v160
	v_exp_f32_e32 v209, v3
	v_add_f32_e32 v163, v131, v211
	v_mul_f32_e32 v163, 0xbfb8aa3b, v163
	v_add_f32_e32 v3, 1.0, v160
	v_rcp_f32_e32 v211, v3
	v_lshlrev_b32_e32 v3, 16, v154
	v_add_f32_e32 v3, v142, v3
	v_exp_f32_e32 v163, v163
	v_mul_f32_e32 v3, 0xbfb8aa3b, v3
	v_exp_f32_e32 v3, v3
	v_pk_mul_f32 v[114:115], v[114:115], v[158:159]
	v_pk_add_f32 v[158:159], v[208:209], 1.0 op_sel_hi:[1,0]
	v_pk_add_f32 v[160:161], v[162:163], 1.0 op_sel_hi:[1,0]
	v_pk_mul_f32 v[158:159], v[158:159], v[210:211]
	v_pk_mul_f32 v[160:161], v[160:161], v[164:165]
	v_pk_mul_f32 v[112:113], v[112:113], v[158:159]
	v_and_b32_e32 v158, 0xffff0000, v154
	v_lshlrev_b32_e32 v154, 16, v156
	v_add_f32_e32 v3, 1.0, v3
	v_pk_mul_f32 v[110:111], v[110:111], v[160:161]
	v_lshlrev_b32_e32 v160, 16, v151
	v_and_b32_e32 v204, 0xffff0000, v151
	v_lshlrev_b32_e32 v151, 16, v152
	v_and_b32_e32 v162, 0xffff0000, v152
	v_rcp_f32_e32 v152, v3
	v_add_f32_e32 v3, v126, v154
	v_mul_f32_e32 v3, 0xbfb8aa3b, v3
	v_exp_f32_e32 v3, v3
	v_lshlrev_b32_e32 v159, 16, v155
	v_and_b32_e32 v161, 0xffff0000, v155
	v_and_b32_e32 v155, 0xffff0000, v156
	v_lshlrev_b32_e32 v156, 16, v150
	v_add_f32_e32 v3, 1.0, v3
	v_lshlrev_b32_e32 v164, 16, v157
	v_and_b32_e32 v165, 0xffff0000, v157
	v_and_b32_e32 v157, 0xffff0000, v150
	v_add_f32_e32 v150, v146, v156
	v_rcp_f32_e32 v156, v3
	v_add_f32_e32 v3, v143, v158
	v_mul_f32_e32 v3, 0xbfb8aa3b, v3
	v_exp_f32_e32 v3, v3
	v_lshlrev_b32_e32 v205, 16, v153
	v_and_b32_e32 v206, 0xffff0000, v153
	v_add_f32_e32 v151, v130, v151
	v_add_f32_e32 v3, 1.0, v3
	v_rcp_f32_e32 v153, v3
	v_add_f32_e32 v3, v127, v155
	v_add_f32_e32 v155, v131, v162
	v_add_co_u32_e32 v162, vcc, s26, v192
	v_mul_f32_e32 v3, 0xbfb8aa3b, v3
	s_nop 0
	v_addc_co_u32_e32 v163, vcc, 0, v193, vcc
	global_load_dwordx4 v[228:231], v[162:163], off
	v_exp_f32_e32 v3, v3
	v_mul_f32_e32 v151, 0xbfb8aa3b, v151
	s_mov_b32 s26, 0x202000
	v_exp_f32_e32 v154, v151
	v_add_f32_e32 v3, 1.0, v3
	v_add_f32_e32 v151, v147, v157
	v_rcp_f32_e32 v157, v3
	v_add_f32_e32 v3, v144, v159
	v_add_co_u32_e32 v162, vcc, s26, v192
	v_mul_f32_e32 v3, 0xbfb8aa3b, v3
	s_nop 0
	v_addc_co_u32_e32 v163, vcc, 0, v193, vcc
	v_exp_f32_e32 v3, v3
	global_load_dwordx4 v[232:235], v[162:163], off
	v_add_f32_e32 v158, v148, v160
	v_add_f32_e32 v161, v145, v161
	v_add_f32_e32 v3, 1.0, v3
	v_rcp_f32_e32 v160, v3
	v_add_f32_e32 v3, v128, v164
	v_mul_f32_e32 v3, 0xbfb8aa3b, v3
	v_exp_f32_e32 v3, v3
	v_mul_f32_e32 v161, 0xbfb8aa3b, v161
	v_add_f32_e32 v159, v132, v205
	v_exp_f32_e32 v161, v161
	v_mul_f32_e32 v159, 0xbfb8aa3b, v159
; __device__ __forceinline__ void unpack8(const u32x4 w, float (&v)[8]) { v[0] = bf_lo(w.x); v[1] = bf_hi(w.x); v[2] = bf_lo(w.y); v[3] = bf_hi(w.y); v[4] = bf_lo(w.z); v[5] = bf_hi(w.z); v[6] = bf_lo(w.w); v[7] = bf_hi(w.w); }
;     __device__ __forceinline__ void after(int te, f32x4 (&acc)[2][2][4][2], const Unit& u, int wr, int wc, int fr, int fq) const {
;     ...
;                     for (int m = 0; m < 4; ++m) { const size_t r = (size_t)(row0 + ai * HALF + m * 16); gs[m] = *(const u32x4*)(proj + r * LDP + PGS + c); ga[m] = *(const u32x4*)(proj + r * LDP + PGA + c); }
; #pragma unroll
;                     for (int m = 0; m < 4; ++m) { float vs[8], va[8]; unpack8(gs[m], vs); unpack8(ga[m], va);
; #pragma unroll
;                         for (int e = 0; e < 4; ++e) {
;                             acc[ai][bj][m][0][e] *= (1.f + __expf(-(va[e] + a0[e]))) * __builtin_amdgcn_rcpf(1.f + __expf(-(vs[e] + s0[e])));
;                             acc[ai][bj][m][1][e] *= (1.f + __expf(-(va[4 + e] + a1[e]))) * __builtin_amdgcn_rcpf(1.f + __expf(-(vs[4 + e] + s1[e]))); } }
	v_exp_f32_e32 v162, v159
	v_add_f32_e32 v159, v149, v204
	v_mul_f32_e32 v150, 0xbfb8aa3b, v150
	v_mul_f32_e32 v151, 0xbfb8aa3b, v151
	v_mul_f32_e32 v158, 0xbfb8aa3b, v158
	v_add_f32_e32 v3, 1.0, v3
	v_mul_f32_e32 v159, 0xbfb8aa3b, v159
	v_exp_f32_e32 v150, v150
	v_exp_f32_e32 v151, v151
	v_exp_f32_e32 v158, v158
	v_exp_f32_e32 v159, v159
	v_rcp_f32_e32 v164, v3
	v_add_f32_e32 v3, 1.0, v161
	v_rcp_f32_e32 v161, v3
	v_pk_add_f32 v[158:159], v[158:159], 1.0 op_sel_hi:[1,0]
	v_pk_add_f32 v[150:151], v[150:151], 1.0 op_sel_hi:[1,0]
	v_add_f32_e32 v3, v133, v206
	v_pk_mul_f32 v[150:151], v[150:151], v[152:153]
	v_pk_mul_f32 v[152:153], v[158:159], v[160:161]
	v_mul_f32_e32 v3, 0xbfb8aa3b, v3
	v_pk_mul_f32 v[108:109], v[108:109], v[152:153]
	v_add_f32_e32 v152, v129, v165
	v_mul_f32_e32 v152, 0xbfb8aa3b, v152
	v_exp_f32_e32 v152, v152
	v_exp_f32_e32 v163, v3
	v_mul_f32_e32 v155, 0xbfb8aa3b, v155
	v_exp_f32_e32 v155, v155
	v_add_f32_e32 v3, 1.0, v152
	v_rcp_f32_e32 v165, v3
	s_mov_b64 s[26:27], 0x200000
	v_lshl_add_u64 v[218:219], v[192:193], 0, s[26:27]
	s_mov_b64 s[26:27], 0x202000
	v_pk_mul_f32 v[106:107], v[106:107], v[150:151]
	v_pk_add_f32 v[150:151], v[162:163], 1.0 op_sel_hi:[1,0]
	v_lshl_add_u64 v[216:217], v[192:193], 0, s[26:27]
	s_mov_b64 s[26:27], 0x240000
	v_pk_mul_f32 v[150:151], v[150:151], v[164:165]
	v_lshl_add_u64 v[204:205], v[192:193], 0, s[26:27]
	s_mov_b32 s26, 0x240000
	v_pk_add_f32 v[152:153], v[154:155], 1.0 op_sel_hi:[1,0]
	v_pk_mul_f32 v[104:105], v[104:105], v[150:151]
	v_add_co_u32_e32 v150, vcc, s26, v192
	s_mov_b64 s[26:27], 0x242000
	v_pk_mul_f32 v[152:153], v[152:153], v[156:157]
	v_addc_co_u32_e32 v151, vcc, 0, v193, vcc
	v_lshl_add_u64 v[206:207], v[192:193], 0, s[26:27]
	s_mov_b32 s26, 0x242000
	v_pk_mul_f32 v[102:103], v[102:103], v[152:153]
	v_add_co_u32_e32 v152, vcc, s26, v192
	s_mov_b64 s[26:27], 0x280000
	s_nop 0
	v_addc_co_u32_e32 v153, vcc, 0, v193, vcc
	global_load_dwordx4 v[236:239], v[150:151], off
	global_load_dwordx4 v[240:243], v[152:153], off
	s_waitcnt vmcnt(3)
	v_lshlrev_b32_e32 v3, 16, v228
	v_add_f32_e32 v3, v142, v3
	v_mul_f32_e32 v3, 0xbfb8aa3b, v3
	v_exp_f32_e32 v3, v3
	v_lshlrev_b32_e32 v227, 16, v229
	v_and_b32_e32 v245, 0xffff0000, v229
	v_lshlrev_b32_e32 v229, 16, v230
	v_add_f32_e32 v3, 1.0, v3
	v_and_b32_e32 v246, 0xffff0000, v230
	v_rcp_f32_e32 v230, v3
	v_add_f32_e32 v3, v126, v229
	v_mul_f32_e32 v3, 0xbfb8aa3b, v3
	v_exp_f32_e32 v3, v3
	v_lshl_add_u64 v[208:209], v[192:193], 0, s[26:27]
	s_mov_b32 s26, 0x280000
	v_add_co_u32_e32 v150, vcc, s26, v192
	s_mov_b64 s[26:27], 0x282000
	s_nop 0
	v_addc_co_u32_e32 v151, vcc, 0, v193, vcc
	v_lshl_add_u64 v[210:211], v[192:193], 0, s[26:27]
	s_mov_b32 s26, 0x282000
	v_add_co_u32_e32 v152, vcc, s26, v192
	v_and_b32_e32 v225, 0xffff0000, v228
	v_add_f32_e32 v3, 1.0, v3
	v_addc_co_u32_e32 v153, vcc, 0, v193, vcc
	global_load_dwordx4 v[162:165], v[150:151], off
	global_load_dwordx4 v[158:161], v[152:153], off
	v_lshlrev_b32_e32 v247, 16, v231
	v_and_b32_e32 v251, 0xffff0000, v231
	s_waitcnt vmcnt(4)
	v_lshlrev_b32_e32 v228, 16, v232
	v_and_b32_e32 v231, 0xffff0000, v232
	v_lshlrev_b32_e32 v248, 16, v233
	v_and_b32_e32 v249, 0xffff0000, v233
	v_lshlrev_b32_e32 v232, 16, v234
	v_and_b32_e32 v233, 0xffff0000, v234
	v_rcp_f32_e32 v234, v3
	v_add_f32_e32 v3, v143, v225
	v_mul_f32_e32 v3, 0xbfb8aa3b, v3
	v_exp_f32_e32 v3, v3
	v_add_f32_e32 v225, v147, v231
	v_lshlrev_b32_e32 v250, 16, v235
	v_and_b32_e32 v253, 0xffff0000, v235
	v_add_f32_e32 v3, 1.0, v3
	v_rcp_f32_e32 v231, v3
	v_add_f32_e32 v3, v127, v246
	v_mul_f32_e32 v3, 0xbfb8aa3b, v3
	v_exp_f32_e32 v3, v3
	v_add_f32_e32 v229, v130, v232
	v_mul_f32_e32 v229, 0xbfb8aa3b, v229
	v_mul_f32_e32 v225, 0xbfb8aa3b, v225
	v_add_f32_e32 v3, 1.0, v3
	v_rcp_f32_e32 v235, v3
	v_add_f32_e32 v3, v144, v227
	v_mul_f32_e32 v3, 0xbfb8aa3b, v3
	v_exp_f32_e32 v3, v3
	v_exp_f32_e32 v232, v229
	v_exp_f32_e32 v229, v225
	v_add_f32_e32 v225, v131, v233
	v_mul_f32_e32 v225, 0xbfb8aa3b, v225
	v_exp_f32_e32 v233, v225
	v_add_f32_e32 v225, v148, v248
	v_mul_f32_e32 v225, 0xbfb8aa3b, v225
	v_add_f32_e32 v3, 1.0, v3
	v_exp_f32_e32 v246, v225
	v_rcp_f32_e32 v248, v3
	v_add_f32_e32 v3, v128, v247
	v_add_f32_e32 v225, v132, v250
	v_mul_f32_e32 v3, 0xbfb8aa3b, v3
	v_mul_f32_e32 v225, 0xbfb8aa3b, v225
	v_add_f32_e32 v227, v145, v245
	v_exp_f32_e32 v3, v3
	v_exp_f32_e32 v250, v225
	v_add_f32_e32 v225, v149, v249
	v_mul_f32_e32 v227, 0xbfb8aa3b, v227
	v_exp_f32_e32 v227, v227
	v_mul_f32_e32 v225, 0xbfb8aa3b, v225
	v_exp_f32_e32 v247, v225
	v_add_f32_e32 v225, v129, v251
	v_mul_f32_e32 v225, 0xbfb8aa3b, v225
	v_add_f32_e32 v3, 1.0, v3
	v_exp_f32_e32 v225, v225
	v_rcp_f32_e32 v252, v3
	v_add_f32_e32 v3, 1.0, v227
	v_add_f32_e32 v228, v146, v228
	v_rcp_f32_e32 v249, v3
	v_add_f32_e32 v3, v133, v253
	v_mul_f32_e32 v228, 0xbfb8aa3b, v228
	v_mul_f32_e32 v3, 0xbfb8aa3b, v3
	v_exp_f32_e32 v228, v228
	v_exp_f32_e32 v251, v3
	v_add_f32_e32 v3, 1.0, v225
	v_rcp_f32_e32 v253, v3
	s_waitcnt vmcnt(3)
; __device__ __forceinline__ void unpack8(const u32x4 w, float (&v)[8]) { v[0] = bf_lo(w.x); v[1] = bf_hi(w.x); v[2] = bf_lo(w.y); v[3] = bf_hi(w.y); v[4] = bf_lo(w.z); v[5] = bf_hi(w.z); v[6] = bf_lo(w.w); v[7] = bf_hi(w.w); }
;     __device__ __forceinline__ void after(int te, f32x4 (&acc)[2][2][4][2], const Unit& u, int wr, int wc, int fr, int fq) const {
;     ...
;                     for (int m = 0; m < 4; ++m) { const size_t r = (size_t)(row0 + ai * HALF + m * 16); gs[m] = *(const u32x4*)(proj + r * LDP + PGS + c); ga[m] = *(const u32x4*)(proj + r * LDP + PGA + c); }
; #pragma unroll
;                     for (int m = 0; m < 4; ++m) { float vs[8], va[8]; unpack8(gs[m], vs); unpack8(ga[m], va);
; #pragma unroll
;                         for (int e = 0; e < 4; ++e) {
;                             acc[ai][bj][m][0][e] *= (1.f + __expf(-(va[e] + a0[e]))) * __builtin_amdgcn_rcpf(1.f + __expf(-(vs[e] + s0[e])));
;                             acc[ai][bj][m][1][e] *= (1.f + __expf(-(va[4 + e] + a1[e]))) * __builtin_amdgcn_rcpf(1.f + __expf(-(vs[4 + e] + s1[e]))); } }
	v_lshlrev_b32_e32 v3, 16, v236
	v_add_f32_e32 v3, v142, v3
	v_mul_f32_e32 v3, 0xbfb8aa3b, v3
	v_pk_add_f32 v[228:229], v[228:229], 1.0 op_sel_hi:[1,0]
	v_exp_f32_e32 v3, v3
	v_pk_add_f32 v[246:247], v[246:247], 1.0 op_sel_hi:[1,0]
	v_pk_mul_f32 v[228:229], v[228:229], v[230:231]
	v_pk_mul_f32 v[230:231], v[246:247], v[248:249]
	v_pk_mul_f32 v[98:99], v[98:99], v[228:229]
	v_pk_add_f32 v[228:229], v[250:251], 1.0 op_sel_hi:[1,0]
	v_pk_mul_f32 v[100:101], v[100:101], v[230:231]
	v_pk_add_f32 v[230:231], v[232:233], 1.0 op_sel_hi:[1,0]
	v_pk_mul_f32 v[228:229], v[228:229], v[252:253]
	v_pk_mul_f32 v[230:231], v[230:231], v[234:235]
	v_pk_mul_f32 v[96:97], v[96:97], v[228:229]
	v_lshlrev_b32_e32 v229, 16, v238
	v_add_f32_e32 v3, 1.0, v3
	v_pk_mul_f32 v[94:95], v[94:95], v[230:231]
	v_rcp_f32_e32 v230, v3
	v_add_f32_e32 v3, v126, v229
	v_mul_f32_e32 v3, 0xbfb8aa3b, v3
	v_exp_f32_e32 v3, v3
	v_and_b32_e32 v225, 0xffff0000, v236
	s_mov_b64 s[26:27], 0x2c0000
	v_lshl_add_u64 v[212:213], v[192:193], 0, s[26:27]
	v_add_f32_e32 v3, 1.0, v3
	v_rcp_f32_e32 v234, v3
	v_add_f32_e32 v3, v143, v225
	v_mul_f32_e32 v3, 0xbfb8aa3b, v3
	v_exp_f32_e32 v3, v3
	s_mov_b32 s26, 0x2c0000
	v_add_co_u32_e32 v150, vcc, s26, v192
	s_mov_b64 s[26:27], 0x2c2000
	s_nop 0
	v_addc_co_u32_e32 v151, vcc, 0, v193, vcc
	v_lshl_add_u64 v[214:215], v[192:193], 0, s[26:27]
	s_mov_b32 s26, 0x2c2000
	v_and_b32_e32 v233, 0xffff0000, v238
	s_waitcnt vmcnt(2)
	v_and_b32_e32 v231, 0xffff0000, v240
	v_add_f32_e32 v3, 1.0, v3
	v_add_co_u32_e32 v152, vcc, s26, v192
	v_add_f32_e32 v225, v147, v231
	v_rcp_f32_e32 v231, v3
	v_add_f32_e32 v3, v127, v233
	v_addc_co_u32_e32 v153, vcc, 0, v193, vcc
	v_mul_f32_e32 v3, 0xbfb8aa3b, v3
	global_load_dwordx4 v[154:157], v[150:151], off
	s_nop 0
	global_load_dwordx4 v[150:153], v[152:153], off
	v_exp_f32_e32 v3, v3
	v_lshlrev_b32_e32 v232, 16, v242
	v_add_f32_e32 v229, v130, v232
	v_lshlrev_b32_e32 v227, 16, v237
	v_and_b32_e32 v235, 0xffff0000, v242
	v_mul_f32_e32 v229, 0xbfb8aa3b, v229
	v_mul_f32_e32 v225, 0xbfb8aa3b, v225
	v_add_f32_e32 v3, 1.0, v3
	v_exp_f32_e32 v232, v229
	v_exp_f32_e32 v229, v225
	v_add_f32_e32 v225, v131, v235
	v_rcp_f32_e32 v235, v3
	v_add_f32_e32 v3, v144, v227
	v_mul_f32_e32 v3, 0xbfb8aa3b, v3
	v_exp_f32_e32 v3, v3
	v_lshlrev_b32_e32 v236, 16, v241
	v_mul_f32_e32 v225, 0xbfb8aa3b, v225
	v_exp_f32_e32 v233, v225
	v_add_f32_e32 v225, v148, v236
	v_lshlrev_b32_e32 v245, 16, v239
	v_lshlrev_b32_e32 v228, 16, v240
	v_lshlrev_b32_e32 v240, 16, v243
	v_mul_f32_e32 v225, 0xbfb8aa3b, v225
	v_add_f32_e32 v3, 1.0, v3
	v_and_b32_e32 v237, 0xffff0000, v237
	v_exp_f32_e32 v236, v225
	v_rcp_f32_e32 v238, v3
	v_add_f32_e32 v3, v128, v245
	v_add_f32_e32 v225, v132, v240
	v_and_b32_e32 v246, 0xffff0000, v239
	v_and_b32_e32 v239, 0xffff0000, v241
	v_mul_f32_e32 v3, 0xbfb8aa3b, v3
	v_mul_f32_e32 v225, 0xbfb8aa3b, v225
	v_add_f32_e32 v227, v145, v237
	v_exp_f32_e32 v3, v3
	v_exp_f32_e32 v240, v225
	v_add_f32_e32 v225, v149, v239
	v_mul_f32_e32 v227, 0xbfb8aa3b, v227
	v_exp_f32_e32 v227, v227
	v_mul_f32_e32 v225, 0xbfb8aa3b, v225
	v_exp_f32_e32 v237, v225
	v_add_f32_e32 v225, v129, v246
	v_mul_f32_e32 v225, 0xbfb8aa3b, v225
	v_add_f32_e32 v3, 1.0, v3
	v_exp_f32_e32 v225, v225
	v_and_b32_e32 v241, 0xffff0000, v243
	v_rcp_f32_e32 v242, v3
	v_add_f32_e32 v3, 1.0, v227
	v_rcp_f32_e32 v239, v3
	v_add_f32_e32 v3, v133, v241
	v_add_f32_e32 v228, v146, v228
	v_mul_f32_e32 v3, 0xbfb8aa3b, v3
	v_mul_f32_e32 v228, 0xbfb8aa3b, v228
	v_exp_f32_e32 v241, v3
	v_add_f32_e32 v3, 1.0, v225
	v_exp_f32_e32 v228, v228
	v_rcp_f32_e32 v243, v3
	s_waitcnt vmcnt(3)
	v_lshlrev_b32_e32 v3, 16, v162
	v_add_f32_e32 v3, v142, v3
	v_mul_f32_e32 v3, 0xbfb8aa3b, v3
	v_exp_f32_e32 v3, v3
	v_pk_add_f32 v[236:237], v[236:237], 1.0 op_sel_hi:[1,0]
	v_pk_add_f32 v[228:229], v[228:229], 1.0 op_sel_hi:[1,0]
	v_and_b32_e32 v225, 0xffff0000, v162
	v_pk_mul_f32 v[228:229], v[228:229], v[230:231]
	v_pk_mul_f32 v[230:231], v[236:237], v[238:239]
	v_pk_mul_f32 v[90:91], v[90:91], v[228:229]
	v_pk_mul_f32 v[92:93], v[92:93], v[230:231]
	v_pk_add_f32 v[228:229], v[240:241], 1.0 op_sel_hi:[1,0]
	v_pk_add_f32 v[230:231], v[232:233], 1.0 op_sel_hi:[1,0]
	v_pk_mul_f32 v[228:229], v[228:229], v[242:243]
	v_pk_mul_f32 v[230:231], v[230:231], v[234:235]
	v_lshlrev_b32_e32 v162, 16, v164
	v_add_f32_e32 v3, 1.0, v3
	v_pk_mul_f32 v[88:89], v[88:89], v[228:229]
	v_pk_mul_f32 v[86:87], v[86:87], v[230:231]
	s_waitcnt vmcnt(2)
; __device__ __forceinline__ void unpack8(const u32x4 w, float (&v)[8]) { v[0] = bf_lo(w.x); v[1] = bf_hi(w.x); v[2] = bf_lo(w.y); v[3] = bf_hi(w.y); v[4] = bf_lo(w.z); v[5] = bf_hi(w.z); v[6] = bf_lo(w.w); v[7] = bf_hi(w.w); }
;     __device__ __forceinline__ void after(int te, f32x4 (&acc)[2][2][4][2], const Unit& u, int wr, int wc, int fr, int fq) const {
;     ...
;             for (int bj = 0; bj < 2; ++bj) { const int c = col0 + bj * HALF;
;                 const f32x4 s0 = *(const f32x4*)(gb + c), s1 = *(const f32x4*)(gb + c + 4), a0 = *(const f32x4*)(gb + D_MODEL + c), a1 = *(const f32x4*)(gb + D_MODEL + c + 4);
; #pragma unroll
;                 for (int ai = 0; ai < 2; ++ai) {
;                     u32x4 gs[4], ga[4];
; #pragma unroll
;                     for (int m = 0; m < 4; ++m) { const size_t r = (size_t)(row0 + ai * HALF + m * 16); gs[m] = *(const u32x4*)(proj + r * LDP + PGS + c); ga[m] = *(const u32x4*)(proj + r * LDP + PGA + c); }
; #pragma unroll
;                     for (int m = 0; m < 4; ++m) { float vs[8], va[8]; unpack8(gs[m], vs); unpack8(ga[m], va);
; #pragma unroll
;                         for (int e = 0; e < 4; ++e) {
;                             acc[ai][bj][m][0][e] *= (1.f + __expf(-(va[e] + a0[e]))) * __builtin_amdgcn_rcpf(1.f + __expf(-(vs[e] + s0[e])));
;                             acc[ai][bj][m][1][e] *= (1.f + __expf(-(va[4 + e] + a1[e]))) * __builtin_amdgcn_rcpf(1.f + __expf(-(vs[4 + e] + s1[e]))); } }
	v_lshlrev_b32_e32 v228, 16, v159
	v_and_b32_e32 v234, 0xffff0000, v159
	v_lshlrev_b32_e32 v159, 16, v160
	v_and_b32_e32 v230, 0xffff0000, v160
	v_rcp_f32_e32 v160, v3
	v_add_f32_e32 v3, v126, v162
	v_mul_f32_e32 v3, 0xbfb8aa3b, v3
	v_exp_f32_e32 v3, v3
	v_lshlrev_b32_e32 v227, 16, v163
	v_and_b32_e32 v229, 0xffff0000, v163
	v_and_b32_e32 v163, 0xffff0000, v164
	v_lshlrev_b32_e32 v164, 16, v158
	v_add_f32_e32 v3, 1.0, v3
	v_lshlrev_b32_e32 v231, 16, v165
	v_and_b32_e32 v233, 0xffff0000, v165
	v_and_b32_e32 v165, 0xffff0000, v158
	v_add_f32_e32 v158, v146, v164
	v_rcp_f32_e32 v164, v3
	v_add_f32_e32 v3, v143, v225
	v_mul_f32_e32 v3, 0xbfb8aa3b, v3
	v_exp_f32_e32 v3, v3
	v_lshlrev_b32_e32 v232, 16, v161
	v_and_b32_e32 v235, 0xffff0000, v161
	v_add_f32_e32 v159, v130, v159
	v_add_f32_e32 v3, 1.0, v3
	v_rcp_f32_e32 v161, v3
	v_add_f32_e32 v3, v127, v163
	v_mul_f32_e32 v3, 0xbfb8aa3b, v3
	v_exp_f32_e32 v3, v3
	v_mul_f32_e32 v159, 0xbfb8aa3b, v159
	v_exp_f32_e32 v162, v159
	v_add_f32_e32 v159, v147, v165
	v_add_f32_e32 v3, 1.0, v3
	v_rcp_f32_e32 v165, v3
	v_add_f32_e32 v3, v144, v227
	v_mul_f32_e32 v3, 0xbfb8aa3b, v3
	v_exp_f32_e32 v3, v3
	v_add_f32_e32 v163, v131, v230
	v_add_f32_e32 v225, v148, v228
	v_add_f32_e32 v227, v145, v229
	v_add_f32_e32 v3, 1.0, v3
	v_rcp_f32_e32 v230, v3
	v_add_f32_e32 v3, v128, v231
	v_mul_f32_e32 v3, 0xbfb8aa3b, v3
	v_mul_f32_e32 v225, 0xbfb8aa3b, v225
	v_exp_f32_e32 v3, v3
	v_mul_f32_e32 v227, 0xbfb8aa3b, v227
	v_exp_f32_e32 v228, v225
	v_add_f32_e32 v225, v132, v232
	v_exp_f32_e32 v227, v227
	v_mul_f32_e32 v225, 0xbfb8aa3b, v225
	v_exp_f32_e32 v232, v225
	v_add_f32_e32 v225, v149, v234
	v_mul_f32_e32 v158, 0xbfb8aa3b, v158
	v_mul_f32_e32 v159, 0xbfb8aa3b, v159
	v_add_f32_e32 v3, 1.0, v3
	v_mul_f32_e32 v225, 0xbfb8aa3b, v225
	v_exp_f32_e32 v158, v158
	v_exp_f32_e32 v159, v159
	v_exp_f32_e32 v229, v225
	v_rcp_f32_e32 v234, v3
	v_add_f32_e32 v3, 1.0, v227
	v_rcp_f32_e32 v231, v3
	v_pk_add_f32 v[228:229], v[228:229], 1.0 op_sel_hi:[1,0]
	v_pk_add_f32 v[158:159], v[158:159], 1.0 op_sel_hi:[1,0]
	v_add_f32_e32 v3, v133, v235
	v_pk_mul_f32 v[158:159], v[158:159], v[160:161]
	v_pk_mul_f32 v[160:161], v[228:229], v[230:231]
	v_mul_f32_e32 v3, 0xbfb8aa3b, v3
	v_pk_mul_f32 v[84:85], v[84:85], v[160:161]
	v_add_f32_e32 v160, v129, v233
	v_mul_f32_e32 v160, 0xbfb8aa3b, v160
	v_exp_f32_e32 v160, v160
	v_exp_f32_e32 v233, v3
	s_waitcnt vmcnt(1)
	v_lshlrev_b32_e32 v225, 16, v155
	v_and_b32_e32 v227, 0xffff0000, v155
	v_add_f32_e32 v3, 1.0, v160
	v_rcp_f32_e32 v235, v3
	v_lshlrev_b32_e32 v3, 16, v154
	v_add_f32_e32 v3, v142, v3
	v_mul_f32_e32 v3, 0xbfb8aa3b, v3
	v_exp_f32_e32 v3, v3
	v_lshlrev_b32_e32 v155, 16, v156
	v_and_b32_e32 v236, 0xffff0000, v156
	s_waitcnt vmcnt(0)
	v_lshlrev_b32_e32 v156, 16, v150
	v_add_f32_e32 v3, 1.0, v3
	v_mul_f32_e32 v163, 0xbfb8aa3b, v163
	v_add_f32_e32 v142, v146, v156
	v_rcp_f32_e32 v146, v3
	v_add_f32_e32 v3, v126, v155
	v_exp_f32_e32 v163, v163
	v_mul_f32_e32 v3, 0xbfb8aa3b, v3
	v_exp_f32_e32 v3, v3
	v_pk_mul_f32 v[82:83], v[82:83], v[158:159]
	v_pk_add_f32 v[158:159], v[232:233], 1.0 op_sel_hi:[1,0]
	v_pk_add_f32 v[160:161], v[162:163], 1.0 op_sel_hi:[1,0]
	v_pk_mul_f32 v[158:159], v[158:159], v[234:235]
	v_pk_mul_f32 v[160:161], v[160:161], v[164:165]
	v_and_b32_e32 v150, 0xffff0000, v150
	v_lshlrev_b32_e32 v239, 16, v151
	v_and_b32_e32 v240, 0xffff0000, v151
	v_lshlrev_b32_e32 v151, 16, v152
	global_load_dwordx4 v[228:231], v[192:193], off offset:256
	global_load_dwordx4 v[232:235], v[202:203], off offset:256
	v_add_f32_e32 v3, 1.0, v3
	v_pk_mul_f32 v[80:81], v[80:81], v[158:159]
	v_pk_mul_f32 v[78:79], v[78:79], v[160:161]
	v_and_b32_e32 v241, 0xffff0000, v152
	v_lshlrev_b32_e32 v242, 16, v153
	v_and_b32_e32 v243, 0xffff0000, v153
	v_add_f32_e32 v126, v130, v151
	v_rcp_f32_e32 v130, v3
	v_add_f32_e32 v3, v147, v150
	global_load_dwordx4 v[150:153], v[196:197], off offset:528
	global_load_dwordx4 v[158:161], v[196:197], off offset:512
	v_and_b32_e32 v154, 0xffff0000, v154
	v_lshlrev_b32_e32 v237, 16, v157
	v_and_b32_e32 v238, 0xffff0000, v157
	v_add_f32_e32 v143, v143, v154
	global_load_dwordx4 v[154:157], v[198:199], off offset:528
	global_load_dwordx4 v[162:165], v[198:199], off offset:512
	v_mul_f32_e32 v143, 0xbfb8aa3b, v143
	v_exp_f32_e32 v147, v143
	v_mul_f32_e32 v3, 0xbfb8aa3b, v3
	v_exp_f32_e32 v143, v3
	v_add_f32_e32 v145, v145, v227
	v_add_f32_e32 v3, 1.0, v147
	v_rcp_f32_e32 v147, v3
	v_add_f32_e32 v3, v127, v236
	v_mul_f32_e32 v3, 0xbfb8aa3b, v3
	v_exp_f32_e32 v3, v3
	v_add_f32_e32 v127, v131, v241
	v_mul_f32_e32 v145, 0xbfb8aa3b, v145
	v_add_f32_e32 v129, v129, v238
	v_add_f32_e32 v3, 1.0, v3
	v_rcp_f32_e32 v131, v3
	v_add_f32_e32 v3, v144, v225
	v_mul_f32_e32 v3, 0xbfb8aa3b, v3
	v_exp_f32_e32 v3, v3
	v_add_f32_e32 v144, v148, v239
	v_mul_f32_e32 v129, 0xbfb8aa3b, v129
	v_mul_f32_e32 v142, 0xbfb8aa3b, v142
	v_add_f32_e32 v3, 1.0, v3
	v_rcp_f32_e32 v148, v3
	v_add_f32_e32 v3, v128, v237
	v_mul_f32_e32 v3, 0xbfb8aa3b, v3
	v_exp_f32_e32 v3, v3
	v_add_f32_e32 v128, v132, v242
	v_add_f32_e32 v132, v149, v240
	v_exp_f32_e32 v149, v145
	v_add_f32_e32 v3, 1.0, v3
	v_mul_f32_e32 v132, 0xbfb8aa3b, v132
	v_exp_f32_e32 v145, v132
	v_rcp_f32_e32 v132, v3
	v_add_f32_e32 v3, 1.0, v149
	v_rcp_f32_e32 v149, v3
	v_add_f32_e32 v3, v133, v243
	v_exp_f32_e32 v133, v129
	v_mul_f32_e32 v126, 0xbfb8aa3b, v126
	v_mul_f32_e32 v127, 0xbfb8aa3b, v127
	v_mul_f32_e32 v144, 0xbfb8aa3b, v144
	v_mul_f32_e32 v128, 0xbfb8aa3b, v128
	v_mul_f32_e32 v3, 0xbfb8aa3b, v3
	v_exp_f32_e32 v142, v142
	v_exp_f32_e32 v126, v126
	v_exp_f32_e32 v127, v127
	v_exp_f32_e32 v144, v144
	v_exp_f32_e32 v128, v128
	v_exp_f32_e32 v129, v3
	v_add_f32_e32 v3, 1.0, v133
	v_rcp_f32_e32 v133, v3
	v_pk_add_f32 v[144:145], v[144:145], 1.0 op_sel_hi:[1,0]
	v_pk_add_f32 v[142:143], v[142:143], 1.0 op_sel_hi:[1,0]
	v_pk_add_f32 v[128:129], v[128:129], 1.0 op_sel_hi:[1,0]
	v_pk_add_f32 v[126:127], v[126:127], 1.0 op_sel_hi:[1,0]
	v_pk_mul_f32 v[142:143], v[142:143], v[146:147]
	v_pk_mul_f32 v[144:145], v[144:145], v[148:149]
	v_pk_mul_f32 v[126:127], v[126:127], v[130:131]
	v_pk_mul_f32 v[128:129], v[128:129], v[132:133]
	v_pk_mul_f32 v[76:77], v[76:77], v[144:145]
	v_pk_mul_f32 v[74:75], v[74:75], v[142:143]
	v_pk_mul_f32 v[72:73], v[72:73], v[128:129]
	v_pk_mul_f32 v[70:71], v[70:71], v[126:127]
	global_load_dwordx4 v[196:199], v[4:5], off offset:256
	global_load_dwordx4 v[236:239], v[186:187], off offset:256
	global_load_dwordx4 v[146:149], v[188:189], off offset:256
	global_load_dwordx4 v[142:145], v[190:191], off offset:256
	global_load_dwordx4 v[130:133], v[194:195], off offset:256
	global_load_dwordx4 v[126:129], v[200:201], off offset:256
	s_waitcnt vmcnt(11)
; __device__ __forceinline__ void unpack8(const u32x4 w, float (&v)[8]) { v[0] = bf_lo(w.x); v[1] = bf_hi(w.x); v[2] = bf_lo(w.y); v[3] = bf_hi(w.y); v[4] = bf_lo(w.z); v[5] = bf_hi(w.z); v[6] = bf_lo(w.w); v[7] = bf_hi(w.w); }
;     __device__ __forceinline__ void after(int te, f32x4 (&acc)[2][2][4][2], const Unit& u, int wr, int wc, int fr, int fq) const {
;     ...
;                     for (int m = 0; m < 4; ++m) { float vs[8], va[8]; unpack8(gs[m], vs); unpack8(ga[m], va);
; #pragma unroll
;                         for (int e = 0; e < 4; ++e) {
;                             acc[ai][bj][m][0][e] *= (1.f + __expf(-(va[e] + a0[e]))) * __builtin_amdgcn_rcpf(1.f + __expf(-(vs[e] + s0[e])));
;                             acc[ai][bj][m][1][e] *= (1.f + __expf(-(va[4 + e] + a1[e]))) * __builtin_amdgcn_rcpf(1.f + __expf(-(vs[4 + e] + s1[e]))); } }
	v_lshlrev_b32_e32 v3, 16, v228
	v_lshlrev_b32_e32 v187, 16, v230
	v_and_b32_e32 v5, 0xffff0000, v228
	s_waitcnt vmcnt(10)
	v_lshlrev_b32_e32 v188, 16, v234
	v_and_b32_e32 v189, 0xffff0000, v230
	v_lshlrev_b32_e32 v192, 16, v229
	v_and_b32_e32 v191, 0xffff0000, v232
	v_lshlrev_b32_e32 v195, 16, v231
	v_lshlrev_b32_e32 v194, 16, v233
	v_and_b32_e32 v193, 0xffff0000, v229
	v_lshlrev_b32_e32 v203, 16, v235
	s_waitcnt vmcnt(8)
	v_add_f32_e32 v3, v158, v3
	v_mul_f32_e32 v3, 0xbfb8aa3b, v3
	v_exp_f32_e32 v3, v3
	v_add_f32_e32 v193, v161, v193
	v_mul_f32_e32 v193, 0xbfb8aa3b, v193
	v_lshlrev_b32_e32 v4, 16, v232
	v_add_f32_e32 v3, 1.0, v3
	v_rcp_f32_e32 v186, v3
	v_add_f32_e32 v3, v150, v187
	v_mul_f32_e32 v3, 0xbfb8aa3b, v3
	v_exp_f32_e32 v3, v3
	s_waitcnt vmcnt(7)
	v_add_f32_e32 v187, v154, v188
	v_mul_f32_e32 v187, 0xbfb8aa3b, v187
	v_exp_f32_e32 v188, v187
	v_add_f32_e32 v3, 1.0, v3
	v_rcp_f32_e32 v190, v3
	v_add_f32_e32 v3, v159, v5
	v_mul_f32_e32 v3, 0xbfb8aa3b, v3
	v_exp_f32_e32 v3, v3
	s_waitcnt vmcnt(6)
	v_add_f32_e32 v5, v163, v191
	v_and_b32_e32 v202, 0xffff0000, v233
	v_and_b32_e32 v200, 0xffff0000, v234
	v_add_f32_e32 v3, 1.0, v3
	v_rcp_f32_e32 v187, v3
	v_add_f32_e32 v3, v151, v189
	v_mul_f32_e32 v3, 0xbfb8aa3b, v3
	v_exp_f32_e32 v3, v3
	v_add_f32_e32 v4, v162, v4
	v_add_f32_e32 v189, v155, v200
	v_mul_f32_e32 v4, 0xbfb8aa3b, v4
	v_add_f32_e32 v3, 1.0, v3
	v_rcp_f32_e32 v191, v3
	v_add_f32_e32 v3, v160, v192
	v_mul_f32_e32 v3, 0xbfb8aa3b, v3
	v_exp_f32_e32 v3, v3
	v_add_f32_e32 v192, v164, v194
	v_mul_f32_e32 v5, 0xbfb8aa3b, v5
	v_mul_f32_e32 v192, 0xbfb8aa3b, v192
	v_add_f32_e32 v3, 1.0, v3
	v_rcp_f32_e32 v194, v3
	v_add_f32_e32 v3, v152, v195
	v_mul_f32_e32 v3, 0xbfb8aa3b, v3
	v_exp_f32_e32 v3, v3
	v_add_f32_e32 v195, v156, v203
	v_exp_f32_e32 v203, v193
	v_mul_f32_e32 v195, 0xbfb8aa3b, v195
	v_exp_f32_e32 v200, v195
	v_add_f32_e32 v195, v165, v202
	v_add_f32_e32 v3, 1.0, v3
	v_mul_f32_e32 v193, 0xbfb8aa3b, v195
	v_exp_f32_e32 v4, v4
	v_exp_f32_e32 v5, v5
	v_exp_f32_e32 v192, v192
	v_exp_f32_e32 v193, v193
	v_rcp_f32_e32 v202, v3
	v_add_f32_e32 v3, 1.0, v203
	v_rcp_f32_e32 v195, v3
	v_pk_add_f32 v[192:193], v[192:193], 1.0 op_sel_hi:[1,0]
	v_pk_add_f32 v[4:5], v[4:5], 1.0 op_sel_hi:[1,0]
	v_and_b32_e32 v201, 0xffff0000, v231
	v_pk_mul_f32 v[4:5], v[4:5], v[186:187]
	v_pk_mul_f32 v[186:187], v[192:193], v[194:195]
	v_and_b32_e32 v225, 0xffff0000, v235
	v_pk_mul_f32 v[68:69], v[68:69], v[186:187]
	v_add_f32_e32 v186, v153, v201
	v_mul_f32_e32 v186, 0xbfb8aa3b, v186
	v_exp_f32_e32 v186, v186
	v_add_f32_e32 v3, v157, v225
	v_mul_f32_e32 v3, 0xbfb8aa3b, v3
	v_exp_f32_e32 v201, v3
	v_add_f32_e32 v3, 1.0, v186
	v_mul_f32_e32 v189, 0xbfb8aa3b, v189
	v_rcp_f32_e32 v203, v3
	s_waitcnt vmcnt(5)
	v_lshlrev_b32_e32 v3, 16, v196
	v_exp_f32_e32 v189, v189
	v_add_f32_e32 v3, v158, v3
	v_mul_f32_e32 v3, 0xbfb8aa3b, v3
	v_exp_f32_e32 v3, v3
	v_pk_add_f32 v[186:187], v[188:189], 1.0 op_sel_hi:[1,0]
	v_pk_mul_f32 v[66:67], v[66:67], v[4:5]
	v_pk_mul_f32 v[186:187], v[186:187], v[190:191]
	v_add_f32_e32 v3, 1.0, v3
	v_pk_mul_f32 v[62:63], v[62:63], v[186:187]
	v_lshlrev_b32_e32 v187, 16, v198
	v_rcp_f32_e32 v186, v3
	v_add_f32_e32 v3, v150, v187
	v_mul_f32_e32 v3, 0xbfb8aa3b, v3
	v_exp_f32_e32 v3, v3
	v_pk_add_f32 v[4:5], v[200:201], 1.0 op_sel_hi:[1,0]
	s_waitcnt vmcnt(4)
	v_lshlrev_b32_e32 v188, 16, v238
	v_pk_mul_f32 v[4:5], v[4:5], v[202:203]
	v_add_f32_e32 v3, 1.0, v3
	v_pk_mul_f32 v[64:65], v[64:65], v[4:5]
	v_and_b32_e32 v5, 0xffff0000, v196
	v_rcp_f32_e32 v190, v3
	v_add_f32_e32 v3, v159, v5
	v_mul_f32_e32 v3, 0xbfb8aa3b, v3
	v_exp_f32_e32 v3, v3
	v_add_f32_e32 v187, v154, v188
	v_and_b32_e32 v189, 0xffff0000, v198
	v_mul_f32_e32 v187, 0xbfb8aa3b, v187
	v_add_f32_e32 v3, 1.0, v3
	v_exp_f32_e32 v188, v187
	v_rcp_f32_e32 v187, v3
	v_add_f32_e32 v3, v151, v189
	v_mul_f32_e32 v3, 0xbfb8aa3b, v3
	v_exp_f32_e32 v3, v3
	v_lshlrev_b32_e32 v192, 16, v197
	v_and_b32_e32 v191, 0xffff0000, v236
	v_add_f32_e32 v5, v163, v191
	v_add_f32_e32 v3, 1.0, v3
	v_rcp_f32_e32 v191, v3
	v_add_f32_e32 v3, v160, v192
	v_mul_f32_e32 v3, 0xbfb8aa3b, v3
	v_exp_f32_e32 v3, v3
	v_lshlrev_b32_e32 v195, 16, v199
	v_lshlrev_b32_e32 v194, 16, v237
	v_and_b32_e32 v193, 0xffff0000, v197
	v_add_f32_e32 v3, 1.0, v3
	v_add_f32_e32 v192, v164, v194
	v_rcp_f32_e32 v194, v3
	v_add_f32_e32 v3, v152, v195
	v_mul_f32_e32 v3, 0xbfb8aa3b, v3
	v_add_f32_e32 v193, v161, v193
	v_and_b32_e32 v197, 0xffff0000, v199
	v_lshlrev_b32_e32 v199, 16, v239
	v_exp_f32_e32 v3, v3
	v_mul_f32_e32 v193, 0xbfb8aa3b, v193
	v_add_f32_e32 v195, v156, v199
	v_exp_f32_e32 v199, v193
	v_lshlrev_b32_e32 v4, 16, v236
	v_and_b32_e32 v198, 0xffff0000, v237
	v_and_b32_e32 v196, 0xffff0000, v238
	v_mul_f32_e32 v195, 0xbfb8aa3b, v195
	v_add_f32_e32 v4, v162, v4
	v_add_f32_e32 v189, v155, v196
	v_exp_f32_e32 v196, v195
	v_add_f32_e32 v195, v165, v198
	v_mul_f32_e32 v4, 0xbfb8aa3b, v4
	v_mul_f32_e32 v5, 0xbfb8aa3b, v5
	v_mul_f32_e32 v192, 0xbfb8aa3b, v192
	v_add_f32_e32 v3, 1.0, v3
	v_mul_f32_e32 v193, 0xbfb8aa3b, v195
	v_exp_f32_e32 v4, v4
	v_exp_f32_e32 v5, v5
	v_exp_f32_e32 v192, v192
	v_exp_f32_e32 v193, v193
	v_rcp_f32_e32 v198, v3
	v_add_f32_e32 v3, 1.0, v199
	v_rcp_f32_e32 v195, v3
	v_pk_add_f32 v[192:193], v[192:193], 1.0 op_sel_hi:[1,0]
	v_pk_add_f32 v[4:5], v[4:5], 1.0 op_sel_hi:[1,0]
	v_and_b32_e32 v200, 0xffff0000, v239
	v_pk_mul_f32 v[4:5], v[4:5], v[186:187]
	v_pk_mul_f32 v[186:187], v[192:193], v[194:195]
	v_add_f32_e32 v3, v157, v200
	v_pk_mul_f32 v[60:61], v[60:61], v[186:187]
	v_add_f32_e32 v186, v153, v197
	v_mul_f32_e32 v186, 0xbfb8aa3b, v186
	v_exp_f32_e32 v186, v186
	v_mul_f32_e32 v3, 0xbfb8aa3b, v3
	v_exp_f32_e32 v197, v3
	v_mul_f32_e32 v189, 0xbfb8aa3b, v189
	v_add_f32_e32 v3, 1.0, v186
	v_rcp_f32_e32 v199, v3
	s_waitcnt vmcnt(3)
; __device__ __forceinline__ void unpack8(const u32x4 w, float (&v)[8]) { v[0] = bf_lo(w.x); v[1] = bf_hi(w.x); v[2] = bf_lo(w.y); v[3] = bf_hi(w.y); v[4] = bf_lo(w.z); v[5] = bf_hi(w.z); v[6] = bf_lo(w.w); v[7] = bf_hi(w.w); }
;     __device__ __forceinline__ void after(int te, f32x4 (&acc)[2][2][4][2], const Unit& u, int wr, int wc, int fr, int fq) const {
;     ...
;             for (int bj = 0; bj < 2; ++bj) { const int c = col0 + bj * HALF;
;                 const f32x4 s0 = *(const f32x4*)(gb + c), s1 = *(const f32x4*)(gb + c + 4), a0 = *(const f32x4*)(gb + D_MODEL + c), a1 = *(const f32x4*)(gb + D_MODEL + c + 4);
; #pragma unroll
;                 for (int ai = 0; ai < 2; ++ai) {
;                     u32x4 gs[4], ga[4];
; #pragma unroll
;                     for (int m = 0; m < 4; ++m) { const size_t r = (size_t)(row0 + ai * HALF + m * 16); gs[m] = *(const u32x4*)(proj + r * LDP + PGS + c); ga[m] = *(const u32x4*)(proj + r * LDP + PGA + c); }
; #pragma unroll
;                     for (int m = 0; m < 4; ++m) { float vs[8], va[8]; unpack8(gs[m], vs); unpack8(ga[m], va);
; #pragma unroll
;                         for (int e = 0; e < 4; ++e) {
;                             acc[ai][bj][m][0][e] *= (1.f + __expf(-(va[e] + a0[e]))) * __builtin_amdgcn_rcpf(1.f + __expf(-(vs[e] + s0[e])));
;                             acc[ai][bj][m][1][e] *= (1.f + __expf(-(va[4 + e] + a1[e]))) * __builtin_amdgcn_rcpf(1.f + __expf(-(vs[4 + e] + s1[e]))); } }
;                     asm volatile("" ::: "memory");
	v_lshlrev_b32_e32 v3, 16, v146
	v_add_f32_e32 v3, v158, v3
	v_exp_f32_e32 v189, v189
	v_mul_f32_e32 v3, 0xbfb8aa3b, v3
	v_exp_f32_e32 v3, v3
	v_pk_mul_f32 v[58:59], v[58:59], v[4:5]
	v_pk_add_f32 v[4:5], v[196:197], 1.0 op_sel_hi:[1,0]
	v_pk_add_f32 v[186:187], v[188:189], 1.0 op_sel_hi:[1,0]
	v_pk_mul_f32 v[4:5], v[4:5], v[198:199]
	v_pk_mul_f32 v[186:187], v[186:187], v[190:191]
	v_pk_mul_f32 v[56:57], v[56:57], v[4:5]
	v_and_b32_e32 v5, 0xffff0000, v146
	v_lshlrev_b32_e32 v146, 16, v148
	v_add_f32_e32 v3, 1.0, v3
	v_pk_mul_f32 v[54:55], v[54:55], v[186:187]
	v_lshlrev_b32_e32 v186, 16, v147
	v_and_b32_e32 v187, 0xffff0000, v147
	v_and_b32_e32 v147, 0xffff0000, v148
	s_waitcnt vmcnt(2)
	v_lshlrev_b32_e32 v4, 16, v142
	v_and_b32_e32 v148, 0xffff0000, v142
	v_rcp_f32_e32 v142, v3
	v_add_f32_e32 v3, v150, v146
	v_mul_f32_e32 v3, 0xbfb8aa3b, v3
	v_exp_f32_e32 v3, v3
	v_lshlrev_b32_e32 v188, 16, v149
	v_and_b32_e32 v189, 0xffff0000, v149
	v_lshlrev_b32_e32 v149, 16, v143
	v_add_f32_e32 v3, 1.0, v3
	v_rcp_f32_e32 v146, v3
	v_add_f32_e32 v3, v159, v5
	v_mul_f32_e32 v3, 0xbfb8aa3b, v3
	v_exp_f32_e32 v3, v3
	v_and_b32_e32 v190, 0xffff0000, v143
	v_lshlrev_b32_e32 v143, 16, v144
	v_add_f32_e32 v143, v154, v143
	v_mul_f32_e32 v143, 0xbfb8aa3b, v143
	v_add_f32_e32 v3, 1.0, v3
	v_and_b32_e32 v191, 0xffff0000, v144
	v_exp_f32_e32 v144, v143
	v_rcp_f32_e32 v143, v3
	v_add_f32_e32 v3, v151, v147
	v_mul_f32_e32 v3, 0xbfb8aa3b, v3
	v_exp_f32_e32 v3, v3
	v_add_f32_e32 v187, v161, v187
	v_lshlrev_b32_e32 v192, 16, v145
	v_mul_f32_e32 v187, 0xbfb8aa3b, v187
	v_add_f32_e32 v3, 1.0, v3
	v_rcp_f32_e32 v147, v3
	v_add_f32_e32 v3, v160, v186
	v_mul_f32_e32 v3, 0xbfb8aa3b, v3
	v_exp_f32_e32 v3, v3
	v_add_f32_e32 v5, v163, v148
	v_add_f32_e32 v148, v164, v149
	v_add_f32_e32 v149, v156, v192
	v_add_f32_e32 v3, 1.0, v3
	v_rcp_f32_e32 v186, v3
	v_add_f32_e32 v3, v152, v188
	v_mul_f32_e32 v3, 0xbfb8aa3b, v3
	v_exp_f32_e32 v3, v3
	v_exp_f32_e32 v187, v187
	v_mul_f32_e32 v149, 0xbfb8aa3b, v149
	v_add_f32_e32 v4, v162, v4
	v_exp_f32_e32 v188, v149
	v_add_f32_e32 v149, v165, v190
	v_mul_f32_e32 v4, 0xbfb8aa3b, v4
	v_mul_f32_e32 v5, 0xbfb8aa3b, v5
	v_mul_f32_e32 v148, 0xbfb8aa3b, v148
	v_add_f32_e32 v3, 1.0, v3
	v_mul_f32_e32 v149, 0xbfb8aa3b, v149
	v_exp_f32_e32 v4, v4
	v_exp_f32_e32 v5, v5
	v_exp_f32_e32 v148, v148
	v_exp_f32_e32 v149, v149
	v_rcp_f32_e32 v190, v3
	v_add_f32_e32 v3, 1.0, v187
	v_rcp_f32_e32 v187, v3
	v_pk_add_f32 v[148:149], v[148:149], 1.0 op_sel_hi:[1,0]
	v_pk_add_f32 v[4:5], v[4:5], 1.0 op_sel_hi:[1,0]
	v_and_b32_e32 v193, 0xffff0000, v145
	v_pk_mul_f32 v[4:5], v[4:5], v[142:143]
	v_pk_mul_f32 v[142:143], v[148:149], v[186:187]
	v_add_f32_e32 v3, v157, v193
	v_pk_mul_f32 v[52:53], v[52:53], v[142:143]
	v_add_f32_e32 v142, v153, v189
	v_mul_f32_e32 v142, 0xbfb8aa3b, v142
	v_mul_f32_e32 v3, 0xbfb8aa3b, v3
	v_exp_f32_e32 v142, v142
	v_exp_f32_e32 v189, v3
	v_pk_mul_f32 v[50:51], v[50:51], v[4:5]
	v_add_f32_e32 v3, 1.0, v142
	v_pk_add_f32 v[4:5], v[188:189], 1.0 op_sel_hi:[1,0]
	global_load_dwordx4 v[186:189], v[218:219], off offset:256
	v_add_f32_e32 v145, v155, v191
	v_rcp_f32_e32 v191, v3
	s_waitcnt vmcnt(2)
	v_lshlrev_b32_e32 v3, 16, v130
	v_mul_f32_e32 v145, 0xbfb8aa3b, v145
	v_add_f32_e32 v3, v158, v3
	v_exp_f32_e32 v145, v145
	v_mul_f32_e32 v3, 0xbfb8aa3b, v3
	v_exp_f32_e32 v3, v3
	v_pk_mul_f32 v[4:5], v[4:5], v[190:191]
	v_pk_add_f32 v[142:143], v[144:145], 1.0 op_sel_hi:[1,0]
	v_pk_mul_f32 v[48:49], v[48:49], v[4:5]
	v_pk_mul_f32 v[142:143], v[142:143], v[146:147]
	v_and_b32_e32 v5, 0xffff0000, v130
	v_lshlrev_b32_e32 v130, 16, v132
	v_add_f32_e32 v3, 1.0, v3
	v_pk_mul_f32 v[46:47], v[46:47], v[142:143]
	v_lshlrev_b32_e32 v142, 16, v131
	v_and_b32_e32 v143, 0xffff0000, v131
	v_and_b32_e32 v131, 0xffff0000, v132
	s_waitcnt vmcnt(1)
	v_lshlrev_b32_e32 v4, 16, v126
	v_and_b32_e32 v132, 0xffff0000, v126
	v_rcp_f32_e32 v126, v3
	v_add_f32_e32 v3, v150, v130
	v_mul_f32_e32 v3, 0xbfb8aa3b, v3
	v_exp_f32_e32 v3, v3
	global_load_dwordx4 v[190:193], v[216:217], off offset:256
	v_lshlrev_b32_e32 v144, 16, v133
	v_and_b32_e32 v145, 0xffff0000, v133
	v_add_f32_e32 v3, 1.0, v3
	v_rcp_f32_e32 v130, v3
	v_add_f32_e32 v3, v159, v5
	v_mul_f32_e32 v3, 0xbfb8aa3b, v3
	v_exp_f32_e32 v3, v3
	v_lshlrev_b32_e32 v133, 16, v127
	v_and_b32_e32 v146, 0xffff0000, v127
	v_lshlrev_b32_e32 v127, 16, v128
	v_add_f32_e32 v127, v154, v127
	v_mul_f32_e32 v127, 0xbfb8aa3b, v127
	v_add_f32_e32 v3, 1.0, v3
	v_and_b32_e32 v147, 0xffff0000, v128
	v_exp_f32_e32 v128, v127
	v_rcp_f32_e32 v127, v3
	v_add_f32_e32 v3, v151, v131
	v_mul_f32_e32 v3, 0xbfb8aa3b, v3
	v_exp_f32_e32 v3, v3
	v_add_f32_e32 v143, v161, v143
	v_lshlrev_b32_e32 v148, 16, v129
	v_mul_f32_e32 v143, 0xbfb8aa3b, v143
	v_add_f32_e32 v3, 1.0, v3
	v_rcp_f32_e32 v131, v3
	v_add_f32_e32 v3, v160, v142
	v_mul_f32_e32 v3, 0xbfb8aa3b, v3
	v_exp_f32_e32 v3, v3
	v_add_f32_e32 v5, v163, v132
	v_add_f32_e32 v132, v164, v133
	v_add_f32_e32 v133, v156, v148
	v_add_f32_e32 v3, 1.0, v3
	v_rcp_f32_e32 v142, v3
	v_add_f32_e32 v3, v152, v144
	v_mul_f32_e32 v3, 0xbfb8aa3b, v3
	v_exp_f32_e32 v3, v3
	v_exp_f32_e32 v143, v143
	v_mul_f32_e32 v133, 0xbfb8aa3b, v133
	v_add_f32_e32 v4, v162, v4
	v_exp_f32_e32 v144, v133
	v_add_f32_e32 v133, v165, v146
	v_mul_f32_e32 v4, 0xbfb8aa3b, v4
	v_mul_f32_e32 v5, 0xbfb8aa3b, v5
	v_mul_f32_e32 v132, 0xbfb8aa3b, v132
	v_add_f32_e32 v3, 1.0, v3
	v_mul_f32_e32 v133, 0xbfb8aa3b, v133
	v_exp_f32_e32 v4, v4
	v_exp_f32_e32 v5, v5
	v_exp_f32_e32 v132, v132
	v_exp_f32_e32 v133, v133
	v_rcp_f32_e32 v146, v3
	v_add_f32_e32 v3, 1.0, v143
	v_rcp_f32_e32 v143, v3
	v_pk_add_f32 v[132:133], v[132:133], 1.0 op_sel_hi:[1,0]
	v_pk_add_f32 v[4:5], v[4:5], 1.0 op_sel_hi:[1,0]
	v_and_b32_e32 v149, 0xffff0000, v129
	v_pk_mul_f32 v[4:5], v[4:5], v[126:127]
	v_pk_mul_f32 v[126:127], v[132:133], v[142:143]
	v_add_f32_e32 v129, v155, v147
	v_pk_mul_f32 v[44:45], v[44:45], v[126:127]
	v_add_f32_e32 v126, v153, v145
	v_mul_f32_e32 v126, 0xbfb8aa3b, v126
	v_exp_f32_e32 v126, v126
	v_mul_f32_e32 v129, 0xbfb8aa3b, v129
	v_add_f32_e32 v3, v157, v149
	v_exp_f32_e32 v129, v129
	v_mul_f32_e32 v3, 0xbfb8aa3b, v3
	v_exp_f32_e32 v145, v3
	v_add_f32_e32 v3, 1.0, v126
	v_rcp_f32_e32 v147, v3
	v_pk_add_f32 v[126:127], v[128:129], 1.0 op_sel_hi:[1,0]
	v_pk_mul_f32 v[42:43], v[42:43], v[4:5]
	v_pk_add_f32 v[4:5], v[144:145], 1.0 op_sel_hi:[1,0]
	v_pk_mul_f32 v[126:127], v[126:127], v[130:131]
	v_pk_mul_f32 v[4:5], v[4:5], v[146:147]
	v_pk_mul_f32 v[38:39], v[38:39], v[126:127]
	global_load_dwordx4 v[194:197], v[204:205], off offset:256
	global_load_dwordx4 v[198:201], v[206:207], off offset:256
	global_load_dwordx4 v[146:149], v[208:209], off offset:256
	global_load_dwordx4 v[142:145], v[210:211], off offset:256
	global_load_dwordx4 v[130:133], v[212:213], off offset:256
	global_load_dwordx4 v[126:129], v[214:215], off offset:256
	s_waitcnt vmcnt(7)
; __device__ __forceinline__ void unpack8(const u32x4 w, float (&v)[8]) { v[0] = bf_lo(w.x); v[1] = bf_hi(w.x); v[2] = bf_lo(w.y); v[3] = bf_hi(w.y); v[4] = bf_lo(w.z); v[5] = bf_hi(w.z); v[6] = bf_lo(w.w); v[7] = bf_hi(w.w); }
;     __device__ __forceinline__ void after(int te, f32x4 (&acc)[2][2][4][2], const Unit& u, int wr, int wc, int fr, int fq) const {
;     ...
;             for (int bj = 0; bj < 2; ++bj) { const int c = col0 + bj * HALF;
;                 const f32x4 s0 = *(const f32x4*)(gb + c), s1 = *(const f32x4*)(gb + c + 4), a0 = *(const f32x4*)(gb + D_MODEL + c), a1 = *(const f32x4*)(gb + D_MODEL + c + 4);
; #pragma unroll
;                 for (int ai = 0; ai < 2; ++ai) {
;                     u32x4 gs[4], ga[4];
; #pragma unroll
;                     for (int m = 0; m < 4; ++m) { const size_t r = (size_t)(row0 + ai * HALF + m * 16); gs[m] = *(const u32x4*)(proj + r * LDP + PGS + c); ga[m] = *(const u32x4*)(proj + r * LDP + PGA + c); }
; #pragma unroll
;                     for (int m = 0; m < 4; ++m) { float vs[8], va[8]; unpack8(gs[m], vs); unpack8(ga[m], va);
; #pragma unroll
;                         for (int e = 0; e < 4; ++e) {
;                             acc[ai][bj][m][0][e] *= (1.f + __expf(-(va[e] + a0[e]))) * __builtin_amdgcn_rcpf(1.f + __expf(-(vs[e] + s0[e])));
;                             acc[ai][bj][m][1][e] *= (1.f + __expf(-(va[4 + e] + a1[e]))) * __builtin_amdgcn_rcpf(1.f + __expf(-(vs[4 + e] + s1[e]))); } }
;                     asm volatile("" ::: "memory");
	v_lshlrev_b32_e32 v3, 16, v186
	v_add_f32_e32 v3, v158, v3
	v_mul_f32_e32 v3, 0xbfb8aa3b, v3
	v_exp_f32_e32 v3, v3
	v_lshlrev_b32_e32 v202, 16, v187
	v_and_b32_e32 v203, 0xffff0000, v187
	v_lshlrev_b32_e32 v187, 16, v188
	v_add_f32_e32 v3, 1.0, v3
	v_pk_mul_f32 v[40:41], v[40:41], v[4:5]
	v_and_b32_e32 v5, 0xffff0000, v186
	v_rcp_f32_e32 v186, v3
	v_add_f32_e32 v3, v150, v187
	v_mul_f32_e32 v3, 0xbfb8aa3b, v3
	v_exp_f32_e32 v3, v3
	v_lshlrev_b32_e32 v205, 16, v189
	v_and_b32_e32 v207, 0xffff0000, v189
	s_waitcnt vmcnt(6)
	v_lshlrev_b32_e32 v4, 16, v190
	v_add_f32_e32 v3, 1.0, v3
	v_and_b32_e32 v189, 0xffff0000, v190
	v_rcp_f32_e32 v190, v3
	v_add_f32_e32 v3, v159, v5
	v_mul_f32_e32 v3, 0xbfb8aa3b, v3
	v_exp_f32_e32 v3, v3
	v_and_b32_e32 v204, 0xffff0000, v188
	v_lshlrev_b32_e32 v188, 16, v192
	v_add_f32_e32 v187, v154, v188
	v_mul_f32_e32 v187, 0xbfb8aa3b, v187
	v_add_f32_e32 v3, 1.0, v3
	v_exp_f32_e32 v188, v187
	v_rcp_f32_e32 v187, v3
	v_add_f32_e32 v3, v151, v204
	v_mul_f32_e32 v3, 0xbfb8aa3b, v3
	v_exp_f32_e32 v3, v3
	v_lshlrev_b32_e32 v206, 16, v191
	v_and_b32_e32 v208, 0xffff0000, v191
	v_and_b32_e32 v191, 0xffff0000, v192
	v_add_f32_e32 v3, 1.0, v3
	v_add_f32_e32 v5, v163, v189
	v_add_f32_e32 v189, v155, v191
	v_rcp_f32_e32 v191, v3
	v_add_f32_e32 v3, v160, v202
	v_mul_f32_e32 v3, 0xbfb8aa3b, v3
	v_exp_f32_e32 v3, v3
	v_add_f32_e32 v203, v161, v203
	v_lshlrev_b32_e32 v209, 16, v193
	v_mul_f32_e32 v203, 0xbfb8aa3b, v203
	v_add_f32_e32 v3, 1.0, v3
	v_rcp_f32_e32 v202, v3
	v_add_f32_e32 v3, v152, v205
	v_mul_f32_e32 v3, 0xbfb8aa3b, v3
	v_exp_f32_e32 v3, v3
	v_and_b32_e32 v210, 0xffff0000, v193
	v_add_f32_e32 v193, v156, v209
	v_exp_f32_e32 v203, v203
	v_mul_f32_e32 v193, 0xbfb8aa3b, v193
	v_add_f32_e32 v4, v162, v4
	v_add_f32_e32 v192, v164, v206
	v_exp_f32_e32 v204, v193
	v_add_f32_e32 v193, v165, v208
	v_mul_f32_e32 v4, 0xbfb8aa3b, v4
	v_mul_f32_e32 v5, 0xbfb8aa3b, v5
	v_mul_f32_e32 v192, 0xbfb8aa3b, v192
	v_add_f32_e32 v3, 1.0, v3
	v_mul_f32_e32 v193, 0xbfb8aa3b, v193
	v_exp_f32_e32 v4, v4
	v_exp_f32_e32 v5, v5
	v_exp_f32_e32 v192, v192
	v_exp_f32_e32 v193, v193
	v_rcp_f32_e32 v206, v3
	v_add_f32_e32 v3, 1.0, v203
	v_rcp_f32_e32 v203, v3
	v_pk_add_f32 v[192:193], v[192:193], 1.0 op_sel_hi:[1,0]
	v_pk_add_f32 v[4:5], v[4:5], 1.0 op_sel_hi:[1,0]
	v_add_f32_e32 v3, v157, v210
	v_pk_mul_f32 v[4:5], v[4:5], v[186:187]
	v_pk_mul_f32 v[186:187], v[192:193], v[202:203]
	v_mul_f32_e32 v3, 0xbfb8aa3b, v3
	v_pk_mul_f32 v[36:37], v[36:37], v[186:187]
	v_add_f32_e32 v186, v153, v207
	v_mul_f32_e32 v186, 0xbfb8aa3b, v186
	v_exp_f32_e32 v186, v186
	v_exp_f32_e32 v205, v3
	v_mul_f32_e32 v189, 0xbfb8aa3b, v189
	v_exp_f32_e32 v189, v189
	v_add_f32_e32 v3, 1.0, v186
	v_rcp_f32_e32 v207, v3
	s_waitcnt vmcnt(5)
	v_lshlrev_b32_e32 v3, 16, v194
	v_add_f32_e32 v3, v158, v3
	v_mul_f32_e32 v3, 0xbfb8aa3b, v3
	v_exp_f32_e32 v3, v3
	v_pk_add_f32 v[186:187], v[188:189], 1.0 op_sel_hi:[1,0]
	v_pk_mul_f32 v[34:35], v[34:35], v[4:5]
	v_pk_mul_f32 v[186:187], v[186:187], v[190:191]
	v_add_f32_e32 v3, 1.0, v3
	v_pk_mul_f32 v[30:31], v[30:31], v[186:187]
	v_lshlrev_b32_e32 v187, 16, v196
	v_rcp_f32_e32 v186, v3
	v_add_f32_e32 v3, v150, v187
	v_mul_f32_e32 v3, 0xbfb8aa3b, v3
	v_exp_f32_e32 v3, v3
	v_pk_add_f32 v[4:5], v[204:205], 1.0 op_sel_hi:[1,0]
	s_waitcnt vmcnt(4)
	v_lshlrev_b32_e32 v188, 16, v200
	v_pk_mul_f32 v[4:5], v[4:5], v[206:207]
	v_add_f32_e32 v3, 1.0, v3
	v_pk_mul_f32 v[32:33], v[32:33], v[4:5]
	v_and_b32_e32 v5, 0xffff0000, v194
	v_rcp_f32_e32 v190, v3
	v_add_f32_e32 v3, v159, v5
	v_mul_f32_e32 v3, 0xbfb8aa3b, v3
	v_exp_f32_e32 v3, v3
	v_add_f32_e32 v187, v154, v188
	v_and_b32_e32 v189, 0xffff0000, v196
	v_mul_f32_e32 v187, 0xbfb8aa3b, v187
	v_add_f32_e32 v3, 1.0, v3
	v_exp_f32_e32 v188, v187
	v_rcp_f32_e32 v187, v3
	v_add_f32_e32 v3, v151, v189
	v_mul_f32_e32 v3, 0xbfb8aa3b, v3
	v_exp_f32_e32 v3, v3
	v_lshlrev_b32_e32 v192, 16, v195
	v_and_b32_e32 v191, 0xffff0000, v198
	v_add_f32_e32 v5, v163, v191
	v_add_f32_e32 v3, 1.0, v3
	v_rcp_f32_e32 v191, v3
	v_add_f32_e32 v3, v160, v192
	v_mul_f32_e32 v3, 0xbfb8aa3b, v3
	v_exp_f32_e32 v3, v3
	v_and_b32_e32 v193, 0xffff0000, v195
	v_lshlrev_b32_e32 v195, 16, v197
	v_lshlrev_b32_e32 v194, 16, v199
	v_add_f32_e32 v3, 1.0, v3
	v_add_f32_e32 v192, v164, v194
	v_rcp_f32_e32 v194, v3
	v_add_f32_e32 v3, v152, v195
	v_mul_f32_e32 v3, 0xbfb8aa3b, v3
	v_add_f32_e32 v193, v161, v193
	v_lshlrev_b32_e32 v4, 16, v198
	v_and_b32_e32 v198, 0xffff0000, v199
	v_lshlrev_b32_e32 v199, 16, v201
	v_exp_f32_e32 v3, v3
	v_mul_f32_e32 v193, 0xbfb8aa3b, v193
	v_add_f32_e32 v195, v156, v199
	v_exp_f32_e32 v199, v193
	v_and_b32_e32 v196, 0xffff0000, v200
	v_mul_f32_e32 v195, 0xbfb8aa3b, v195
	v_add_f32_e32 v4, v162, v4
	v_add_f32_e32 v189, v155, v196
	v_exp_f32_e32 v196, v195
	v_add_f32_e32 v195, v165, v198
	v_mul_f32_e32 v4, 0xbfb8aa3b, v4
	v_mul_f32_e32 v5, 0xbfb8aa3b, v5
	v_mul_f32_e32 v192, 0xbfb8aa3b, v192
	v_add_f32_e32 v3, 1.0, v3
	v_mul_f32_e32 v193, 0xbfb8aa3b, v195
	v_exp_f32_e32 v4, v4
	v_exp_f32_e32 v5, v5
	v_exp_f32_e32 v192, v192
	v_exp_f32_e32 v193, v193
	v_rcp_f32_e32 v198, v3
	v_add_f32_e32 v3, 1.0, v199
	v_rcp_f32_e32 v195, v3
	v_pk_add_f32 v[192:193], v[192:193], 1.0 op_sel_hi:[1,0]
	v_pk_add_f32 v[4:5], v[4:5], 1.0 op_sel_hi:[1,0]
	v_and_b32_e32 v197, 0xffff0000, v197
	v_pk_mul_f32 v[4:5], v[4:5], v[186:187]
	v_pk_mul_f32 v[186:187], v[192:193], v[194:195]
	v_and_b32_e32 v200, 0xffff0000, v201
	v_pk_mul_f32 v[28:29], v[28:29], v[186:187]
	v_add_f32_e32 v186, v153, v197
	v_mul_f32_e32 v186, 0xbfb8aa3b, v186
	v_exp_f32_e32 v186, v186
	v_add_f32_e32 v3, v157, v200
	v_mul_f32_e32 v3, 0xbfb8aa3b, v3
	v_exp_f32_e32 v197, v3
	v_add_f32_e32 v3, 1.0, v186
	v_rcp_f32_e32 v199, v3
	s_waitcnt vmcnt(3)
; __device__ __forceinline__ void unpack8(const u32x4 w, float (&v)[8]) { v[0] = bf_lo(w.x); v[1] = bf_hi(w.x); v[2] = bf_lo(w.y); v[3] = bf_hi(w.y); v[4] = bf_lo(w.z); v[5] = bf_hi(w.z); v[6] = bf_lo(w.w); v[7] = bf_hi(w.w); }
;     __device__ __forceinline__ void after(int te, f32x4 (&acc)[2][2][4][2], const Unit& u, int wr, int wc, int fr, int fq) const {
;     ...
;             for (int bj = 0; bj < 2; ++bj) { const int c = col0 + bj * HALF;
;                 const f32x4 s0 = *(const f32x4*)(gb + c), s1 = *(const f32x4*)(gb + c + 4), a0 = *(const f32x4*)(gb + D_MODEL + c), a1 = *(const f32x4*)(gb + D_MODEL + c + 4);
; #pragma unroll
;                 for (int ai = 0; ai < 2; ++ai) {
;                     u32x4 gs[4], ga[4];
; #pragma unroll
;                     for (int m = 0; m < 4; ++m) { const size_t r = (size_t)(row0 + ai * HALF + m * 16); gs[m] = *(const u32x4*)(proj + r * LDP + PGS + c); ga[m] = *(const u32x4*)(proj + r * LDP + PGA + c); }
; #pragma unroll
;                     for (int m = 0; m < 4; ++m) { float vs[8], va[8]; unpack8(gs[m], vs); unpack8(ga[m], va);
; #pragma unroll
;                         for (int e = 0; e < 4; ++e) {
;                             acc[ai][bj][m][0][e] *= (1.f + __expf(-(va[e] + a0[e]))) * __builtin_amdgcn_rcpf(1.f + __expf(-(vs[e] + s0[e])));
;                             acc[ai][bj][m][1][e] *= (1.f + __expf(-(va[4 + e] + a1[e]))) * __builtin_amdgcn_rcpf(1.f + __expf(-(vs[4 + e] + s1[e]))); } }
;                     asm volatile("" ::: "memory");
	v_lshlrev_b32_e32 v3, 16, v146
	v_mul_f32_e32 v189, 0xbfb8aa3b, v189
	v_add_f32_e32 v3, v158, v3
	v_exp_f32_e32 v189, v189
	v_mul_f32_e32 v3, 0xbfb8aa3b, v3
	v_exp_f32_e32 v3, v3
	v_pk_mul_f32 v[26:27], v[26:27], v[4:5]
	v_pk_add_f32 v[4:5], v[196:197], 1.0 op_sel_hi:[1,0]
	v_pk_add_f32 v[186:187], v[188:189], 1.0 op_sel_hi:[1,0]
	v_pk_mul_f32 v[4:5], v[4:5], v[198:199]
	v_pk_mul_f32 v[186:187], v[186:187], v[190:191]
	v_pk_mul_f32 v[24:25], v[24:25], v[4:5]
	v_and_b32_e32 v5, 0xffff0000, v146
	v_lshlrev_b32_e32 v146, 16, v148
	v_add_f32_e32 v3, 1.0, v3
	v_pk_mul_f32 v[22:23], v[22:23], v[186:187]
	v_lshlrev_b32_e32 v186, 16, v147
	v_and_b32_e32 v187, 0xffff0000, v147
	v_and_b32_e32 v147, 0xffff0000, v148
	s_waitcnt vmcnt(2)
	v_lshlrev_b32_e32 v4, 16, v142
	v_and_b32_e32 v148, 0xffff0000, v142
	v_rcp_f32_e32 v142, v3
	v_add_f32_e32 v3, v150, v146
	v_mul_f32_e32 v3, 0xbfb8aa3b, v3
	v_exp_f32_e32 v3, v3
	v_lshlrev_b32_e32 v188, 16, v149
	v_and_b32_e32 v189, 0xffff0000, v149
	v_lshlrev_b32_e32 v149, 16, v143
	v_add_f32_e32 v3, 1.0, v3
	v_rcp_f32_e32 v146, v3
	v_add_f32_e32 v3, v159, v5
	v_mul_f32_e32 v3, 0xbfb8aa3b, v3
	v_exp_f32_e32 v3, v3
	v_and_b32_e32 v190, 0xffff0000, v143
	v_lshlrev_b32_e32 v143, 16, v144
	v_add_f32_e32 v143, v154, v143
	v_mul_f32_e32 v143, 0xbfb8aa3b, v143
	v_add_f32_e32 v3, 1.0, v3
	v_and_b32_e32 v191, 0xffff0000, v144
	v_exp_f32_e32 v144, v143
	v_rcp_f32_e32 v143, v3
	v_add_f32_e32 v3, v151, v147
	v_mul_f32_e32 v3, 0xbfb8aa3b, v3
	v_exp_f32_e32 v3, v3
	v_add_f32_e32 v187, v161, v187
	v_lshlrev_b32_e32 v192, 16, v145
	v_mul_f32_e32 v187, 0xbfb8aa3b, v187
	v_add_f32_e32 v3, 1.0, v3
	v_rcp_f32_e32 v147, v3
	v_add_f32_e32 v3, v160, v186
	v_mul_f32_e32 v3, 0xbfb8aa3b, v3
	v_exp_f32_e32 v3, v3
	v_add_f32_e32 v5, v163, v148
	v_add_f32_e32 v148, v164, v149
	v_add_f32_e32 v149, v156, v192
	v_add_f32_e32 v3, 1.0, v3
	v_rcp_f32_e32 v186, v3
	v_add_f32_e32 v3, v152, v188
	v_mul_f32_e32 v3, 0xbfb8aa3b, v3
	v_exp_f32_e32 v3, v3
	v_exp_f32_e32 v187, v187
	v_mul_f32_e32 v149, 0xbfb8aa3b, v149
	v_add_f32_e32 v4, v162, v4
	v_exp_f32_e32 v188, v149
	v_add_f32_e32 v149, v165, v190
	v_mul_f32_e32 v4, 0xbfb8aa3b, v4
	v_mul_f32_e32 v5, 0xbfb8aa3b, v5
	v_mul_f32_e32 v148, 0xbfb8aa3b, v148
	v_add_f32_e32 v3, 1.0, v3
	v_mul_f32_e32 v149, 0xbfb8aa3b, v149
	v_exp_f32_e32 v4, v4
	v_exp_f32_e32 v5, v5
	v_exp_f32_e32 v148, v148
	v_exp_f32_e32 v149, v149
	v_rcp_f32_e32 v190, v3
	v_add_f32_e32 v3, 1.0, v187
	v_rcp_f32_e32 v187, v3
	v_pk_add_f32 v[148:149], v[148:149], 1.0 op_sel_hi:[1,0]
	v_pk_add_f32 v[4:5], v[4:5], 1.0 op_sel_hi:[1,0]
	v_and_b32_e32 v193, 0xffff0000, v145
	v_pk_mul_f32 v[4:5], v[4:5], v[142:143]
	v_pk_mul_f32 v[142:143], v[148:149], v[186:187]
	v_add_f32_e32 v3, v157, v193
	v_pk_mul_f32 v[20:21], v[20:21], v[142:143]
	v_add_f32_e32 v142, v153, v189
	v_mul_f32_e32 v142, 0xbfb8aa3b, v142
	v_exp_f32_e32 v142, v142
	v_mul_f32_e32 v3, 0xbfb8aa3b, v3
	v_exp_f32_e32 v189, v3
	v_add_f32_e32 v145, v155, v191
	v_add_f32_e32 v3, 1.0, v142
	v_rcp_f32_e32 v191, v3
	s_waitcnt vmcnt(1)
	v_lshlrev_b32_e32 v3, 16, v130
	v_mul_f32_e32 v145, 0xbfb8aa3b, v145
	v_add_f32_e32 v3, v158, v3
	v_exp_f32_e32 v145, v145
	v_mul_f32_e32 v3, 0xbfb8aa3b, v3
	v_exp_f32_e32 v3, v3
	v_pk_mul_f32 v[18:19], v[18:19], v[4:5]
	v_pk_add_f32 v[4:5], v[188:189], 1.0 op_sel_hi:[1,0]
	v_pk_add_f32 v[142:143], v[144:145], 1.0 op_sel_hi:[1,0]
	v_pk_mul_f32 v[4:5], v[4:5], v[190:191]
	v_pk_mul_f32 v[142:143], v[142:143], v[146:147]
	v_pk_mul_f32 v[16:17], v[16:17], v[4:5]
	v_and_b32_e32 v5, 0xffff0000, v130
	v_lshlrev_b32_e32 v130, 16, v132
	v_add_f32_e32 v3, 1.0, v3
	v_pk_mul_f32 v[14:15], v[14:15], v[142:143]
	v_lshlrev_b32_e32 v142, 16, v131
	v_and_b32_e32 v143, 0xffff0000, v131
	v_and_b32_e32 v131, 0xffff0000, v132
	s_waitcnt vmcnt(0)
	v_lshlrev_b32_e32 v4, 16, v126
	v_and_b32_e32 v132, 0xffff0000, v126
	v_rcp_f32_e32 v126, v3
	v_add_f32_e32 v3, v150, v130
	v_mul_f32_e32 v3, 0xbfb8aa3b, v3
	v_exp_f32_e32 v3, v3
	v_lshlrev_b32_e32 v144, 16, v133
	v_and_b32_e32 v145, 0xffff0000, v133
	v_lshlrev_b32_e32 v133, 16, v127
	v_add_f32_e32 v3, 1.0, v3
	v_rcp_f32_e32 v130, v3
	v_add_f32_e32 v3, v159, v5
	v_mul_f32_e32 v3, 0xbfb8aa3b, v3
	v_exp_f32_e32 v3, v3
	v_and_b32_e32 v146, 0xffff0000, v127
	v_lshlrev_b32_e32 v127, 16, v128
	v_add_f32_e32 v127, v154, v127
	v_mul_f32_e32 v127, 0xbfb8aa3b, v127
	v_add_f32_e32 v3, 1.0, v3
	v_and_b32_e32 v147, 0xffff0000, v128
	v_exp_f32_e32 v128, v127
	v_rcp_f32_e32 v127, v3
	v_add_f32_e32 v3, v151, v131
	v_mul_f32_e32 v3, 0xbfb8aa3b, v3
	v_exp_f32_e32 v3, v3
	v_add_f32_e32 v143, v161, v143
	v_lshlrev_b32_e32 v148, 16, v129
	v_mul_f32_e32 v143, 0xbfb8aa3b, v143
	v_add_f32_e32 v3, 1.0, v3
	v_rcp_f32_e32 v131, v3
	v_add_f32_e32 v3, v160, v142
	v_mul_f32_e32 v3, 0xbfb8aa3b, v3
	v_exp_f32_e32 v3, v3
	v_add_f32_e32 v5, v163, v132
	v_add_f32_e32 v132, v164, v133
	v_add_f32_e32 v133, v156, v148
	v_add_f32_e32 v3, 1.0, v3
	v_rcp_f32_e32 v142, v3
	v_add_f32_e32 v3, v152, v144
	v_mul_f32_e32 v3, 0xbfb8aa3b, v3
	v_exp_f32_e32 v3, v3
	v_exp_f32_e32 v143, v143
	v_mul_f32_e32 v133, 0xbfb8aa3b, v133
	v_add_f32_e32 v4, v162, v4
	v_exp_f32_e32 v144, v133
	v_add_f32_e32 v133, v165, v146
	v_mul_f32_e32 v4, 0xbfb8aa3b, v4
	v_mul_f32_e32 v5, 0xbfb8aa3b, v5
	v_mul_f32_e32 v132, 0xbfb8aa3b, v132
	v_add_f32_e32 v3, 1.0, v3
	v_mul_f32_e32 v133, 0xbfb8aa3b, v133
	v_exp_f32_e32 v4, v4
	v_exp_f32_e32 v5, v5
	v_exp_f32_e32 v132, v132
	v_exp_f32_e32 v133, v133
	v_rcp_f32_e32 v146, v3
	v_add_f32_e32 v3, 1.0, v143
	v_rcp_f32_e32 v143, v3
	v_pk_add_f32 v[132:133], v[132:133], 1.0 op_sel_hi:[1,0]
	v_pk_add_f32 v[4:5], v[4:5], 1.0 op_sel_hi:[1,0]
	v_and_b32_e32 v149, 0xffff0000, v129
	v_pk_mul_f32 v[4:5], v[4:5], v[126:127]
	v_pk_mul_f32 v[126:127], v[132:133], v[142:143]
	v_add_f32_e32 v129, v155, v147
	v_pk_mul_f32 v[12:13], v[12:13], v[126:127]
	v_add_f32_e32 v126, v153, v145
	v_mul_f32_e32 v126, 0xbfb8aa3b, v126
	v_exp_f32_e32 v126, v126
	v_add_f32_e32 v3, v157, v149
	v_mul_f32_e32 v129, 0xbfb8aa3b, v129
	v_mul_f32_e32 v3, 0xbfb8aa3b, v3
	v_exp_f32_e32 v129, v129
	v_exp_f32_e32 v145, v3
	v_add_f32_e32 v3, 1.0, v126
	v_rcp_f32_e32 v147, v3
	v_pk_mul_f32 v[10:11], v[10:11], v[4:5]
	v_pk_add_f32 v[4:5], v[144:145], 1.0 op_sel_hi:[1,0]
	v_pk_add_f32 v[126:127], v[128:129], 1.0 op_sel_hi:[1,0]
	v_pk_mul_f32 v[4:5], v[4:5], v[146:147]
	v_pk_mul_f32 v[126:127], v[126:127], v[130:131]
	v_pk_mul_f32 v[8:9], v[8:9], v[4:5]
	v_pk_mul_f32 v[6:7], v[6:7], v[126:127]

; #define PG8_STAGE(bufoff, gbase, voff) do { _Pragma("unroll") for (int _i = 0; _i < 2; ++_i) \
;         __builtin_amdgcn_global_load_lds((const unsigned*)((const char*)(gbase) + (voff)[_i]), (LAS unsigned*)(lds + (bufoff) + ldsw + _i * 8192), 16, 0, 0); } while (0)
; #define PG8_LDA(dst, b, h) do { _Pragma("unroll") for (int m = 0; m < 4; ++m) _Pragma("unroll") for (int k = 0; k < 2; ++k) dst[m][k] = *(const LAS bf16x8*)(lds + PG8_SA(b, h) + aoff + m * 2048 + k * 1024); } while (0)
; #define PG8_LDB(dst, b, h) do { _Pragma("unroll") for (int n = 0; n < 2; ++n) _Pragma("unroll") for (int k = 0; k < 2; ++k) dst[n][k] = *(const LAS bf16x8*)(lds + PG8_SB(b, h) + boff + n * 2048 + k * 1024); } while (0)
; #define PG8_MMA(ai, bj, At, Bt) do { __builtin_amdgcn_s_setprio(1); _Pragma("unroll") for (int m = 0; m < 4; ++m) _Pragma("unroll") for (int n = 0; n < 2; ++n) _Pragma("unroll") for (int k = 0; k < 2; ++k) \
;         acc[ai][bj][m][n] = __builtin_amdgcn_mfma_f32_16x16x32_bf16(Bt[n][k], At[m][k], acc[ai][bj][m][n], 0, 0, 0); __builtin_amdgcn_s_setprio(0); } while (0)
; #define PG8_WAIT_V(n) asm volatile("s_waitcnt vmcnt(" #n ")" ::: "memory")
; #define PG8_WAIT_L(n) asm volatile("s_waitcnt lgkmcnt(" #n ")" ::: "memory")
; template <class Epi, class Sched, bool ALIGN_EPI, class Hook = NoHook>
; __device__ __forceinline__ void gemm_phase(LAS unsigned char* lds, const Gemm g, const Sched& S, const Epi& E, const Hook& H = Hook()) {
;     ...
;         for (int t = tb; t < te; t += 2) {
;             const bool last = (t == nt - 2);
;             const char* a1 = cA + (size_t)(t + 1) * kstep;
;             const char* a2 = last ? nA : cA + (size_t)(t + 2) * kstep; const char* b2 = last ? nB : cB + (size_t)(t + 2) * kstep;
;             const char* a3 = a2 + kstep; const char* b3 = b2 + kstep;
;             if (last && has_next) S.a_ready(nxt);
;             PG8_LDB(B0, 0, 0); PG8_LDB(B1, 0, 1); PG8_SCHED; PG8_LDA(At, 0, 0); PG8_STAGE(PG8_SA(1, 1), a1 + hA, voffA);
;             PG8_WAIT_V(8); PG8_WAIT_L(0); PG8_BAR; PG8_MMA(0, 0, At, B0); PG8_MMA(0, 1, At, B1); PG8_BAR; PG8_SCHED;
;             PG8_LDA(At, 0, 1); PG8_STAGE(PG8_SB(0, 0), b2, voffB); PG8_STAGE(PG8_SB(0, 1), b2 + hB, voffB); PG8_STAGE(PG8_SA(0, 0), a2, voffA);
;             PG8_WAIT_V(8); PG8_WAIT_L(0); PG8_BAR; PG8_MMA(1, 0, At, B0); PG8_MMA(1, 1, At, B1); PG8_BAR; PG8_SCHED;
.LBB0_850:
	ds_read_b128 v[146:149], v1
	ds_read_b128 v[150:153], v1 offset:1024
	ds_read_b128 v[154:157], v1 offset:2048
	ds_read_b128 v[158:161], v1 offset:3072
	ds_read_b128 v[162:165], v142
	ds_read_b128 v[166:169], v142 offset:1024
	ds_read_b128 v[170:173], v142 offset:2048
	ds_read_b128 v[174:177], v142 offset:3072
	s_add_u32 s20, s6, 0x87c00080
	s_addc_u32 s21, s7, -1
	s_cmp_lg_u32 s42, 60
	s_cselect_b32 s20, s20, 0
	s_cselect_b32 s21, s21, 0
	s_add_u32 s22, s2, s20
	s_addc_u32 s23, s3, s21
	s_add_u32 s20, s14, s20
	s_addc_u32 s21, s15, s21
	s_mov_b32 m0, s43
	v_lshl_add_u64 v[178:179], v[138:139], 0, s[6:7]
	ds_read_b128 v[186:189], v143
	ds_read_b128 v[190:193], v143 offset:1024
	ds_read_b128 v[194:197], v143 offset:2048
	ds_read_b128 v[198:201], v143 offset:3072
	ds_read_b128 v[202:205], v143 offset:4096
	ds_read_b128 v[206:209], v143 offset:5120
	ds_read_b128 v[210:213], v143 offset:6144
	ds_read_b128 v[214:217], v143 offset:7168
	global_load_lds_dwordx4 v[178:179], off
	v_lshl_add_u64 v[178:179], v[140:141], 0, s[6:7]
	s_mov_b32 m0, s44
	s_nop 0
	global_load_lds_dwordx4 v[178:179], off
	s_waitcnt vmcnt(8)
	s_waitcnt lgkmcnt(0)
	s_barrier
	s_setprio 1
	s_waitcnt lgkmcnt(0)
	v_mfma_f32_16x16x32_bf16 v[54:57], v[146:149], v[186:189], v[54:57]
	v_mfma_f32_16x16x32_bf16 v[34:37], v[154:157], v[186:189], v[34:37]
	v_mfma_f32_16x16x32_bf16 v[42:45], v[146:149], v[194:197], v[42:45]
	v_mfma_f32_16x16x32_bf16 v[30:33], v[154:157], v[194:197], v[30:33]
	v_mfma_f32_16x16x32_bf16 v[62:65], v[146:149], v[202:205], v[62:65]
	v_mfma_f32_16x16x32_bf16 v[50:53], v[154:157], v[202:205], v[50:53]
	v_mfma_f32_16x16x32_bf16 v[78:81], v[146:149], v[210:213], v[78:81]
	v_mfma_f32_16x16x32_bf16 v[70:73], v[154:157], v[210:213], v[70:73]
	v_mfma_f32_16x16x32_bf16 v[54:57], v[150:153], v[190:193], v[54:57]
	v_mfma_f32_16x16x32_bf16 v[34:37], v[158:161], v[190:193], v[34:37]
	v_mfma_f32_16x16x32_bf16 v[42:45], v[150:153], v[198:201], v[42:45]
	v_mfma_f32_16x16x32_bf16 v[30:33], v[158:161], v[198:201], v[30:33]
	v_mfma_f32_16x16x32_bf16 v[62:65], v[150:153], v[206:209], v[62:65]
	v_mfma_f32_16x16x32_bf16 v[50:53], v[158:161], v[206:209], v[50:53]
	v_mfma_f32_16x16x32_bf16 v[78:81], v[150:153], v[214:217], v[78:81]
	v_mfma_f32_16x16x32_bf16 v[70:73], v[158:161], v[214:217], v[70:73]
	s_setprio 0
	s_setprio 1
	v_mfma_f32_16x16x32_bf16 v[10:13], v[162:165], v[186:189], v[10:13]
	v_mfma_f32_16x16x32_bf16 v[2:5], v[170:173], v[186:189], v[2:5]
	v_mfma_f32_16x16x32_bf16 v[14:17], v[162:165], v[194:197], v[14:17]
	v_mfma_f32_16x16x32_bf16 v[6:9], v[170:173], v[194:197], v[6:9]
	v_mfma_f32_16x16x32_bf16 v[22:25], v[162:165], v[202:205], v[22:25]
	v_mfma_f32_16x16x32_bf16 v[18:21], v[170:173], v[202:205], v[18:21]
	v_mfma_f32_16x16x32_bf16 v[38:41], v[162:165], v[210:213], v[38:41]
	v_mfma_f32_16x16x32_bf16 v[26:29], v[170:173], v[210:213], v[26:29]
	v_mfma_f32_16x16x32_bf16 v[10:13], v[166:169], v[190:193], v[10:13]
	v_mfma_f32_16x16x32_bf16 v[2:5], v[174:177], v[190:193], v[2:5]
	v_mfma_f32_16x16x32_bf16 v[14:17], v[166:169], v[198:201], v[14:17]
	v_mfma_f32_16x16x32_bf16 v[6:9], v[174:177], v[198:201], v[6:9]
	v_mfma_f32_16x16x32_bf16 v[22:25], v[166:169], v[206:209], v[22:25]
	v_mfma_f32_16x16x32_bf16 v[18:21], v[174:177], v[206:209], v[18:21]
	v_mfma_f32_16x16x32_bf16 v[38:41], v[166:169], v[214:217], v[38:41]
	v_mfma_f32_16x16x32_bf16 v[26:29], v[174:177], v[214:217], v[26:29]
	s_setprio 0
	s_barrier
	s_mov_b32 m0, s45
	s_add_u32 s54, s20, 0x100000
	ds_read_b128 v[186:189], v143 offset:16384
	ds_read_b128 v[190:193], v143 offset:17408
	ds_read_b128 v[194:197], v143 offset:18432
	ds_read_b128 v[198:201], v143 offset:19456
	ds_read_b128 v[202:205], v143 offset:20480
	ds_read_b128 v[206:209], v143 offset:21504
	ds_read_b128 v[210:213], v143 offset:22528
	ds_read_b128 v[214:217], v143 offset:23552
	global_load_lds_dwordx4 v132, s[20:21]
	s_mov_b32 m0, s46
	s_addc_u32 s55, s21, 0
	global_load_lds_dwordx4 v136, s[20:21]
	s_mov_b32 m0, s47
	s_nop 0
	global_load_lds_dwordx4 v132, s[54:55]
	s_mov_b32 m0, s48
	s_nop 0
	global_load_lds_dwordx4 v136, s[54:55]
	s_add_u32 s58, s22, s4
	s_addc_u32 s59, s23, s5
	s_mov_b32 m0, s28
	s_nop 0
	global_load_lds_dwordx4 v130, s[22:23]
	s_mov_b32 m0, s29
	s_nop 0
	global_load_lds_dwordx4 v134, s[22:23]
	s_waitcnt vmcnt(8)
	s_waitcnt lgkmcnt(0)
	s_barrier
	s_setprio 1
	s_waitcnt lgkmcnt(0)
	v_mfma_f32_16x16x32_bf16 v[94:97], v[146:149], v[186:189], v[94:97]
	v_mfma_f32_16x16x32_bf16 v[86:89], v[154:157], v[186:189], v[86:89]
	v_mfma_f32_16x16x32_bf16 v[102:105], v[146:149], v[194:197], v[102:105]
	v_mfma_f32_16x16x32_bf16 v[98:101], v[154:157], v[194:197], v[98:101]
	v_mfma_f32_16x16x32_bf16 v[110:113], v[146:149], v[202:205], v[110:113]
	v_mfma_f32_16x16x32_bf16 v[106:109], v[154:157], v[202:205], v[106:109]
	v_mfma_f32_16x16x32_bf16 v[126:129], v[146:149], v[210:213], v[126:129]
	v_mfma_f32_16x16x32_bf16 v[122:125], v[154:157], v[210:213], v[122:125]
	v_mfma_f32_16x16x32_bf16 v[94:97], v[150:153], v[190:193], v[94:97]
	v_mfma_f32_16x16x32_bf16 v[86:89], v[158:161], v[190:193], v[86:89]
	v_mfma_f32_16x16x32_bf16 v[102:105], v[150:153], v[198:201], v[102:105]
	v_mfma_f32_16x16x32_bf16 v[98:101], v[158:161], v[198:201], v[98:101]
	v_mfma_f32_16x16x32_bf16 v[110:113], v[150:153], v[206:209], v[110:113]
	v_mfma_f32_16x16x32_bf16 v[106:109], v[158:161], v[206:209], v[106:109]
	v_mfma_f32_16x16x32_bf16 v[126:129], v[150:153], v[214:217], v[126:129]
	v_mfma_f32_16x16x32_bf16 v[122:125], v[158:161], v[214:217], v[122:125]
	s_setprio 0
	s_setprio 1
	v_mfma_f32_16x16x32_bf16 v[58:61], v[162:165], v[186:189], v[58:61]
	v_mfma_f32_16x16x32_bf16 v[46:49], v[170:173], v[186:189], v[46:49]
	v_mfma_f32_16x16x32_bf16 v[74:77], v[162:165], v[194:197], v[74:77]
	v_mfma_f32_16x16x32_bf16 v[66:69], v[170:173], v[194:197], v[66:69]
	v_mfma_f32_16x16x32_bf16 v[90:93], v[162:165], v[202:205], v[90:93]
	v_mfma_f32_16x16x32_bf16 v[82:85], v[170:173], v[202:205], v[82:85]
	v_mfma_f32_16x16x32_bf16 v[118:121], v[162:165], v[210:213], v[118:121]
	v_mfma_f32_16x16x32_bf16 v[114:117], v[170:173], v[210:213], v[114:117]
	v_mfma_f32_16x16x32_bf16 v[58:61], v[166:169], v[190:193], v[58:61]
	v_mfma_f32_16x16x32_bf16 v[46:49], v[174:177], v[190:193], v[46:49]
	v_mfma_f32_16x16x32_bf16 v[74:77], v[166:169], v[198:201], v[74:77]
	v_mfma_f32_16x16x32_bf16 v[66:69], v[174:177], v[198:201], v[66:69]
	v_mfma_f32_16x16x32_bf16 v[90:93], v[166:169], v[206:209], v[90:93]
	v_mfma_f32_16x16x32_bf16 v[82:85], v[174:177], v[206:209], v[82:85]
	v_mfma_f32_16x16x32_bf16 v[118:121], v[166:169], v[214:217], v[118:121]
	v_mfma_f32_16x16x32_bf16 v[114:117], v[174:177], v[214:217], v[114:117]
	s_setprio 0
	s_barrier
; #define PG8_STAGE(bufoff, gbase, voff) do { _Pragma("unroll") for (int _i = 0; _i < 2; ++_i) \
;         __builtin_amdgcn_global_load_lds((const unsigned*)((const char*)(gbase) + (voff)[_i]), (LAS unsigned*)(lds + (bufoff) + ldsw + _i * 8192), 16, 0, 0); } while (0)
; #define PG8_LDA(dst, b, h) do { _Pragma("unroll") for (int m = 0; m < 4; ++m) _Pragma("unroll") for (int k = 0; k < 2; ++k) dst[m][k] = *(const LAS bf16x8*)(lds + PG8_SA(b, h) + aoff + m * 2048 + k * 1024); } while (0)
; #define PG8_LDB(dst, b, h) do { _Pragma("unroll") for (int n = 0; n < 2; ++n) _Pragma("unroll") for (int k = 0; k < 2; ++k) dst[n][k] = *(const LAS bf16x8*)(lds + PG8_SB(b, h) + boff + n * 2048 + k * 1024); } while (0)
; #define PG8_MMA(ai, bj, At, Bt) do { __builtin_amdgcn_s_setprio(1); _Pragma("unroll") for (int m = 0; m < 4; ++m) _Pragma("unroll") for (int n = 0; n < 2; ++n) _Pragma("unroll") for (int k = 0; k < 2; ++k) \
;         acc[ai][bj][m][n] = __builtin_amdgcn_mfma_f32_16x16x32_bf16(Bt[n][k], At[m][k], acc[ai][bj][m][n], 0, 0, 0); __builtin_amdgcn_s_setprio(0); } while (0)
; #define PG8_WAIT_V(n) asm volatile("s_waitcnt vmcnt(" #n ")" ::: "memory")
; #define PG8_WAIT_L(n) asm volatile("s_waitcnt lgkmcnt(" #n ")" ::: "memory")
; #define PG8_BAR __builtin_amdgcn_s_barrier()
; #define PG8_SCHED __builtin_amdgcn_sched_barrier(0)
; template <class Epi, class Sched, bool ALIGN_EPI, class Hook = NoHook>
; __device__ __forceinline__ void gemm_phase(LAS unsigned char* lds, const Gemm g, const Sched& S, const Epi& E, const Hook& H = Hook()) {
;     ...
;             PG8_LDB(B0, 1, 0); PG8_LDB(B1, 1, 1); PG8_SCHED; PG8_LDA(At, 1, 0); PG8_STAGE(PG8_SA(0, 1), a2 + hA, voffA);
;             PG8_WAIT_V(8); PG8_WAIT_L(0); PG8_BAR; PG8_MMA(0, 0, At, B0); PG8_MMA(0, 1, At, B1); PG8_BAR; PG8_SCHED;
;             PG8_LDA(At, 1, 1); PG8_STAGE(PG8_SB(1, 0), b3, voffB); PG8_STAGE(PG8_SB(1, 1), b3 + hB, voffB); PG8_STAGE(PG8_SA(1, 0), a3, voffA);
;             PG8_WAIT_V(8); PG8_WAIT_L(0); PG8_BAR; PG8_MMA(1, 0, At, B0); PG8_MMA(1, 1, At, B1); PG8_BAR; PG8_SCHED;
;         }
	ds_read_b128 v[146:149], v144
	ds_read_b128 v[150:153], v144 offset:1024
	ds_read_b128 v[154:157], v144 offset:2048
	ds_read_b128 v[158:161], v144 offset:3072
	ds_read_b128 v[162:165], v145
	ds_read_b128 v[166:169], v145 offset:1024
	ds_read_b128 v[170:173], v145 offset:2048
	ds_read_b128 v[174:177], v145 offset:3072
	s_add_u32 s22, s22, 0x100000
	s_addc_u32 s23, s23, 0
	s_mov_b32 m0, s38
	ds_read_b128 v[186:189], v143 offset:32768
	ds_read_b128 v[190:193], v143 offset:33792
	ds_read_b128 v[194:197], v143 offset:34816
	ds_read_b128 v[198:201], v143 offset:35840
	ds_read_b128 v[202:205], v143 offset:36864
	ds_read_b128 v[206:209], v143 offset:37888
	ds_read_b128 v[210:213], v143 offset:38912
	ds_read_b128 v[214:217], v143 offset:39936
	global_load_lds_dwordx4 v130, s[22:23]
	s_mov_b32 m0, s39
	s_nop 0
	global_load_lds_dwordx4 v134, s[22:23]
	s_waitcnt vmcnt(8)
	s_waitcnt lgkmcnt(0)
	s_barrier
	s_setprio 1
	s_waitcnt lgkmcnt(0)
	v_mfma_f32_16x16x32_bf16 v[54:57], v[146:149], v[186:189], v[54:57]
	v_mfma_f32_16x16x32_bf16 v[34:37], v[154:157], v[186:189], v[34:37]
	v_mfma_f32_16x16x32_bf16 v[42:45], v[146:149], v[194:197], v[42:45]
	v_mfma_f32_16x16x32_bf16 v[30:33], v[154:157], v[194:197], v[30:33]
	v_mfma_f32_16x16x32_bf16 v[62:65], v[146:149], v[202:205], v[62:65]
	v_mfma_f32_16x16x32_bf16 v[50:53], v[154:157], v[202:205], v[50:53]
	v_mfma_f32_16x16x32_bf16 v[78:81], v[146:149], v[210:213], v[78:81]
	v_mfma_f32_16x16x32_bf16 v[70:73], v[154:157], v[210:213], v[70:73]
	v_mfma_f32_16x16x32_bf16 v[54:57], v[150:153], v[190:193], v[54:57]
	v_mfma_f32_16x16x32_bf16 v[34:37], v[158:161], v[190:193], v[34:37]
	v_mfma_f32_16x16x32_bf16 v[42:45], v[150:153], v[198:201], v[42:45]
	v_mfma_f32_16x16x32_bf16 v[30:33], v[158:161], v[198:201], v[30:33]
	v_mfma_f32_16x16x32_bf16 v[62:65], v[150:153], v[206:209], v[62:65]
	v_mfma_f32_16x16x32_bf16 v[50:53], v[158:161], v[206:209], v[50:53]
	v_mfma_f32_16x16x32_bf16 v[78:81], v[150:153], v[214:217], v[78:81]
	v_mfma_f32_16x16x32_bf16 v[70:73], v[158:161], v[214:217], v[70:73]
	s_setprio 0
	s_setprio 1
	v_mfma_f32_16x16x32_bf16 v[10:13], v[162:165], v[186:189], v[10:13]
	v_mfma_f32_16x16x32_bf16 v[2:5], v[170:173], v[186:189], v[2:5]
	v_mfma_f32_16x16x32_bf16 v[14:17], v[162:165], v[194:197], v[14:17]
	v_mfma_f32_16x16x32_bf16 v[6:9], v[170:173], v[194:197], v[6:9]
	v_mfma_f32_16x16x32_bf16 v[22:25], v[162:165], v[202:205], v[22:25]
	v_mfma_f32_16x16x32_bf16 v[18:21], v[170:173], v[202:205], v[18:21]
	v_mfma_f32_16x16x32_bf16 v[38:41], v[162:165], v[210:213], v[38:41]
	v_mfma_f32_16x16x32_bf16 v[26:29], v[170:173], v[210:213], v[26:29]
	v_mfma_f32_16x16x32_bf16 v[10:13], v[166:169], v[190:193], v[10:13]
	v_mfma_f32_16x16x32_bf16 v[2:5], v[174:177], v[190:193], v[2:5]
	v_mfma_f32_16x16x32_bf16 v[14:17], v[166:169], v[198:201], v[14:17]
	v_mfma_f32_16x16x32_bf16 v[6:9], v[174:177], v[198:201], v[6:9]
	v_mfma_f32_16x16x32_bf16 v[22:25], v[166:169], v[206:209], v[22:25]
	v_mfma_f32_16x16x32_bf16 v[18:21], v[174:177], v[206:209], v[18:21]
	v_mfma_f32_16x16x32_bf16 v[38:41], v[166:169], v[214:217], v[38:41]
	v_mfma_f32_16x16x32_bf16 v[26:29], v[174:177], v[214:217], v[26:29]
	s_setprio 0
	s_barrier
	s_mov_b32 m0, s49
	s_add_u32 s56, s20, s4
	s_addc_u32 s57, s21, s5
	s_add_u32 s20, s20, 0x100080
	ds_read_b128 v[186:189], v143 offset:49152
	ds_read_b128 v[190:193], v143 offset:50176
	ds_read_b128 v[194:197], v143 offset:51200
	ds_read_b128 v[198:201], v143 offset:52224
	ds_read_b128 v[202:205], v143 offset:53248
	ds_read_b128 v[206:209], v143 offset:54272
	ds_read_b128 v[210:213], v143 offset:55296
	ds_read_b128 v[214:217], v143 offset:56320
	global_load_lds_dwordx4 v132, s[56:57]
	s_mov_b32 m0, s50
	s_addc_u32 s21, s21, 0
	global_load_lds_dwordx4 v136, s[56:57]
	s_mov_b32 m0, s51
	s_nop 0
	global_load_lds_dwordx4 v132, s[20:21]
	s_mov_b32 m0, s52
	s_nop 0
	global_load_lds_dwordx4 v136, s[20:21]
	s_mov_b32 m0, s40
	s_nop 0
	global_load_lds_dwordx4 v130, s[58:59]
	s_mov_b32 m0, s41
	s_nop 0
	global_load_lds_dwordx4 v134, s[58:59]
	s_waitcnt vmcnt(8)
	s_waitcnt lgkmcnt(0)
	s_barrier
	s_setprio 1
	s_waitcnt lgkmcnt(0)
	v_mfma_f32_16x16x32_bf16 v[94:97], v[146:149], v[186:189], v[94:97]
	v_mfma_f32_16x16x32_bf16 v[86:89], v[154:157], v[186:189], v[86:89]
	v_mfma_f32_16x16x32_bf16 v[102:105], v[146:149], v[194:197], v[102:105]
	v_mfma_f32_16x16x32_bf16 v[98:101], v[154:157], v[194:197], v[98:101]
	v_mfma_f32_16x16x32_bf16 v[110:113], v[146:149], v[202:205], v[110:113]
	v_mfma_f32_16x16x32_bf16 v[106:109], v[154:157], v[202:205], v[106:109]
	v_mfma_f32_16x16x32_bf16 v[126:129], v[146:149], v[210:213], v[126:129]
	v_mfma_f32_16x16x32_bf16 v[122:125], v[154:157], v[210:213], v[122:125]
	v_mfma_f32_16x16x32_bf16 v[94:97], v[150:153], v[190:193], v[94:97]
	v_mfma_f32_16x16x32_bf16 v[86:89], v[158:161], v[190:193], v[86:89]
	v_mfma_f32_16x16x32_bf16 v[102:105], v[150:153], v[198:201], v[102:105]
	v_mfma_f32_16x16x32_bf16 v[98:101], v[158:161], v[198:201], v[98:101]
	v_mfma_f32_16x16x32_bf16 v[110:113], v[150:153], v[206:209], v[110:113]
	v_mfma_f32_16x16x32_bf16 v[106:109], v[158:161], v[206:209], v[106:109]
	v_mfma_f32_16x16x32_bf16 v[126:129], v[150:153], v[214:217], v[126:129]
	v_mfma_f32_16x16x32_bf16 v[122:125], v[158:161], v[214:217], v[122:125]
	s_setprio 0
	s_setprio 1
	v_mfma_f32_16x16x32_bf16 v[58:61], v[162:165], v[186:189], v[58:61]
	v_mfma_f32_16x16x32_bf16 v[46:49], v[170:173], v[186:189], v[46:49]
	v_mfma_f32_16x16x32_bf16 v[74:77], v[162:165], v[194:197], v[74:77]
	v_mfma_f32_16x16x32_bf16 v[66:69], v[170:173], v[194:197], v[66:69]
	v_mfma_f32_16x16x32_bf16 v[90:93], v[162:165], v[202:205], v[90:93]
	v_mfma_f32_16x16x32_bf16 v[82:85], v[170:173], v[202:205], v[82:85]
	v_mfma_f32_16x16x32_bf16 v[118:121], v[162:165], v[210:213], v[118:121]
	v_mfma_f32_16x16x32_bf16 v[114:117], v[170:173], v[210:213], v[114:117]
	v_mfma_f32_16x16x32_bf16 v[58:61], v[166:169], v[190:193], v[58:61]
	v_mfma_f32_16x16x32_bf16 v[46:49], v[174:177], v[190:193], v[46:49]
	v_mfma_f32_16x16x32_bf16 v[74:77], v[166:169], v[198:201], v[74:77]
	v_mfma_f32_16x16x32_bf16 v[66:69], v[174:177], v[198:201], v[66:69]
	v_mfma_f32_16x16x32_bf16 v[90:93], v[166:169], v[206:209], v[90:93]
	v_mfma_f32_16x16x32_bf16 v[82:85], v[174:177], v[206:209], v[82:85]
	v_mfma_f32_16x16x32_bf16 v[118:121], v[166:169], v[214:217], v[118:121]
	v_mfma_f32_16x16x32_bf16 v[114:117], v[174:177], v[214:217], v[114:117]
	s_setprio 0
	s_barrier
	s_add_i32 s42, s42, 2
	s_add_u32 s6, s6, 0x100
	s_addc_u32 s7, s7, 0
	s_cmp_gt_u32 s42, 61
	s_cbranch_scc0 .LBB0_850
	s_cmpk_lt_u32 s26, 0x100
	s_cbranch_scc0 .LBB0_853
	s_barrier

; #define PG8_STAGE(bufoff, gbase, voff) do { _Pragma("unroll") for (int _i = 0; _i < 2; ++_i) \
;         __builtin_amdgcn_global_load_lds((const unsigned*)((const char*)(gbase) + (voff)[_i]), (LAS unsigned*)(lds + (bufoff) + ldsw + _i * 8192), 16, 0, 0); } while (0)
; #define PG8_LDA(dst, b, h) do { _Pragma("unroll") for (int m = 0; m < 4; ++m) _Pragma("unroll") for (int k = 0; k < 2; ++k) dst[m][k] = *(const LAS bf16x8*)(lds + PG8_SA(b, h) + aoff + m * 2048 + k * 1024); } while (0)
; #define PG8_LDB(dst, b, h) do { _Pragma("unroll") for (int n = 0; n < 2; ++n) _Pragma("unroll") for (int k = 0; k < 2; ++k) dst[n][k] = *(const LAS bf16x8*)(lds + PG8_SB(b, h) + boff + n * 2048 + k * 1024); } while (0)
; #define PG8_MMA(ai, bj, At, Bt) do { __builtin_amdgcn_s_setprio(1); _Pragma("unroll") for (int m = 0; m < 4; ++m) _Pragma("unroll") for (int n = 0; n < 2; ++n) _Pragma("unroll") for (int k = 0; k < 2; ++k) \
;         acc[ai][bj][m][n] = __builtin_amdgcn_mfma_f32_16x16x32_bf16(Bt[n][k], At[m][k], acc[ai][bj][m][n], 0, 0, 0); __builtin_amdgcn_s_setprio(0); } while (0)
; #define PG8_WAIT_V(n) asm volatile("s_waitcnt vmcnt(" #n ")" ::: "memory")
; #define PG8_WAIT_L(n) asm volatile("s_waitcnt lgkmcnt(" #n ")" ::: "memory")
; template <class Epi, class Sched, bool ALIGN_EPI, class Hook = NoHook>
; __device__ __forceinline__ void gemm_phase(LAS unsigned char* lds, const Gemm g, const Sched& S, const Epi& E, const Hook& H = Hook()) {
;     ...
;         for (int t = tb; t < te; t += 2) {
;             const bool last = (t == nt - 2);
;             const char* a1 = cA + (size_t)(t + 1) * kstep;
;             const char* a2 = last ? nA : cA + (size_t)(t + 2) * kstep; const char* b2 = last ? nB : cB + (size_t)(t + 2) * kstep;
;             const char* a3 = a2 + kstep; const char* b3 = b2 + kstep;
;             if (last && has_next) S.a_ready(nxt);
;             PG8_LDB(B0, 0, 0); PG8_LDB(B1, 0, 1); PG8_SCHED; PG8_LDA(At, 0, 0); PG8_STAGE(PG8_SA(1, 1), a1 + hA, voffA);
;             PG8_WAIT_V(8); PG8_WAIT_L(0); PG8_BAR; PG8_MMA(0, 0, At, B0); PG8_MMA(0, 1, At, B1); PG8_BAR; PG8_SCHED;
;             PG8_LDA(At, 0, 1); PG8_STAGE(PG8_SB(0, 0), b2, voffB); PG8_STAGE(PG8_SB(0, 1), b2 + hB, voffB); PG8_STAGE(PG8_SA(0, 0), a2, voffA);
;             PG8_WAIT_V(8); PG8_WAIT_L(0); PG8_BAR; PG8_MMA(1, 0, At, B0); PG8_MMA(1, 1, At, B1); PG8_BAR; PG8_SCHED;
.LBB0_896:
	ds_read_b128 v[146:149], v140
	ds_read_b128 v[150:153], v140 offset:1024
	ds_read_b128 v[154:157], v140 offset:2048
	ds_read_b128 v[158:161], v140 offset:3072
	ds_read_b128 v[162:165], v141
	ds_read_b128 v[166:169], v141 offset:1024
	ds_read_b128 v[170:173], v141 offset:2048
	ds_read_b128 v[174:177], v141 offset:3072
	s_add_u32 s10, s6, 0x87c00080
	s_addc_u32 s11, s7, -1
	s_cmp_lg_u32 s18, 60
	s_cselect_b32 s10, s10, 0
	s_cselect_b32 s11, s11, 0
	s_add_u32 s16, s2, s10
	s_addc_u32 s17, s3, s11
	s_add_u32 s10, s14, s10
	s_addc_u32 s11, s15, s11
	s_mov_b32 m0, s19
	v_lshl_add_u64 v[178:179], v[136:137], 0, s[6:7]
	ds_read_b128 v[186:189], v142
	ds_read_b128 v[190:193], v142 offset:1024
	ds_read_b128 v[194:197], v142 offset:2048
	ds_read_b128 v[198:201], v142 offset:3072
	ds_read_b128 v[202:205], v142 offset:4096
	ds_read_b128 v[206:209], v142 offset:5120
	ds_read_b128 v[210:213], v142 offset:6144
	ds_read_b128 v[214:217], v142 offset:7168
	global_load_lds_dwordx4 v[178:179], off
	v_lshl_add_u64 v[178:179], v[138:139], 0, s[6:7]
	s_mov_b32 m0, s31
	s_nop 0
	global_load_lds_dwordx4 v[178:179], off
	s_waitcnt vmcnt(8)
	s_waitcnt lgkmcnt(0)
	s_barrier
	s_setprio 1
	s_waitcnt lgkmcnt(0)
	v_mfma_f32_16x16x32_bf16 v[54:57], v[146:149], v[186:189], v[54:57]
	v_mfma_f32_16x16x32_bf16 v[34:37], v[154:157], v[186:189], v[34:37]
	v_mfma_f32_16x16x32_bf16 v[42:45], v[146:149], v[194:197], v[42:45]
	v_mfma_f32_16x16x32_bf16 v[30:33], v[154:157], v[194:197], v[30:33]
	v_mfma_f32_16x16x32_bf16 v[62:65], v[146:149], v[202:205], v[62:65]
	v_mfma_f32_16x16x32_bf16 v[50:53], v[154:157], v[202:205], v[50:53]
	v_mfma_f32_16x16x32_bf16 v[78:81], v[146:149], v[210:213], v[78:81]
	v_mfma_f32_16x16x32_bf16 v[70:73], v[154:157], v[210:213], v[70:73]
	v_mfma_f32_16x16x32_bf16 v[54:57], v[150:153], v[190:193], v[54:57]
	v_mfma_f32_16x16x32_bf16 v[34:37], v[158:161], v[190:193], v[34:37]
	v_mfma_f32_16x16x32_bf16 v[42:45], v[150:153], v[198:201], v[42:45]
	v_mfma_f32_16x16x32_bf16 v[30:33], v[158:161], v[198:201], v[30:33]
	v_mfma_f32_16x16x32_bf16 v[62:65], v[150:153], v[206:209], v[62:65]
	v_mfma_f32_16x16x32_bf16 v[50:53], v[158:161], v[206:209], v[50:53]
	v_mfma_f32_16x16x32_bf16 v[78:81], v[150:153], v[214:217], v[78:81]
	v_mfma_f32_16x16x32_bf16 v[70:73], v[158:161], v[214:217], v[70:73]
	s_setprio 0
	s_setprio 1
	v_mfma_f32_16x16x32_bf16 v[10:13], v[162:165], v[186:189], v[10:13]
	v_mfma_f32_16x16x32_bf16 v[2:5], v[170:173], v[186:189], v[2:5]
	v_mfma_f32_16x16x32_bf16 v[14:17], v[162:165], v[194:197], v[14:17]
	v_mfma_f32_16x16x32_bf16 v[6:9], v[170:173], v[194:197], v[6:9]
	v_mfma_f32_16x16x32_bf16 v[22:25], v[162:165], v[202:205], v[22:25]
	v_mfma_f32_16x16x32_bf16 v[18:21], v[170:173], v[202:205], v[18:21]
	v_mfma_f32_16x16x32_bf16 v[38:41], v[162:165], v[210:213], v[38:41]
	v_mfma_f32_16x16x32_bf16 v[26:29], v[170:173], v[210:213], v[26:29]
	v_mfma_f32_16x16x32_bf16 v[10:13], v[166:169], v[190:193], v[10:13]
	v_mfma_f32_16x16x32_bf16 v[2:5], v[174:177], v[190:193], v[2:5]
	v_mfma_f32_16x16x32_bf16 v[14:17], v[166:169], v[198:201], v[14:17]
	v_mfma_f32_16x16x32_bf16 v[6:9], v[174:177], v[198:201], v[6:9]
	v_mfma_f32_16x16x32_bf16 v[22:25], v[166:169], v[206:209], v[22:25]
	v_mfma_f32_16x16x32_bf16 v[18:21], v[174:177], v[206:209], v[18:21]
	v_mfma_f32_16x16x32_bf16 v[38:41], v[166:169], v[214:217], v[38:41]
	v_mfma_f32_16x16x32_bf16 v[26:29], v[174:177], v[214:217], v[26:29]
	s_setprio 0
	s_barrier
	s_mov_b32 m0, s33
	s_add_u32 s46, s10, 0x100000
	ds_read_b128 v[186:189], v142 offset:16384
	ds_read_b128 v[190:193], v142 offset:17408
	ds_read_b128 v[194:197], v142 offset:18432
	ds_read_b128 v[198:201], v142 offset:19456
	ds_read_b128 v[202:205], v142 offset:20480
	ds_read_b128 v[206:209], v142 offset:21504
	ds_read_b128 v[210:213], v142 offset:22528
	ds_read_b128 v[214:217], v142 offset:23552
	global_load_lds_dwordx4 v180, s[10:11]
	s_mov_b32 m0, s34
	s_addc_u32 s47, s11, 0
	global_load_lds_dwordx4 v134, s[10:11]
	s_mov_b32 m0, s35
	s_nop 0
	global_load_lds_dwordx4 v180, s[46:47]
	s_mov_b32 m0, s42
	s_nop 0
	global_load_lds_dwordx4 v134, s[46:47]
	s_add_u32 s50, s16, s4
	s_addc_u32 s51, s17, s5
	s_mov_b32 m0, s27
	s_nop 0
	global_load_lds_dwordx4 v130, s[16:17]
	s_mov_b32 m0, s28
	s_nop 0
	global_load_lds_dwordx4 v132, s[16:17]
	s_waitcnt vmcnt(8)
	s_waitcnt lgkmcnt(0)
	s_barrier
	s_setprio 1
	s_waitcnt lgkmcnt(0)
	v_mfma_f32_16x16x32_bf16 v[94:97], v[146:149], v[186:189], v[94:97]
	v_mfma_f32_16x16x32_bf16 v[86:89], v[154:157], v[186:189], v[86:89]
	v_mfma_f32_16x16x32_bf16 v[102:105], v[146:149], v[194:197], v[102:105]
	v_mfma_f32_16x16x32_bf16 v[98:101], v[154:157], v[194:197], v[98:101]
	v_mfma_f32_16x16x32_bf16 v[110:113], v[146:149], v[202:205], v[110:113]
	v_mfma_f32_16x16x32_bf16 v[106:109], v[154:157], v[202:205], v[106:109]
	v_mfma_f32_16x16x32_bf16 v[126:129], v[146:149], v[210:213], v[126:129]
	v_mfma_f32_16x16x32_bf16 v[122:125], v[154:157], v[210:213], v[122:125]
	v_mfma_f32_16x16x32_bf16 v[94:97], v[150:153], v[190:193], v[94:97]
	v_mfma_f32_16x16x32_bf16 v[86:89], v[158:161], v[190:193], v[86:89]
	v_mfma_f32_16x16x32_bf16 v[102:105], v[150:153], v[198:201], v[102:105]
	v_mfma_f32_16x16x32_bf16 v[98:101], v[158:161], v[198:201], v[98:101]
	v_mfma_f32_16x16x32_bf16 v[110:113], v[150:153], v[206:209], v[110:113]
	v_mfma_f32_16x16x32_bf16 v[106:109], v[158:161], v[206:209], v[106:109]
	v_mfma_f32_16x16x32_bf16 v[126:129], v[150:153], v[214:217], v[126:129]
	v_mfma_f32_16x16x32_bf16 v[122:125], v[158:161], v[214:217], v[122:125]
	s_setprio 0
	s_setprio 1
	v_mfma_f32_16x16x32_bf16 v[58:61], v[162:165], v[186:189], v[58:61]
	v_mfma_f32_16x16x32_bf16 v[46:49], v[170:173], v[186:189], v[46:49]
	v_mfma_f32_16x16x32_bf16 v[74:77], v[162:165], v[194:197], v[74:77]
	v_mfma_f32_16x16x32_bf16 v[66:69], v[170:173], v[194:197], v[66:69]
	v_mfma_f32_16x16x32_bf16 v[90:93], v[162:165], v[202:205], v[90:93]
	v_mfma_f32_16x16x32_bf16 v[82:85], v[170:173], v[202:205], v[82:85]
	v_mfma_f32_16x16x32_bf16 v[118:121], v[162:165], v[210:213], v[118:121]
	v_mfma_f32_16x16x32_bf16 v[114:117], v[170:173], v[210:213], v[114:117]
	v_mfma_f32_16x16x32_bf16 v[58:61], v[166:169], v[190:193], v[58:61]
	v_mfma_f32_16x16x32_bf16 v[46:49], v[174:177], v[190:193], v[46:49]
	v_mfma_f32_16x16x32_bf16 v[74:77], v[166:169], v[198:201], v[74:77]
	v_mfma_f32_16x16x32_bf16 v[66:69], v[174:177], v[198:201], v[66:69]
	v_mfma_f32_16x16x32_bf16 v[90:93], v[166:169], v[206:209], v[90:93]
	v_mfma_f32_16x16x32_bf16 v[82:85], v[174:177], v[206:209], v[82:85]
	v_mfma_f32_16x16x32_bf16 v[118:121], v[166:169], v[214:217], v[118:121]
	v_mfma_f32_16x16x32_bf16 v[114:117], v[174:177], v[214:217], v[114:117]
	s_setprio 0
	s_barrier
; #define PG8_STAGE(bufoff, gbase, voff) do { _Pragma("unroll") for (int _i = 0; _i < 2; ++_i) \
;         __builtin_amdgcn_global_load_lds((const unsigned*)((const char*)(gbase) + (voff)[_i]), (LAS unsigned*)(lds + (bufoff) + ldsw + _i * 8192), 16, 0, 0); } while (0)
; #define PG8_LDA(dst, b, h) do { _Pragma("unroll") for (int m = 0; m < 4; ++m) _Pragma("unroll") for (int k = 0; k < 2; ++k) dst[m][k] = *(const LAS bf16x8*)(lds + PG8_SA(b, h) + aoff + m * 2048 + k * 1024); } while (0)
; #define PG8_LDB(dst, b, h) do { _Pragma("unroll") for (int n = 0; n < 2; ++n) _Pragma("unroll") for (int k = 0; k < 2; ++k) dst[n][k] = *(const LAS bf16x8*)(lds + PG8_SB(b, h) + boff + n * 2048 + k * 1024); } while (0)
; #define PG8_MMA(ai, bj, At, Bt) do { __builtin_amdgcn_s_setprio(1); _Pragma("unroll") for (int m = 0; m < 4; ++m) _Pragma("unroll") for (int n = 0; n < 2; ++n) _Pragma("unroll") for (int k = 0; k < 2; ++k) \
;         acc[ai][bj][m][n] = __builtin_amdgcn_mfma_f32_16x16x32_bf16(Bt[n][k], At[m][k], acc[ai][bj][m][n], 0, 0, 0); __builtin_amdgcn_s_setprio(0); } while (0)
; #define PG8_WAIT_V(n) asm volatile("s_waitcnt vmcnt(" #n ")" ::: "memory")
; #define PG8_WAIT_L(n) asm volatile("s_waitcnt lgkmcnt(" #n ")" ::: "memory")
; #define PG8_BAR __builtin_amdgcn_s_barrier()
; #define PG8_SCHED __builtin_amdgcn_sched_barrier(0)
; template <class Epi, class Sched, bool ALIGN_EPI, class Hook = NoHook>
; __device__ __forceinline__ void gemm_phase(LAS unsigned char* lds, const Gemm g, const Sched& S, const Epi& E, const Hook& H = Hook()) {
;     ...
;             PG8_LDB(B0, 1, 0); PG8_LDB(B1, 1, 1); PG8_SCHED; PG8_LDA(At, 1, 0); PG8_STAGE(PG8_SA(0, 1), a2 + hA, voffA);
;             PG8_WAIT_V(8); PG8_WAIT_L(0); PG8_BAR; PG8_MMA(0, 0, At, B0); PG8_MMA(0, 1, At, B1); PG8_BAR; PG8_SCHED;
;             PG8_LDA(At, 1, 1); PG8_STAGE(PG8_SB(1, 0), b3, voffB); PG8_STAGE(PG8_SB(1, 1), b3 + hB, voffB); PG8_STAGE(PG8_SA(1, 0), a3, voffA);
;             PG8_WAIT_V(8); PG8_WAIT_L(0); PG8_BAR; PG8_MMA(1, 0, At, B0); PG8_MMA(1, 1, At, B1); PG8_BAR; PG8_SCHED;
;         }
	ds_read_b128 v[146:149], v143
	ds_read_b128 v[150:153], v143 offset:1024
	ds_read_b128 v[154:157], v143 offset:2048
	ds_read_b128 v[158:161], v143 offset:3072
	ds_read_b128 v[162:165], v144
	ds_read_b128 v[166:169], v144 offset:1024
	ds_read_b128 v[170:173], v144 offset:2048
	ds_read_b128 v[174:177], v144 offset:3072
	s_add_u32 s16, s16, 0x100000
	s_addc_u32 s17, s17, 0
	s_mov_b32 m0, s29
	ds_read_b128 v[186:189], v142 offset:32768
	ds_read_b128 v[190:193], v142 offset:33792
	ds_read_b128 v[194:197], v142 offset:34816
	ds_read_b128 v[198:201], v142 offset:35840
	ds_read_b128 v[202:205], v142 offset:36864
	ds_read_b128 v[206:209], v142 offset:37888
	ds_read_b128 v[210:213], v142 offset:38912
	ds_read_b128 v[214:217], v142 offset:39936
	global_load_lds_dwordx4 v130, s[16:17]
	s_mov_b32 m0, s39
	s_nop 0
	global_load_lds_dwordx4 v132, s[16:17]
	s_waitcnt vmcnt(8)
	s_waitcnt lgkmcnt(0)
	s_barrier
	s_setprio 1
	s_waitcnt lgkmcnt(0)
	v_mfma_f32_16x16x32_bf16 v[54:57], v[146:149], v[186:189], v[54:57]
	v_mfma_f32_16x16x32_bf16 v[34:37], v[154:157], v[186:189], v[34:37]
	v_mfma_f32_16x16x32_bf16 v[42:45], v[146:149], v[194:197], v[42:45]
	v_mfma_f32_16x16x32_bf16 v[30:33], v[154:157], v[194:197], v[30:33]
	v_mfma_f32_16x16x32_bf16 v[62:65], v[146:149], v[202:205], v[62:65]
	v_mfma_f32_16x16x32_bf16 v[50:53], v[154:157], v[202:205], v[50:53]
	v_mfma_f32_16x16x32_bf16 v[78:81], v[146:149], v[210:213], v[78:81]
	v_mfma_f32_16x16x32_bf16 v[70:73], v[154:157], v[210:213], v[70:73]
	v_mfma_f32_16x16x32_bf16 v[54:57], v[150:153], v[190:193], v[54:57]
	v_mfma_f32_16x16x32_bf16 v[34:37], v[158:161], v[190:193], v[34:37]
	v_mfma_f32_16x16x32_bf16 v[42:45], v[150:153], v[198:201], v[42:45]
	v_mfma_f32_16x16x32_bf16 v[30:33], v[158:161], v[198:201], v[30:33]
	v_mfma_f32_16x16x32_bf16 v[62:65], v[150:153], v[206:209], v[62:65]
	v_mfma_f32_16x16x32_bf16 v[50:53], v[158:161], v[206:209], v[50:53]
	v_mfma_f32_16x16x32_bf16 v[78:81], v[150:153], v[214:217], v[78:81]
	v_mfma_f32_16x16x32_bf16 v[70:73], v[158:161], v[214:217], v[70:73]
	s_setprio 0
	s_setprio 1
	v_mfma_f32_16x16x32_bf16 v[10:13], v[162:165], v[186:189], v[10:13]
	v_mfma_f32_16x16x32_bf16 v[2:5], v[170:173], v[186:189], v[2:5]
	v_mfma_f32_16x16x32_bf16 v[14:17], v[162:165], v[194:197], v[14:17]
	v_mfma_f32_16x16x32_bf16 v[6:9], v[170:173], v[194:197], v[6:9]
	v_mfma_f32_16x16x32_bf16 v[22:25], v[162:165], v[202:205], v[22:25]
	v_mfma_f32_16x16x32_bf16 v[18:21], v[170:173], v[202:205], v[18:21]
	v_mfma_f32_16x16x32_bf16 v[38:41], v[162:165], v[210:213], v[38:41]
	v_mfma_f32_16x16x32_bf16 v[26:29], v[170:173], v[210:213], v[26:29]
	v_mfma_f32_16x16x32_bf16 v[10:13], v[166:169], v[190:193], v[10:13]
	v_mfma_f32_16x16x32_bf16 v[2:5], v[174:177], v[190:193], v[2:5]
	v_mfma_f32_16x16x32_bf16 v[14:17], v[166:169], v[198:201], v[14:17]
	v_mfma_f32_16x16x32_bf16 v[6:9], v[174:177], v[198:201], v[6:9]
	v_mfma_f32_16x16x32_bf16 v[22:25], v[166:169], v[206:209], v[22:25]
	v_mfma_f32_16x16x32_bf16 v[18:21], v[174:177], v[206:209], v[18:21]
	v_mfma_f32_16x16x32_bf16 v[38:41], v[166:169], v[214:217], v[38:41]
	v_mfma_f32_16x16x32_bf16 v[26:29], v[174:177], v[214:217], v[26:29]
	s_setprio 0
	s_barrier
	s_mov_b32 m0, s36
	s_add_u32 s48, s10, s4
	s_addc_u32 s49, s11, s5
	s_add_u32 s10, s10, 0x100080
	ds_read_b128 v[186:189], v142 offset:49152
	ds_read_b128 v[190:193], v142 offset:50176
	ds_read_b128 v[194:197], v142 offset:51200
	ds_read_b128 v[198:201], v142 offset:52224
	ds_read_b128 v[202:205], v142 offset:53248
	ds_read_b128 v[206:209], v142 offset:54272
	ds_read_b128 v[210:213], v142 offset:55296
	ds_read_b128 v[214:217], v142 offset:56320
	global_load_lds_dwordx4 v180, s[48:49]
	s_mov_b32 m0, s43
	s_addc_u32 s11, s11, 0
	global_load_lds_dwordx4 v134, s[48:49]
	s_mov_b32 m0, s37
	s_nop 0
	global_load_lds_dwordx4 v180, s[10:11]
	s_mov_b32 m0, s44
	s_nop 0
	global_load_lds_dwordx4 v134, s[10:11]
	s_mov_b32 m0, s40
	s_nop 0
	global_load_lds_dwordx4 v130, s[50:51]
	s_mov_b32 m0, s41
	s_nop 0
	global_load_lds_dwordx4 v132, s[50:51]
	s_waitcnt vmcnt(8)
	s_waitcnt lgkmcnt(0)
	s_barrier
	s_setprio 1
	s_waitcnt lgkmcnt(0)
	v_mfma_f32_16x16x32_bf16 v[94:97], v[146:149], v[186:189], v[94:97]
	v_mfma_f32_16x16x32_bf16 v[86:89], v[154:157], v[186:189], v[86:89]
	v_mfma_f32_16x16x32_bf16 v[102:105], v[146:149], v[194:197], v[102:105]
	v_mfma_f32_16x16x32_bf16 v[98:101], v[154:157], v[194:197], v[98:101]
	v_mfma_f32_16x16x32_bf16 v[110:113], v[146:149], v[202:205], v[110:113]
	v_mfma_f32_16x16x32_bf16 v[106:109], v[154:157], v[202:205], v[106:109]
	v_mfma_f32_16x16x32_bf16 v[126:129], v[146:149], v[210:213], v[126:129]
	v_mfma_f32_16x16x32_bf16 v[122:125], v[154:157], v[210:213], v[122:125]
	v_mfma_f32_16x16x32_bf16 v[94:97], v[150:153], v[190:193], v[94:97]
	v_mfma_f32_16x16x32_bf16 v[86:89], v[158:161], v[190:193], v[86:89]
	v_mfma_f32_16x16x32_bf16 v[102:105], v[150:153], v[198:201], v[102:105]
	v_mfma_f32_16x16x32_bf16 v[98:101], v[158:161], v[198:201], v[98:101]
	v_mfma_f32_16x16x32_bf16 v[110:113], v[150:153], v[206:209], v[110:113]
	v_mfma_f32_16x16x32_bf16 v[106:109], v[158:161], v[206:209], v[106:109]
	v_mfma_f32_16x16x32_bf16 v[126:129], v[150:153], v[214:217], v[126:129]
	v_mfma_f32_16x16x32_bf16 v[122:125], v[158:161], v[214:217], v[122:125]
	s_setprio 0
	s_setprio 1
	v_mfma_f32_16x16x32_bf16 v[58:61], v[162:165], v[186:189], v[58:61]
	v_mfma_f32_16x16x32_bf16 v[46:49], v[170:173], v[186:189], v[46:49]
	v_mfma_f32_16x16x32_bf16 v[74:77], v[162:165], v[194:197], v[74:77]
	v_mfma_f32_16x16x32_bf16 v[66:69], v[170:173], v[194:197], v[66:69]
	v_mfma_f32_16x16x32_bf16 v[90:93], v[162:165], v[202:205], v[90:93]
	v_mfma_f32_16x16x32_bf16 v[82:85], v[170:173], v[202:205], v[82:85]
	v_mfma_f32_16x16x32_bf16 v[118:121], v[162:165], v[210:213], v[118:121]
	v_mfma_f32_16x16x32_bf16 v[114:117], v[170:173], v[210:213], v[114:117]
	v_mfma_f32_16x16x32_bf16 v[58:61], v[166:169], v[190:193], v[58:61]
	v_mfma_f32_16x16x32_bf16 v[46:49], v[174:177], v[190:193], v[46:49]
	v_mfma_f32_16x16x32_bf16 v[74:77], v[166:169], v[198:201], v[74:77]
	v_mfma_f32_16x16x32_bf16 v[66:69], v[174:177], v[198:201], v[66:69]
	v_mfma_f32_16x16x32_bf16 v[90:93], v[166:169], v[206:209], v[90:93]
	v_mfma_f32_16x16x32_bf16 v[82:85], v[174:177], v[206:209], v[82:85]
	v_mfma_f32_16x16x32_bf16 v[118:121], v[166:169], v[214:217], v[118:121]
	v_mfma_f32_16x16x32_bf16 v[114:117], v[174:177], v[214:217], v[114:117]
	s_setprio 0
	s_barrier
	s_add_i32 s18, s18, 2
	s_add_u32 s6, s6, 0x100
	s_addc_u32 s7, s7, 0
	s_cmp_gt_u32 s18, 61
	s_cbranch_scc0 .LBB0_896
	s_cmpk_lt_u32 s22, 0x100
	s_cbranch_scc0 .LBB0_899
	s_barrier

; #define PG8_STAGE(bufoff, gbase, voff) do { _Pragma("unroll") for (int _i = 0; _i < 2; ++_i) \
;         __builtin_amdgcn_global_load_lds((const unsigned*)((const char*)(gbase) + (voff)[_i]), (LAS unsigned*)(lds + (bufoff) + ldsw + _i * 8192), 16, 0, 0); } while (0)
; #define PG8_LDA(dst, b, h) do { _Pragma("unroll") for (int m = 0; m < 4; ++m) _Pragma("unroll") for (int k = 0; k < 2; ++k) dst[m][k] = *(const LAS bf16x8*)(lds + PG8_SA(b, h) + aoff + m * 2048 + k * 1024); } while (0)
; #define PG8_LDB(dst, b, h) do { _Pragma("unroll") for (int n = 0; n < 2; ++n) _Pragma("unroll") for (int k = 0; k < 2; ++k) dst[n][k] = *(const LAS bf16x8*)(lds + PG8_SB(b, h) + boff + n * 2048 + k * 1024); } while (0)
; #define PG8_MMA(ai, bj, At, Bt) do { __builtin_amdgcn_s_setprio(1); _Pragma("unroll") for (int m = 0; m < 4; ++m) _Pragma("unroll") for (int n = 0; n < 2; ++n) _Pragma("unroll") for (int k = 0; k < 2; ++k) \
;         acc[ai][bj][m][n] = __builtin_amdgcn_mfma_f32_16x16x32_bf16(Bt[n][k], At[m][k], acc[ai][bj][m][n], 0, 0, 0); __builtin_amdgcn_s_setprio(0); } while (0)
; #define PG8_WAIT_V(n) asm volatile("s_waitcnt vmcnt(" #n ")" ::: "memory")
; #define PG8_WAIT_L(n) asm volatile("s_waitcnt lgkmcnt(" #n ")" ::: "memory")
; template <class Epi, class Sched, bool ALIGN_EPI, class Hook = NoHook>
; __device__ __forceinline__ void gemm_phase(LAS unsigned char* lds, const Gemm g, const Sched& S, const Epi& E, const Hook& H = Hook()) {
;     ...
;         for (int t = tb; t < te; t += 2) {
;             const bool last = (t == nt - 2);
;             const char* a1 = cA + (size_t)(t + 1) * kstep;
;             const char* a2 = last ? nA : cA + (size_t)(t + 2) * kstep; const char* b2 = last ? nB : cB + (size_t)(t + 2) * kstep;
;             const char* a3 = a2 + kstep; const char* b3 = b2 + kstep;
;             if (last && has_next) S.a_ready(nxt);
;             PG8_LDB(B0, 0, 0); PG8_LDB(B1, 0, 1); PG8_SCHED; PG8_LDA(At, 0, 0); PG8_STAGE(PG8_SA(1, 1), a1 + hA, voffA);
;             PG8_WAIT_V(8); PG8_WAIT_L(0); PG8_BAR; PG8_MMA(0, 0, At, B0); PG8_MMA(0, 1, At, B1); PG8_BAR; PG8_SCHED;
;             PG8_LDA(At, 0, 1); PG8_STAGE(PG8_SB(0, 0), b2, voffB); PG8_STAGE(PG8_SB(0, 1), b2 + hB, voffB); PG8_STAGE(PG8_SA(0, 0), a2, voffA);
;             PG8_WAIT_V(8); PG8_WAIT_L(0); PG8_BAR; PG8_MMA(1, 0, At, B0); PG8_MMA(1, 1, At, B1); PG8_BAR; PG8_SCHED;
.LBB0_1360:
	ds_read_b128 v[146:149], v1
	ds_read_b128 v[150:153], v1 offset:1024
	ds_read_b128 v[154:157], v1 offset:2048
	ds_read_b128 v[158:161], v1 offset:3072
	ds_read_b128 v[164:167], v142
	ds_read_b128 v[170:173], v142 offset:1024
	ds_read_b128 v[174:177], v142 offset:2048
	ds_read_b128 v[178:181], v142 offset:3072
	s_add_u32 s14, s4, 0xbb050080
	s_addc_u32 s15, s5, -1
	s_cmpk_lg_i32 s41, 0xa8
	s_cselect_b32 s14, s14, 0
	s_cselect_b32 s15, s15, 0
	s_add_u32 s20, s0, s14
	s_addc_u32 s21, s1, s15
	s_add_u32 s14, s12, s14
	s_addc_u32 s15, s13, s15
	s_mov_b32 m0, s42
	v_lshl_add_u64 v[214:215], v[138:139], 0, s[4:5]
	ds_read_b128 v[182:185], v143
	ds_read_b128 v[186:189], v143 offset:1024
	ds_read_b128 v[190:193], v143 offset:2048
	ds_read_b128 v[194:197], v143 offset:3072
	ds_read_b128 v[198:201], v143 offset:4096
	ds_read_b128 v[202:205], v143 offset:5120
	ds_read_b128 v[206:209], v143 offset:6144
	ds_read_b128 v[210:213], v143 offset:7168
	global_load_lds_dwordx4 v[214:215], off
	v_lshl_add_u64 v[214:215], v[140:141], 0, s[4:5]
	s_mov_b32 m0, s43
	s_nop 0
	global_load_lds_dwordx4 v[214:215], off
	s_waitcnt vmcnt(8)
	s_waitcnt lgkmcnt(0)
	s_barrier
	s_setprio 1
	s_waitcnt lgkmcnt(0)
	v_mfma_f32_16x16x32_bf16 v[82:85], v[146:149], v[182:185], v[82:85]
	v_mfma_f32_16x16x32_bf16 v[54:57], v[154:157], v[182:185], v[54:57]
	v_mfma_f32_16x16x32_bf16 v[58:61], v[146:149], v[190:193], v[58:61]
	v_mfma_f32_16x16x32_bf16 v[42:45], v[154:157], v[190:193], v[42:45]
	v_mfma_f32_16x16x32_bf16 v[70:73], v[146:149], v[198:201], v[70:73]
	v_mfma_f32_16x16x32_bf16 v[50:53], v[154:157], v[198:201], v[50:53]
	v_mfma_f32_16x16x32_bf16 v[86:89], v[146:149], v[206:209], v[86:89]
	v_mfma_f32_16x16x32_bf16 v[74:77], v[154:157], v[206:209], v[74:77]
	v_mfma_f32_16x16x32_bf16 v[82:85], v[150:153], v[186:189], v[82:85]
	v_mfma_f32_16x16x32_bf16 v[54:57], v[158:161], v[186:189], v[54:57]
	v_mfma_f32_16x16x32_bf16 v[58:61], v[150:153], v[194:197], v[58:61]
	v_mfma_f32_16x16x32_bf16 v[42:45], v[158:161], v[194:197], v[42:45]
	v_mfma_f32_16x16x32_bf16 v[70:73], v[150:153], v[202:205], v[70:73]
	v_mfma_f32_16x16x32_bf16 v[50:53], v[158:161], v[202:205], v[50:53]
	v_mfma_f32_16x16x32_bf16 v[86:89], v[150:153], v[210:213], v[86:89]
	v_mfma_f32_16x16x32_bf16 v[74:77], v[158:161], v[210:213], v[74:77]
	s_setprio 0
	s_setprio 1
	v_mfma_f32_16x16x32_bf16 v[14:17], v[164:167], v[182:185], v[14:17]
	v_mfma_f32_16x16x32_bf16 v[2:5], v[174:177], v[182:185], v[2:5]
	v_mfma_f32_16x16x32_bf16 v[18:21], v[164:167], v[190:193], v[18:21]
	v_mfma_f32_16x16x32_bf16 v[6:9], v[174:177], v[190:193], v[6:9]
	v_mfma_f32_16x16x32_bf16 v[22:25], v[164:167], v[198:201], v[22:25]
	v_mfma_f32_16x16x32_bf16 v[10:13], v[174:177], v[198:201], v[10:13]
	v_mfma_f32_16x16x32_bf16 v[30:33], v[164:167], v[206:209], v[30:33]
	v_mfma_f32_16x16x32_bf16 v[26:29], v[174:177], v[206:209], v[26:29]
	v_mfma_f32_16x16x32_bf16 v[14:17], v[170:173], v[186:189], v[14:17]
	v_mfma_f32_16x16x32_bf16 v[2:5], v[178:181], v[186:189], v[2:5]
	v_mfma_f32_16x16x32_bf16 v[18:21], v[170:173], v[194:197], v[18:21]
	v_mfma_f32_16x16x32_bf16 v[6:9], v[178:181], v[194:197], v[6:9]
	v_mfma_f32_16x16x32_bf16 v[22:25], v[170:173], v[202:205], v[22:25]
	v_mfma_f32_16x16x32_bf16 v[10:13], v[178:181], v[202:205], v[10:13]
	v_mfma_f32_16x16x32_bf16 v[30:33], v[170:173], v[210:213], v[30:33]
	v_mfma_f32_16x16x32_bf16 v[26:29], v[178:181], v[210:213], v[26:29]
	s_setprio 0
	s_barrier
	s_mov_b32 m0, s44
	s_add_u32 s52, s14, 0x2b0000
	ds_read_b128 v[182:185], v143 offset:16384
	ds_read_b128 v[186:189], v143 offset:17408
	ds_read_b128 v[190:193], v143 offset:18432
	ds_read_b128 v[194:197], v143 offset:19456
	ds_read_b128 v[198:201], v143 offset:20480
	ds_read_b128 v[202:205], v143 offset:21504
	ds_read_b128 v[206:209], v143 offset:22528
	ds_read_b128 v[210:213], v143 offset:23552
	global_load_lds_dwordx4 v132, s[14:15]
	s_mov_b32 m0, s45
	s_addc_u32 s53, s15, 0
	global_load_lds_dwordx4 v136, s[14:15]
	s_mov_b32 m0, s46
	s_nop 0
	global_load_lds_dwordx4 v132, s[52:53]
	s_mov_b32 m0, s47
	s_nop 0
	global_load_lds_dwordx4 v136, s[52:53]
	s_add_u32 s56, s20, s2
	s_addc_u32 s57, s21, s3
	s_mov_b32 m0, s25
	s_nop 0
	global_load_lds_dwordx4 v130, s[20:21]
	s_mov_b32 m0, s27
	s_nop 0
	global_load_lds_dwordx4 v134, s[20:21]
	s_waitcnt vmcnt(8)
	s_waitcnt lgkmcnt(0)
	s_barrier
	s_setprio 1
	s_waitcnt lgkmcnt(0)
	v_mfma_f32_16x16x32_bf16 v[94:97], v[146:149], v[182:185], v[94:97]
	v_mfma_f32_16x16x32_bf16 v[90:93], v[154:157], v[182:185], v[90:93]
	v_mfma_f32_16x16x32_bf16 v[106:109], v[146:149], v[190:193], v[106:109]
	v_mfma_f32_16x16x32_bf16 v[98:101], v[154:157], v[190:193], v[98:101]
	v_mfma_f32_16x16x32_bf16 v[110:113], v[146:149], v[198:201], v[110:113]
	v_mfma_f32_16x16x32_bf16 v[102:105], v[154:157], v[198:201], v[102:105]
	v_mfma_f32_16x16x32_bf16 v[126:129], v[146:149], v[206:209], v[126:129]
	v_mfma_f32_16x16x32_bf16 v[122:125], v[154:157], v[206:209], v[122:125]
	v_mfma_f32_16x16x32_bf16 v[94:97], v[150:153], v[186:189], v[94:97]
	v_mfma_f32_16x16x32_bf16 v[90:93], v[158:161], v[186:189], v[90:93]
	v_mfma_f32_16x16x32_bf16 v[106:109], v[150:153], v[194:197], v[106:109]
	v_mfma_f32_16x16x32_bf16 v[98:101], v[158:161], v[194:197], v[98:101]
	v_mfma_f32_16x16x32_bf16 v[110:113], v[150:153], v[202:205], v[110:113]
	v_mfma_f32_16x16x32_bf16 v[102:105], v[158:161], v[202:205], v[102:105]
	v_mfma_f32_16x16x32_bf16 v[126:129], v[150:153], v[210:213], v[126:129]
	v_mfma_f32_16x16x32_bf16 v[122:125], v[158:161], v[210:213], v[122:125]
	s_setprio 0
	s_setprio 1
	v_mfma_f32_16x16x32_bf16 v[38:41], v[164:167], v[182:185], v[38:41]
	v_mfma_f32_16x16x32_bf16 v[34:37], v[174:177], v[182:185], v[34:37]
	v_mfma_f32_16x16x32_bf16 v[66:69], v[164:167], v[190:193], v[66:69]
	v_mfma_f32_16x16x32_bf16 v[46:49], v[174:177], v[190:193], v[46:49]
	v_mfma_f32_16x16x32_bf16 v[78:81], v[164:167], v[198:201], v[78:81]
	v_mfma_f32_16x16x32_bf16 v[62:65], v[174:177], v[198:201], v[62:65]
	v_mfma_f32_16x16x32_bf16 v[118:121], v[164:167], v[206:209], v[118:121]
	v_mfma_f32_16x16x32_bf16 v[114:117], v[174:177], v[206:209], v[114:117]
	v_mfma_f32_16x16x32_bf16 v[38:41], v[170:173], v[186:189], v[38:41]
	v_mfma_f32_16x16x32_bf16 v[34:37], v[178:181], v[186:189], v[34:37]
	v_mfma_f32_16x16x32_bf16 v[66:69], v[170:173], v[194:197], v[66:69]
	v_mfma_f32_16x16x32_bf16 v[46:49], v[178:181], v[194:197], v[46:49]
	v_mfma_f32_16x16x32_bf16 v[78:81], v[170:173], v[202:205], v[78:81]
	v_mfma_f32_16x16x32_bf16 v[62:65], v[178:181], v[202:205], v[62:65]
	v_mfma_f32_16x16x32_bf16 v[118:121], v[170:173], v[210:213], v[118:121]
	v_mfma_f32_16x16x32_bf16 v[114:117], v[178:181], v[210:213], v[114:117]
	s_setprio 0
	s_barrier
; #define PG8_STAGE(bufoff, gbase, voff) do { _Pragma("unroll") for (int _i = 0; _i < 2; ++_i) \
;         __builtin_amdgcn_global_load_lds((const unsigned*)((const char*)(gbase) + (voff)[_i]), (LAS unsigned*)(lds + (bufoff) + ldsw + _i * 8192), 16, 0, 0); } while (0)
; #define PG8_LDA(dst, b, h) do { _Pragma("unroll") for (int m = 0; m < 4; ++m) _Pragma("unroll") for (int k = 0; k < 2; ++k) dst[m][k] = *(const LAS bf16x8*)(lds + PG8_SA(b, h) + aoff + m * 2048 + k * 1024); } while (0)
; #define PG8_LDB(dst, b, h) do { _Pragma("unroll") for (int n = 0; n < 2; ++n) _Pragma("unroll") for (int k = 0; k < 2; ++k) dst[n][k] = *(const LAS bf16x8*)(lds + PG8_SB(b, h) + boff + n * 2048 + k * 1024); } while (0)
; #define PG8_MMA(ai, bj, At, Bt) do { __builtin_amdgcn_s_setprio(1); _Pragma("unroll") for (int m = 0; m < 4; ++m) _Pragma("unroll") for (int n = 0; n < 2; ++n) _Pragma("unroll") for (int k = 0; k < 2; ++k) \
;         acc[ai][bj][m][n] = __builtin_amdgcn_mfma_f32_16x16x32_bf16(Bt[n][k], At[m][k], acc[ai][bj][m][n], 0, 0, 0); __builtin_amdgcn_s_setprio(0); } while (0)
; #define PG8_WAIT_V(n) asm volatile("s_waitcnt vmcnt(" #n ")" ::: "memory")
; #define PG8_WAIT_L(n) asm volatile("s_waitcnt lgkmcnt(" #n ")" ::: "memory")
; #define PG8_BAR __builtin_amdgcn_s_barrier()
; #define PG8_SCHED __builtin_amdgcn_sched_barrier(0)
; template <class Epi, class Sched, bool ALIGN_EPI, class Hook = NoHook>
; __device__ __forceinline__ void gemm_phase(LAS unsigned char* lds, const Gemm g, const Sched& S, const Epi& E, const Hook& H = Hook()) {
;     ...
;             PG8_LDB(B0, 1, 0); PG8_LDB(B1, 1, 1); PG8_SCHED; PG8_LDA(At, 1, 0); PG8_STAGE(PG8_SA(0, 1), a2 + hA, voffA);
;             PG8_WAIT_V(8); PG8_WAIT_L(0); PG8_BAR; PG8_MMA(0, 0, At, B0); PG8_MMA(0, 1, At, B1); PG8_BAR; PG8_SCHED;
;             PG8_LDA(At, 1, 1); PG8_STAGE(PG8_SB(1, 0), b3, voffB); PG8_STAGE(PG8_SB(1, 1), b3 + hB, voffB); PG8_STAGE(PG8_SA(1, 0), a3, voffA);
;             PG8_WAIT_V(8); PG8_WAIT_L(0); PG8_BAR; PG8_MMA(1, 0, At, B0); PG8_MMA(1, 1, At, B1); PG8_BAR; PG8_SCHED;
;         }
	ds_read_b128 v[146:149], v144
	ds_read_b128 v[150:153], v144 offset:1024
	ds_read_b128 v[154:157], v144 offset:2048
	ds_read_b128 v[158:161], v144 offset:3072
	ds_read_b128 v[164:167], v145
	ds_read_b128 v[170:173], v145 offset:1024
	ds_read_b128 v[174:177], v145 offset:2048
	ds_read_b128 v[178:181], v145 offset:3072
	s_add_u32 s20, s20, 0x2b0000
	s_addc_u32 s21, s21, 0
	s_mov_b32 m0, s28
	ds_read_b128 v[182:185], v143 offset:32768
	ds_read_b128 v[186:189], v143 offset:33792
	ds_read_b128 v[190:193], v143 offset:34816
	ds_read_b128 v[194:197], v143 offset:35840
	ds_read_b128 v[198:201], v143 offset:36864
	ds_read_b128 v[202:205], v143 offset:37888
	ds_read_b128 v[206:209], v143 offset:38912
	ds_read_b128 v[210:213], v143 offset:39936
	global_load_lds_dwordx4 v130, s[20:21]
	s_mov_b32 m0, s38
	s_nop 0
	global_load_lds_dwordx4 v134, s[20:21]
	s_waitcnt vmcnt(8)
	s_waitcnt lgkmcnt(0)
	s_barrier
	s_setprio 1
	s_waitcnt lgkmcnt(0)
	v_mfma_f32_16x16x32_bf16 v[82:85], v[146:149], v[182:185], v[82:85]
	v_mfma_f32_16x16x32_bf16 v[54:57], v[154:157], v[182:185], v[54:57]
	v_mfma_f32_16x16x32_bf16 v[58:61], v[146:149], v[190:193], v[58:61]
	v_mfma_f32_16x16x32_bf16 v[42:45], v[154:157], v[190:193], v[42:45]
	v_mfma_f32_16x16x32_bf16 v[70:73], v[146:149], v[198:201], v[70:73]
	v_mfma_f32_16x16x32_bf16 v[50:53], v[154:157], v[198:201], v[50:53]
	v_mfma_f32_16x16x32_bf16 v[86:89], v[146:149], v[206:209], v[86:89]
	v_mfma_f32_16x16x32_bf16 v[74:77], v[154:157], v[206:209], v[74:77]
	v_mfma_f32_16x16x32_bf16 v[82:85], v[150:153], v[186:189], v[82:85]
	v_mfma_f32_16x16x32_bf16 v[54:57], v[158:161], v[186:189], v[54:57]
	v_mfma_f32_16x16x32_bf16 v[58:61], v[150:153], v[194:197], v[58:61]
	v_mfma_f32_16x16x32_bf16 v[42:45], v[158:161], v[194:197], v[42:45]
	v_mfma_f32_16x16x32_bf16 v[70:73], v[150:153], v[202:205], v[70:73]
	v_mfma_f32_16x16x32_bf16 v[50:53], v[158:161], v[202:205], v[50:53]
	v_mfma_f32_16x16x32_bf16 v[86:89], v[150:153], v[210:213], v[86:89]
	v_mfma_f32_16x16x32_bf16 v[74:77], v[158:161], v[210:213], v[74:77]
	s_setprio 0
	s_setprio 1
	v_mfma_f32_16x16x32_bf16 v[14:17], v[164:167], v[182:185], v[14:17]
	v_mfma_f32_16x16x32_bf16 v[2:5], v[174:177], v[182:185], v[2:5]
	v_mfma_f32_16x16x32_bf16 v[18:21], v[164:167], v[190:193], v[18:21]
	v_mfma_f32_16x16x32_bf16 v[6:9], v[174:177], v[190:193], v[6:9]
	v_mfma_f32_16x16x32_bf16 v[22:25], v[164:167], v[198:201], v[22:25]
	v_mfma_f32_16x16x32_bf16 v[10:13], v[174:177], v[198:201], v[10:13]
	v_mfma_f32_16x16x32_bf16 v[30:33], v[164:167], v[206:209], v[30:33]
	v_mfma_f32_16x16x32_bf16 v[26:29], v[174:177], v[206:209], v[26:29]
	v_mfma_f32_16x16x32_bf16 v[14:17], v[170:173], v[186:189], v[14:17]
	v_mfma_f32_16x16x32_bf16 v[2:5], v[178:181], v[186:189], v[2:5]
	v_mfma_f32_16x16x32_bf16 v[18:21], v[170:173], v[194:197], v[18:21]
	v_mfma_f32_16x16x32_bf16 v[6:9], v[178:181], v[194:197], v[6:9]
	v_mfma_f32_16x16x32_bf16 v[22:25], v[170:173], v[202:205], v[22:25]
	v_mfma_f32_16x16x32_bf16 v[10:13], v[178:181], v[202:205], v[10:13]
	v_mfma_f32_16x16x32_bf16 v[30:33], v[170:173], v[210:213], v[30:33]
	v_mfma_f32_16x16x32_bf16 v[26:29], v[178:181], v[210:213], v[26:29]
	s_setprio 0
	s_barrier
	s_mov_b32 m0, s48
	s_add_u32 s54, s14, s2
	s_addc_u32 s55, s15, s3
	s_add_u32 s14, s14, 0x2b0080
	ds_read_b128 v[182:185], v143 offset:49152
	ds_read_b128 v[186:189], v143 offset:50176
	ds_read_b128 v[190:193], v143 offset:51200
	ds_read_b128 v[194:197], v143 offset:52224
	ds_read_b128 v[198:201], v143 offset:53248
	ds_read_b128 v[202:205], v143 offset:54272
	ds_read_b128 v[206:209], v143 offset:55296
	ds_read_b128 v[210:213], v143 offset:56320
	global_load_lds_dwordx4 v132, s[54:55]
	s_mov_b32 m0, s49
	s_addc_u32 s15, s15, 0
	global_load_lds_dwordx4 v136, s[54:55]
	s_mov_b32 m0, s50
	s_nop 0
	global_load_lds_dwordx4 v132, s[14:15]
	s_mov_b32 m0, s51
	s_nop 0
	global_load_lds_dwordx4 v136, s[14:15]
	s_mov_b32 m0, s39
	s_nop 0
	global_load_lds_dwordx4 v130, s[56:57]
	s_mov_b32 m0, s40
	s_nop 0
	global_load_lds_dwordx4 v134, s[56:57]
	s_waitcnt vmcnt(8)
	s_waitcnt lgkmcnt(0)
	s_barrier
	s_setprio 1
	s_waitcnt lgkmcnt(0)
	v_mfma_f32_16x16x32_bf16 v[94:97], v[146:149], v[182:185], v[94:97]
	v_mfma_f32_16x16x32_bf16 v[90:93], v[154:157], v[182:185], v[90:93]
	v_mfma_f32_16x16x32_bf16 v[106:109], v[146:149], v[190:193], v[106:109]
	v_mfma_f32_16x16x32_bf16 v[98:101], v[154:157], v[190:193], v[98:101]
	v_mfma_f32_16x16x32_bf16 v[110:113], v[146:149], v[198:201], v[110:113]
	v_mfma_f32_16x16x32_bf16 v[102:105], v[154:157], v[198:201], v[102:105]
	v_mfma_f32_16x16x32_bf16 v[126:129], v[146:149], v[206:209], v[126:129]
	v_mfma_f32_16x16x32_bf16 v[122:125], v[154:157], v[206:209], v[122:125]
	v_mfma_f32_16x16x32_bf16 v[94:97], v[150:153], v[186:189], v[94:97]
	v_mfma_f32_16x16x32_bf16 v[90:93], v[158:161], v[186:189], v[90:93]
	v_mfma_f32_16x16x32_bf16 v[106:109], v[150:153], v[194:197], v[106:109]
	v_mfma_f32_16x16x32_bf16 v[98:101], v[158:161], v[194:197], v[98:101]
	v_mfma_f32_16x16x32_bf16 v[110:113], v[150:153], v[202:205], v[110:113]
	v_mfma_f32_16x16x32_bf16 v[102:105], v[158:161], v[202:205], v[102:105]
	v_mfma_f32_16x16x32_bf16 v[126:129], v[150:153], v[210:213], v[126:129]
	v_mfma_f32_16x16x32_bf16 v[122:125], v[158:161], v[210:213], v[122:125]
	s_setprio 0
	s_setprio 1
	v_mfma_f32_16x16x32_bf16 v[38:41], v[164:167], v[182:185], v[38:41]
	v_mfma_f32_16x16x32_bf16 v[34:37], v[174:177], v[182:185], v[34:37]
	v_mfma_f32_16x16x32_bf16 v[66:69], v[164:167], v[190:193], v[66:69]
	v_mfma_f32_16x16x32_bf16 v[46:49], v[174:177], v[190:193], v[46:49]
	v_mfma_f32_16x16x32_bf16 v[78:81], v[164:167], v[198:201], v[78:81]
	v_mfma_f32_16x16x32_bf16 v[62:65], v[174:177], v[198:201], v[62:65]
	v_mfma_f32_16x16x32_bf16 v[118:121], v[164:167], v[206:209], v[118:121]
	v_mfma_f32_16x16x32_bf16 v[114:117], v[174:177], v[206:209], v[114:117]
	v_mfma_f32_16x16x32_bf16 v[38:41], v[170:173], v[186:189], v[38:41]
	v_mfma_f32_16x16x32_bf16 v[34:37], v[178:181], v[186:189], v[34:37]
	v_mfma_f32_16x16x32_bf16 v[66:69], v[170:173], v[194:197], v[66:69]
	v_mfma_f32_16x16x32_bf16 v[46:49], v[178:181], v[194:197], v[46:49]
	v_mfma_f32_16x16x32_bf16 v[78:81], v[170:173], v[202:205], v[78:81]
	v_mfma_f32_16x16x32_bf16 v[62:65], v[178:181], v[202:205], v[62:65]
	v_mfma_f32_16x16x32_bf16 v[118:121], v[170:173], v[210:213], v[118:121]
	v_mfma_f32_16x16x32_bf16 v[114:117], v[178:181], v[210:213], v[114:117]
	s_setprio 0
	s_barrier
	s_add_i32 s41, s41, 2
	s_add_u32 s4, s4, 0x100
	s_addc_u32 s5, s5, 0
	s_cmpk_gt_u32 s41, 0xa9
	s_cbranch_scc0 .LBB0_1360
	s_cmpk_lt_u32 s26, 0x100
	s_cbranch_scc0 .LBB0_1363
	s_barrier

; #define PG8_STAGE(bufoff, gbase, voff) do { _Pragma("unroll") for (int _i = 0; _i < 2; ++_i) \
;         __builtin_amdgcn_global_load_lds((const unsigned*)((const char*)(gbase) + (voff)[_i]), (LAS unsigned*)(lds + (bufoff) + ldsw + _i * 8192), 16, 0, 0); } while (0)
; #define PG8_LDA(dst, b, h) do { _Pragma("unroll") for (int m = 0; m < 4; ++m) _Pragma("unroll") for (int k = 0; k < 2; ++k) dst[m][k] = *(const LAS bf16x8*)(lds + PG8_SA(b, h) + aoff + m * 2048 + k * 1024); } while (0)
; #define PG8_LDB(dst, b, h) do { _Pragma("unroll") for (int n = 0; n < 2; ++n) _Pragma("unroll") for (int k = 0; k < 2; ++k) dst[n][k] = *(const LAS bf16x8*)(lds + PG8_SB(b, h) + boff + n * 2048 + k * 1024); } while (0)
; #define PG8_MMA(ai, bj, At, Bt) do { __builtin_amdgcn_s_setprio(1); _Pragma("unroll") for (int m = 0; m < 4; ++m) _Pragma("unroll") for (int n = 0; n < 2; ++n) _Pragma("unroll") for (int k = 0; k < 2; ++k) \
;         acc[ai][bj][m][n] = __builtin_amdgcn_mfma_f32_16x16x32_bf16(Bt[n][k], At[m][k], acc[ai][bj][m][n], 0, 0, 0); __builtin_amdgcn_s_setprio(0); } while (0)
; #define PG8_WAIT_V(n) asm volatile("s_waitcnt vmcnt(" #n ")" ::: "memory")
; #define PG8_WAIT_L(n) asm volatile("s_waitcnt lgkmcnt(" #n ")" ::: "memory")
; template <class Epi, class Sched, bool ALIGN_EPI, class Hook = NoHook>
; __device__ __forceinline__ void gemm_phase(LAS unsigned char* lds, const Gemm g, const Sched& S, const Epi& E, const Hook& H = Hook()) {
;     ...
;         for (int t = tb; t < te; t += 2) {
;             const bool last = (t == nt - 2);
;             const char* a1 = cA + (size_t)(t + 1) * kstep;
;             const char* a2 = last ? nA : cA + (size_t)(t + 2) * kstep; const char* b2 = last ? nB : cB + (size_t)(t + 2) * kstep;
;             const char* a3 = a2 + kstep; const char* b3 = b2 + kstep;
;             if (last && has_next) S.a_ready(nxt);
;             PG8_LDB(B0, 0, 0); PG8_LDB(B1, 0, 1); PG8_SCHED; PG8_LDA(At, 0, 0); PG8_STAGE(PG8_SA(1, 1), a1 + hA, voffA);
;             PG8_WAIT_V(8); PG8_WAIT_L(0); PG8_BAR; PG8_MMA(0, 0, At, B0); PG8_MMA(0, 1, At, B1); PG8_BAR; PG8_SCHED;
;             PG8_LDA(At, 0, 1); PG8_STAGE(PG8_SB(0, 0), b2, voffB); PG8_STAGE(PG8_SB(0, 1), b2 + hB, voffB); PG8_STAGE(PG8_SA(0, 0), a2, voffA);
;             PG8_WAIT_V(8); PG8_WAIT_L(0); PG8_BAR; PG8_MMA(1, 0, At, B0); PG8_MMA(1, 1, At, B1); PG8_BAR; PG8_SCHED;
.LBB0_1406:
	ds_read_b128 v[146:149], v140
	ds_read_b128 v[150:153], v140 offset:1024
	ds_read_b128 v[154:157], v140 offset:2048
	ds_read_b128 v[158:161], v140 offset:3072
	ds_read_b128 v[170:173], v141
	ds_read_b128 v[174:177], v141 offset:1024
	ds_read_b128 v[178:181], v141 offset:2048
	ds_read_b128 v[182:185], v141 offset:3072
	s_add_u32 s10, s4, 0xbb050080
	s_addc_u32 s11, s5, -1
	s_cmpk_lg_i32 s18, 0xa8
	s_cselect_b32 s10, s10, 0
	s_cselect_b32 s11, s11, 0
	s_add_u32 s16, s0, s10
	s_addc_u32 s17, s1, s11
	s_add_u32 s10, s12, s10
	s_addc_u32 s11, s13, s11
	s_mov_b32 m0, s19
	v_lshl_add_u64 v[218:219], v[136:137], 0, s[4:5]
	ds_read_b128 v[186:189], v142
	ds_read_b128 v[190:193], v142 offset:1024
	ds_read_b128 v[194:197], v142 offset:2048
	ds_read_b128 v[198:201], v142 offset:3072
	ds_read_b128 v[202:205], v142 offset:4096
	ds_read_b128 v[206:209], v142 offset:5120
	ds_read_b128 v[210:213], v142 offset:6144
	ds_read_b128 v[214:217], v142 offset:7168
	global_load_lds_dwordx4 v[218:219], off
	v_lshl_add_u64 v[218:219], v[138:139], 0, s[4:5]
	s_mov_b32 m0, s31
	s_nop 0
	global_load_lds_dwordx4 v[218:219], off
	s_waitcnt vmcnt(8)
	s_waitcnt lgkmcnt(0)
	s_barrier
	s_setprio 1
	s_waitcnt lgkmcnt(0)
	v_mfma_f32_16x16x32_bf16 v[82:85], v[146:149], v[186:189], v[82:85]
	v_mfma_f32_16x16x32_bf16 v[54:57], v[154:157], v[186:189], v[54:57]
	v_mfma_f32_16x16x32_bf16 v[58:61], v[146:149], v[194:197], v[58:61]
	v_mfma_f32_16x16x32_bf16 v[42:45], v[154:157], v[194:197], v[42:45]
	v_mfma_f32_16x16x32_bf16 v[70:73], v[146:149], v[202:205], v[70:73]
	v_mfma_f32_16x16x32_bf16 v[50:53], v[154:157], v[202:205], v[50:53]
	v_mfma_f32_16x16x32_bf16 v[86:89], v[146:149], v[210:213], v[86:89]
	v_mfma_f32_16x16x32_bf16 v[74:77], v[154:157], v[210:213], v[74:77]
	v_mfma_f32_16x16x32_bf16 v[82:85], v[150:153], v[190:193], v[82:85]
	v_mfma_f32_16x16x32_bf16 v[54:57], v[158:161], v[190:193], v[54:57]
	v_mfma_f32_16x16x32_bf16 v[58:61], v[150:153], v[198:201], v[58:61]
	v_mfma_f32_16x16x32_bf16 v[42:45], v[158:161], v[198:201], v[42:45]
	v_mfma_f32_16x16x32_bf16 v[70:73], v[150:153], v[206:209], v[70:73]
	v_mfma_f32_16x16x32_bf16 v[50:53], v[158:161], v[206:209], v[50:53]
	v_mfma_f32_16x16x32_bf16 v[86:89], v[150:153], v[214:217], v[86:89]
	v_mfma_f32_16x16x32_bf16 v[74:77], v[158:161], v[214:217], v[74:77]
	s_setprio 0
	s_setprio 1
	v_mfma_f32_16x16x32_bf16 v[14:17], v[170:173], v[186:189], v[14:17]
	v_mfma_f32_16x16x32_bf16 v[2:5], v[178:181], v[186:189], v[2:5]
	v_mfma_f32_16x16x32_bf16 v[18:21], v[170:173], v[194:197], v[18:21]
	v_mfma_f32_16x16x32_bf16 v[6:9], v[178:181], v[194:197], v[6:9]
	v_mfma_f32_16x16x32_bf16 v[22:25], v[170:173], v[202:205], v[22:25]
	v_mfma_f32_16x16x32_bf16 v[10:13], v[178:181], v[202:205], v[10:13]
	v_mfma_f32_16x16x32_bf16 v[30:33], v[170:173], v[210:213], v[30:33]
	v_mfma_f32_16x16x32_bf16 v[26:29], v[178:181], v[210:213], v[26:29]
	v_mfma_f32_16x16x32_bf16 v[14:17], v[174:177], v[190:193], v[14:17]
	v_mfma_f32_16x16x32_bf16 v[2:5], v[182:185], v[190:193], v[2:5]
	v_mfma_f32_16x16x32_bf16 v[18:21], v[174:177], v[198:201], v[18:21]
	v_mfma_f32_16x16x32_bf16 v[6:9], v[182:185], v[198:201], v[6:9]
	v_mfma_f32_16x16x32_bf16 v[22:25], v[174:177], v[206:209], v[22:25]
	v_mfma_f32_16x16x32_bf16 v[10:13], v[182:185], v[206:209], v[10:13]
	v_mfma_f32_16x16x32_bf16 v[30:33], v[174:177], v[214:217], v[30:33]
	v_mfma_f32_16x16x32_bf16 v[26:29], v[182:185], v[214:217], v[26:29]
	s_setprio 0
	s_barrier
	s_mov_b32 m0, s33
	s_add_u32 s46, s10, 0x2b0000
	ds_read_b128 v[186:189], v142 offset:16384
	ds_read_b128 v[190:193], v142 offset:17408
	ds_read_b128 v[194:197], v142 offset:18432
	ds_read_b128 v[198:201], v142 offset:19456
	ds_read_b128 v[202:205], v142 offset:20480
	ds_read_b128 v[206:209], v142 offset:21504
	ds_read_b128 v[210:213], v142 offset:22528
	ds_read_b128 v[214:217], v142 offset:23552
	global_load_lds_dwordx4 v162, s[10:11]
	s_mov_b32 m0, s34
	s_addc_u32 s47, s11, 0
	global_load_lds_dwordx4 v134, s[10:11]
	s_mov_b32 m0, s35
	s_nop 0
	global_load_lds_dwordx4 v162, s[46:47]
	s_mov_b32 m0, s43
	s_nop 0
	global_load_lds_dwordx4 v134, s[46:47]
	s_add_u32 s54, s16, s2
	s_addc_u32 s55, s17, s3
	s_mov_b32 m0, s27
	s_nop 0
	global_load_lds_dwordx4 v130, s[16:17]
	s_mov_b32 m0, s28
	s_nop 0
	global_load_lds_dwordx4 v132, s[16:17]
	s_waitcnt vmcnt(8)
	s_waitcnt lgkmcnt(0)
	s_barrier
	s_setprio 1
	s_waitcnt lgkmcnt(0)
	v_mfma_f32_16x16x32_bf16 v[94:97], v[146:149], v[186:189], v[94:97]
	v_mfma_f32_16x16x32_bf16 v[90:93], v[154:157], v[186:189], v[90:93]
	v_mfma_f32_16x16x32_bf16 v[118:121], v[146:149], v[194:197], v[118:121]
	v_mfma_f32_16x16x32_bf16 v[98:101], v[154:157], v[194:197], v[98:101]
	v_mfma_f32_16x16x32_bf16 v[126:129], v[146:149], v[202:205], v[126:129]
	v_mfma_f32_16x16x32_bf16 v[110:113], v[154:157], v[202:205], v[110:113]
	v_mfma_f32_16x16x32_bf16 v[122:125], v[146:149], v[210:213], v[122:125]
	v_mfma_f32_16x16x32_bf16 v[114:117], v[154:157], v[210:213], v[114:117]
	v_mfma_f32_16x16x32_bf16 v[94:97], v[150:153], v[190:193], v[94:97]
	v_mfma_f32_16x16x32_bf16 v[90:93], v[158:161], v[190:193], v[90:93]
	v_mfma_f32_16x16x32_bf16 v[118:121], v[150:153], v[198:201], v[118:121]
	v_mfma_f32_16x16x32_bf16 v[98:101], v[158:161], v[198:201], v[98:101]
	v_mfma_f32_16x16x32_bf16 v[126:129], v[150:153], v[206:209], v[126:129]
	v_mfma_f32_16x16x32_bf16 v[110:113], v[158:161], v[206:209], v[110:113]
	v_mfma_f32_16x16x32_bf16 v[122:125], v[150:153], v[214:217], v[122:125]
	v_mfma_f32_16x16x32_bf16 v[114:117], v[158:161], v[214:217], v[114:117]
	s_setprio 0
	s_setprio 1
	v_mfma_f32_16x16x32_bf16 v[38:41], v[170:173], v[186:189], v[38:41]
	v_mfma_f32_16x16x32_bf16 v[34:37], v[178:181], v[186:189], v[34:37]
	v_mfma_f32_16x16x32_bf16 v[66:69], v[170:173], v[194:197], v[66:69]
	v_mfma_f32_16x16x32_bf16 v[46:49], v[178:181], v[194:197], v[46:49]
	v_mfma_f32_16x16x32_bf16 v[78:81], v[170:173], v[202:205], v[78:81]
	v_mfma_f32_16x16x32_bf16 v[62:65], v[178:181], v[202:205], v[62:65]
	v_mfma_f32_16x16x32_bf16 v[106:109], v[170:173], v[210:213], v[106:109]
	v_mfma_f32_16x16x32_bf16 v[102:105], v[178:181], v[210:213], v[102:105]
	v_mfma_f32_16x16x32_bf16 v[38:41], v[174:177], v[190:193], v[38:41]
	v_mfma_f32_16x16x32_bf16 v[34:37], v[182:185], v[190:193], v[34:37]
	v_mfma_f32_16x16x32_bf16 v[66:69], v[174:177], v[198:201], v[66:69]
	v_mfma_f32_16x16x32_bf16 v[46:49], v[182:185], v[198:201], v[46:49]
	v_mfma_f32_16x16x32_bf16 v[78:81], v[174:177], v[206:209], v[78:81]
	v_mfma_f32_16x16x32_bf16 v[62:65], v[182:185], v[206:209], v[62:65]
	v_mfma_f32_16x16x32_bf16 v[106:109], v[174:177], v[214:217], v[106:109]
	v_mfma_f32_16x16x32_bf16 v[102:105], v[182:185], v[214:217], v[102:105]
	s_setprio 0
	s_barrier
; #define PG8_STAGE(bufoff, gbase, voff) do { _Pragma("unroll") for (int _i = 0; _i < 2; ++_i) \
;         __builtin_amdgcn_global_load_lds((const unsigned*)((const char*)(gbase) + (voff)[_i]), (LAS unsigned*)(lds + (bufoff) + ldsw + _i * 8192), 16, 0, 0); } while (0)
; #define PG8_LDA(dst, b, h) do { _Pragma("unroll") for (int m = 0; m < 4; ++m) _Pragma("unroll") for (int k = 0; k < 2; ++k) dst[m][k] = *(const LAS bf16x8*)(lds + PG8_SA(b, h) + aoff + m * 2048 + k * 1024); } while (0)
; #define PG8_LDB(dst, b, h) do { _Pragma("unroll") for (int n = 0; n < 2; ++n) _Pragma("unroll") for (int k = 0; k < 2; ++k) dst[n][k] = *(const LAS bf16x8*)(lds + PG8_SB(b, h) + boff + n * 2048 + k * 1024); } while (0)
; #define PG8_MMA(ai, bj, At, Bt) do { __builtin_amdgcn_s_setprio(1); _Pragma("unroll") for (int m = 0; m < 4; ++m) _Pragma("unroll") for (int n = 0; n < 2; ++n) _Pragma("unroll") for (int k = 0; k < 2; ++k) \
;         acc[ai][bj][m][n] = __builtin_amdgcn_mfma_f32_16x16x32_bf16(Bt[n][k], At[m][k], acc[ai][bj][m][n], 0, 0, 0); __builtin_amdgcn_s_setprio(0); } while (0)
; #define PG8_WAIT_V(n) asm volatile("s_waitcnt vmcnt(" #n ")" ::: "memory")
; #define PG8_WAIT_L(n) asm volatile("s_waitcnt lgkmcnt(" #n ")" ::: "memory")
; #define PG8_BAR __builtin_amdgcn_s_barrier()
; #define PG8_SCHED __builtin_amdgcn_sched_barrier(0)
; template <class Epi, class Sched, bool ALIGN_EPI, class Hook = NoHook>
; __device__ __forceinline__ void gemm_phase(LAS unsigned char* lds, const Gemm g, const Sched& S, const Epi& E, const Hook& H = Hook()) {
;     ...
;             PG8_LDB(B0, 1, 0); PG8_LDB(B1, 1, 1); PG8_SCHED; PG8_LDA(At, 1, 0); PG8_STAGE(PG8_SA(0, 1), a2 + hA, voffA);
;             PG8_WAIT_V(8); PG8_WAIT_L(0); PG8_BAR; PG8_MMA(0, 0, At, B0); PG8_MMA(0, 1, At, B1); PG8_BAR; PG8_SCHED;
;             PG8_LDA(At, 1, 1); PG8_STAGE(PG8_SB(1, 0), b3, voffB); PG8_STAGE(PG8_SB(1, 1), b3 + hB, voffB); PG8_STAGE(PG8_SA(1, 0), a3, voffA);
;             PG8_WAIT_V(8); PG8_WAIT_L(0); PG8_BAR; PG8_MMA(1, 0, At, B0); PG8_MMA(1, 1, At, B1); PG8_BAR; PG8_SCHED;
;         }
	ds_read_b128 v[146:149], v143
	ds_read_b128 v[150:153], v143 offset:1024
	ds_read_b128 v[154:157], v143 offset:2048
	ds_read_b128 v[158:161], v143 offset:3072
	ds_read_b128 v[170:173], v144
	ds_read_b128 v[174:177], v144 offset:1024
	ds_read_b128 v[178:181], v144 offset:2048
	ds_read_b128 v[182:185], v144 offset:3072
	s_add_u32 s16, s16, 0x2b0000
	s_addc_u32 s17, s17, 0
	s_mov_b32 m0, s29
	ds_read_b128 v[186:189], v142 offset:32768
	ds_read_b128 v[190:193], v142 offset:33792
	ds_read_b128 v[194:197], v142 offset:34816
	ds_read_b128 v[198:201], v142 offset:35840
	ds_read_b128 v[202:205], v142 offset:36864
	ds_read_b128 v[206:209], v142 offset:37888
	ds_read_b128 v[210:213], v142 offset:38912
	ds_read_b128 v[214:217], v142 offset:39936
	global_load_lds_dwordx4 v130, s[16:17]
	s_mov_b32 m0, s39
	s_nop 0
	global_load_lds_dwordx4 v132, s[16:17]
	s_waitcnt vmcnt(8)
	s_waitcnt lgkmcnt(0)
	s_barrier
	s_setprio 1
	s_waitcnt lgkmcnt(0)
	v_mfma_f32_16x16x32_bf16 v[82:85], v[146:149], v[186:189], v[82:85]
	v_mfma_f32_16x16x32_bf16 v[54:57], v[154:157], v[186:189], v[54:57]
	v_mfma_f32_16x16x32_bf16 v[58:61], v[146:149], v[194:197], v[58:61]
	v_mfma_f32_16x16x32_bf16 v[42:45], v[154:157], v[194:197], v[42:45]
	v_mfma_f32_16x16x32_bf16 v[70:73], v[146:149], v[202:205], v[70:73]
	v_mfma_f32_16x16x32_bf16 v[50:53], v[154:157], v[202:205], v[50:53]
	v_mfma_f32_16x16x32_bf16 v[86:89], v[146:149], v[210:213], v[86:89]
	v_mfma_f32_16x16x32_bf16 v[74:77], v[154:157], v[210:213], v[74:77]
	v_mfma_f32_16x16x32_bf16 v[82:85], v[150:153], v[190:193], v[82:85]
	v_mfma_f32_16x16x32_bf16 v[54:57], v[158:161], v[190:193], v[54:57]
	v_mfma_f32_16x16x32_bf16 v[58:61], v[150:153], v[198:201], v[58:61]
	v_mfma_f32_16x16x32_bf16 v[42:45], v[158:161], v[198:201], v[42:45]
	v_mfma_f32_16x16x32_bf16 v[70:73], v[150:153], v[206:209], v[70:73]
	v_mfma_f32_16x16x32_bf16 v[50:53], v[158:161], v[206:209], v[50:53]
	v_mfma_f32_16x16x32_bf16 v[86:89], v[150:153], v[214:217], v[86:89]
	v_mfma_f32_16x16x32_bf16 v[74:77], v[158:161], v[214:217], v[74:77]
	s_setprio 0
	s_setprio 1
	v_mfma_f32_16x16x32_bf16 v[14:17], v[170:173], v[186:189], v[14:17]
	v_mfma_f32_16x16x32_bf16 v[2:5], v[178:181], v[186:189], v[2:5]
	v_mfma_f32_16x16x32_bf16 v[18:21], v[170:173], v[194:197], v[18:21]
	v_mfma_f32_16x16x32_bf16 v[6:9], v[178:181], v[194:197], v[6:9]
	v_mfma_f32_16x16x32_bf16 v[22:25], v[170:173], v[202:205], v[22:25]
	v_mfma_f32_16x16x32_bf16 v[10:13], v[178:181], v[202:205], v[10:13]
	v_mfma_f32_16x16x32_bf16 v[30:33], v[170:173], v[210:213], v[30:33]
	v_mfma_f32_16x16x32_bf16 v[26:29], v[178:181], v[210:213], v[26:29]
	v_mfma_f32_16x16x32_bf16 v[14:17], v[174:177], v[190:193], v[14:17]
	v_mfma_f32_16x16x32_bf16 v[2:5], v[182:185], v[190:193], v[2:5]
	v_mfma_f32_16x16x32_bf16 v[18:21], v[174:177], v[198:201], v[18:21]
	v_mfma_f32_16x16x32_bf16 v[6:9], v[182:185], v[198:201], v[6:9]
	v_mfma_f32_16x16x32_bf16 v[22:25], v[174:177], v[206:209], v[22:25]
	v_mfma_f32_16x16x32_bf16 v[10:13], v[182:185], v[206:209], v[10:13]
	v_mfma_f32_16x16x32_bf16 v[30:33], v[174:177], v[214:217], v[30:33]
	v_mfma_f32_16x16x32_bf16 v[26:29], v[182:185], v[214:217], v[26:29]
	s_setprio 0
	s_barrier
	s_mov_b32 m0, s36
	s_add_u32 s52, s10, s2
	s_addc_u32 s53, s11, s3
	s_add_u32 s10, s10, 0x2b0080
	ds_read_b128 v[186:189], v142 offset:49152
	ds_read_b128 v[190:193], v142 offset:50176
	ds_read_b128 v[194:197], v142 offset:51200
	ds_read_b128 v[198:201], v142 offset:52224
	ds_read_b128 v[202:205], v142 offset:53248
	ds_read_b128 v[206:209], v142 offset:54272
	ds_read_b128 v[210:213], v142 offset:55296
	ds_read_b128 v[214:217], v142 offset:56320
	global_load_lds_dwordx4 v162, s[52:53]
	s_mov_b32 m0, s44
	s_addc_u32 s11, s11, 0
	global_load_lds_dwordx4 v134, s[52:53]
	s_mov_b32 m0, s37
	s_nop 0
	global_load_lds_dwordx4 v162, s[10:11]
	s_mov_b32 m0, s45
	s_nop 0
	global_load_lds_dwordx4 v134, s[10:11]
	s_mov_b32 m0, s41
	s_nop 0
	global_load_lds_dwordx4 v130, s[54:55]
	s_mov_b32 m0, s42
	s_nop 0
	global_load_lds_dwordx4 v132, s[54:55]
	s_waitcnt vmcnt(8)
	s_waitcnt lgkmcnt(0)
	s_barrier
	s_setprio 1
	s_waitcnt lgkmcnt(0)
	v_mfma_f32_16x16x32_bf16 v[94:97], v[146:149], v[186:189], v[94:97]
	v_mfma_f32_16x16x32_bf16 v[90:93], v[154:157], v[186:189], v[90:93]
	v_mfma_f32_16x16x32_bf16 v[118:121], v[146:149], v[194:197], v[118:121]
	v_mfma_f32_16x16x32_bf16 v[98:101], v[154:157], v[194:197], v[98:101]
	v_mfma_f32_16x16x32_bf16 v[126:129], v[146:149], v[202:205], v[126:129]
	v_mfma_f32_16x16x32_bf16 v[110:113], v[154:157], v[202:205], v[110:113]
	v_mfma_f32_16x16x32_bf16 v[122:125], v[146:149], v[210:213], v[122:125]
	v_mfma_f32_16x16x32_bf16 v[114:117], v[154:157], v[210:213], v[114:117]
	v_mfma_f32_16x16x32_bf16 v[94:97], v[150:153], v[190:193], v[94:97]
	v_mfma_f32_16x16x32_bf16 v[90:93], v[158:161], v[190:193], v[90:93]
	v_mfma_f32_16x16x32_bf16 v[118:121], v[150:153], v[198:201], v[118:121]
	v_mfma_f32_16x16x32_bf16 v[98:101], v[158:161], v[198:201], v[98:101]
	v_mfma_f32_16x16x32_bf16 v[126:129], v[150:153], v[206:209], v[126:129]
	v_mfma_f32_16x16x32_bf16 v[110:113], v[158:161], v[206:209], v[110:113]
	v_mfma_f32_16x16x32_bf16 v[122:125], v[150:153], v[214:217], v[122:125]
	v_mfma_f32_16x16x32_bf16 v[114:117], v[158:161], v[214:217], v[114:117]
	s_setprio 0
	s_setprio 1
	v_mfma_f32_16x16x32_bf16 v[38:41], v[170:173], v[186:189], v[38:41]
	v_mfma_f32_16x16x32_bf16 v[34:37], v[178:181], v[186:189], v[34:37]
	v_mfma_f32_16x16x32_bf16 v[66:69], v[170:173], v[194:197], v[66:69]
	v_mfma_f32_16x16x32_bf16 v[46:49], v[178:181], v[194:197], v[46:49]
	v_mfma_f32_16x16x32_bf16 v[78:81], v[170:173], v[202:205], v[78:81]
	v_mfma_f32_16x16x32_bf16 v[62:65], v[178:181], v[202:205], v[62:65]
	v_mfma_f32_16x16x32_bf16 v[106:109], v[170:173], v[210:213], v[106:109]
	v_mfma_f32_16x16x32_bf16 v[102:105], v[178:181], v[210:213], v[102:105]
	v_mfma_f32_16x16x32_bf16 v[38:41], v[174:177], v[190:193], v[38:41]
	v_mfma_f32_16x16x32_bf16 v[34:37], v[182:185], v[190:193], v[34:37]
	v_mfma_f32_16x16x32_bf16 v[66:69], v[174:177], v[198:201], v[66:69]
	v_mfma_f32_16x16x32_bf16 v[46:49], v[182:185], v[198:201], v[46:49]
	v_mfma_f32_16x16x32_bf16 v[78:81], v[174:177], v[206:209], v[78:81]
	v_mfma_f32_16x16x32_bf16 v[62:65], v[182:185], v[206:209], v[62:65]
	v_mfma_f32_16x16x32_bf16 v[106:109], v[174:177], v[214:217], v[106:109]
	v_mfma_f32_16x16x32_bf16 v[102:105], v[182:185], v[214:217], v[102:105]
	s_setprio 0
	s_barrier
	s_add_i32 s18, s18, 2
	s_add_u32 s4, s4, 0x100
	s_addc_u32 s5, s5, 0
	s_cmpk_gt_u32 s18, 0xa9
	s_cbranch_scc0 .LBB0_1406
	s_cmpk_lt_u32 s22, 0x100
	s_cbranch_scc0 .LBB0_1409
	s_barrier
